# GEMM tiles: first K-tile LDS reads hoisted above tile-order scalar code; first two counted waits of a tile exclude the previous epilogue's stores (vmcnt(E+8)); P10 row bias prefetched one tile ahead
# baseline (speedup 1.0000x reference)
; #define PG8_STAGE(bufoff, gbase, voff) do { _Pragma("unroll") for (int _i = 0; _i < 2; ++_i) \
;         __builtin_amdgcn_global_load_lds((const unsigned*)((const char*)(gbase) + (voff)[_i]), (PG8_LAS unsigned*)(lds + (bufoff) + ldsw + _i * 8192), 16, 0, 0); } while (0)
; #define PG8_WAIT_V(n) asm volatile("s_waitcnt vmcnt(" #n ")" ::: "memory")
; #define PG8_BAR __builtin_amdgcn_s_barrier()
; template <class Epi, class Sched, bool ALIGN_EPI = false, bool SP2 = false>
; __device__ __forceinline__ void gemm_phase(PG8_LAS unsigned char* lds, const Gemm g, const Sched& S, const Epi& E) {
;     ...
;     for (int i = 0; i < 2; ++i) { int R, C; stage_rc(tid * 16 + i * 8192, R, C); const int Rb = Epi::PERM ? ((R & ~31) + perm32(R & 31)) : R;
;         voffA[i] = (unsigned)(R * K + C) * 2u; voffB[i] = (unsigned)(Rb * K + C) * 2u; }
;     const size_t kstep = (size_t)(BK * 2);
;     const size_t hstep = (size_t)HALF * K * 2;
;     const size_t tstep = 2 * hstep;
;     const unsigned ldsw = (unsigned)wid * 1024u;
;     const int aoff = lds_byte(wr * 64 + fr, fq * 8), boff = lds_byte(wc * 32 + fr, fq * 8);
;     ...
;     if constexpr (SP2) {
;         PG8_STAGE(PG8_SB(0, 0), cB, voffB); PG8_STAGE(PG8_SB(0, 1), cB + hstep, voffB); PG8_STAGE(PG8_SA(0, 0), cA, voffA); PG8_STAGE(PG8_SA(0, 1), cA + hstep, voffA);
;         if (wr == 1) PG8_BAR;
;         PG8_WAIT_V(2); PG8_BAR;
;         PG8_STAGE(PG8_SB(1, 0), cB + kstep, voffB); PG8_STAGE(PG8_SA(1, 0), cA + kstep, voffA); PG8_STAGE(PG8_SB(1, 1), cB + hstep + kstep, voffB);
;         PG8_WAIT_V(6); PG8_BAR;
.LBB0_375:
	s_add_u32 s8, s28, 0xfa00000
	s_addc_u32 s9, s29, 0
	s_lshl_b32 s10, s10, 5
	s_and_b32 s22, s10, 0x60
	s_mov_b64 s[10:11], 0x80
	s_add_i32 m0, s41, 0x18000
	v_lshl_add_u64 v[6:7], v[6:7], 0, s[10:11]
	s_ashr_i32 s73, s3, 31
	s_lshl_b32 s13, s12, 13
	s_lshl_b32 s23, s22, 7
	s_waitcnt vmcnt(2)
	s_barrier
	global_load_lds_dwordx4 v[6:7], off
	v_lshl_add_u64 v[4:5], v[4:5], 0, s[10:11]
	s_add_i32 m0, s41, 0x1a000
	s_add_i32 s74, s41, 0x8000
	s_add_i32 s75, s41, 0xa000
	global_load_lds_dwordx4 v[4:5], off
	v_lshl_add_u64 v[0:1], v[0:1], 0, s[10:11]
	s_mov_b32 m0, s74
	s_add_u32 s20, s44, 0x40080
	global_load_lds_dwordx4 v[0:1], off
	v_lshl_add_u64 v[0:1], v[2:3], 0, s[10:11]
	s_mov_b32 m0, s75
	s_addc_u32 s21, s45, 0
	global_load_lds_dwordx4 v[0:1], off
	s_add_i32 m0, s41, 0x1c000
	v_lshl_add_u64 v[0:1], s[20:21], 0, v[130:131]
	global_load_lds_dwordx4 v[0:1], off
	v_lshl_add_u64 v[0:1], s[20:21], 0, v[134:135]
	s_add_i32 m0, s41, 0x1e000
	s_sext_i32_i8 s79, s0
	global_load_lds_dwordx4 v[0:1], off
	v_and_b32_e32 v0, 15, v152
	v_lshlrev_b32_e32 v1, 1, v11
	v_lshlrev_b32_e32 v2, 6, v152
	s_movk_i32 s0, 0x3c0
	v_lshlrev_b32_e32 v3, 2, v152
	v_and_or_b32 v2, v2, s0, v1
	v_and_b32_e32 v3, 32, v3
	v_lshl_or_b32 v148, s12, 6, v0
	v_lshl_or_b32 v0, v0, 6, v1
	v_lshlrev_b32_e32 v1, 8, v152
	v_bitop3_b32 v149, s23, v2, v3 bitop3:0xf6
	v_and_b32_e32 v1, 0x38000, v1
	v_lshlrev_b32_e32 v2, 11, v10
	v_or3_b32 v1, v8, v1, v2
	v_add_u32_e32 v136, v1, v9
	v_lshlrev_b32_e32 v1, 4, v12
	s_waitcnt vmcnt(6)
	s_cmpk_lt_u32 s1, 0x100
	v_and_b32_e32 v1, 0x78000, v1
	v_bitop3_b32 v0, v0, s13, v3 bitop3:0xde
	s_cselect_b64 s[12:13], -1, 0
	v_or3_b32 v1, v8, v1, v2
	s_add_i32 s76, 0, 0x10000
	s_add_i32 s77, 0, 0x14000
	v_or_b32_e32 v150, s22, v11
	v_mov_b32_e32 v137, v131
	v_add_u32_e32 v138, v1, v9
	v_mov_b32_e32 v139, v131
	v_mov_b64_e32 v[140:141], 0x630
	v_mov_b64_e32 v[142:143], 0x62f
	v_add_u32_e32 v151, s76, v149
	v_add_u32_e32 v153, s77, v149
	v_add_u32_e32 v154, 0, v0
	s_movk_i32 s78, 0xc00
	s_barrier
	s_mov_b32 s60, 0
	s_branch .LBB0_378

; #define PG8_STAGE(bufoff, gbase, voff) do { _Pragma("unroll") for (int _i = 0; _i < 2; ++_i) \
;         __builtin_amdgcn_global_load_lds((const unsigned*)((const char*)(gbase) + (voff)[_i]), (PG8_LAS unsigned*)(lds + (bufoff) + ldsw + _i * 8192), 16, 0, 0); } while (0)
; #define PG8_LDA(dst, b, h) do { _Pragma("unroll") for (int m = 0; m < 4; ++m) _Pragma("unroll") for (int k = 0; k < 2; ++k) dst[m][k] = *(const PG8_LAS bf16x8*)(lds + PG8_SA(b, h) + aoff + m * 2048 + k * 1024); } while (0)
; #define PG8_LDB(dst, b, h) do { _Pragma("unroll") for (int n = 0; n < 2; ++n) _Pragma("unroll") for (int k = 0; k < 2; ++k) dst[n][k] = *(const PG8_LAS bf16x8*)(lds + PG8_SB(b, h) + boff + n * 2048 + k * 1024); } while (0)
; #define PG8_SCHED __builtin_amdgcn_sched_barrier(0)
;     __host__ __device__ bool next(int i, Unit& u) const {
;         const long L = (long)i * G + c; if (L >= nwg) return false;
;         int wgid = (int)L; { const int q = nwg / NXCD, r = nwg % NXCD, xcd = wgid % NXCD, off = wgid / NXCD; wgid = (xcd < r ? xcd * (q + 1) : r * (q + 1) + (xcd - r) * q) + off; }
;         const int nig = WGM * nN, gid = wgid / nig, fm = gid * WGM, gsz = (nM - fm) < WGM ? (nM - fm) : WGM;
;         u.pm = fm + ((wgid % nig) % gsz); u.pn = (wgid % nig) / gsz; return true;
;     }
; template <class Epi, class Sched, bool ALIGN_EPI = false, bool SP2 = false>
; __device__ __forceinline__ void gemm_phase(PG8_LAS unsigned char* lds, const Gemm g, const Sched& S, const Epi& E) {
;     ...
;         const bool has_next = S.next(ui + 1, nxt);
;         const char* nA = has_next ? (const char*)g.A + (size_t)nxt.pm * tstep : cA; const char* nB = has_next ? (const char*)g.Bt + (size_t)nxt.pn * tstep : cB;
;         for (int t = 0; t < nt; t += 2) {
;             const bool last = (t == nt - 2);
;             const char* a1 = cA + (size_t)(t + 1) * kstep;
;             const char* a2 = last ? nA : cA + (size_t)(t + 2) * kstep; const char* b2 = last ? nB : cB + (size_t)(t + 2) * kstep;
;             const char* a3 = a2 + kstep; const char* b3 = b2 + kstep;
;             if (last && has_next) S.a_ready(nxt);
;             if constexpr (SP2) {
;             PG8_LDB(B0, 0, 0); PG8_LDB(B1, 0, 1); PG8_SCHED; PG8_LDA(At, 0, 0); PG8_STAGE(PG8_SA(1, 1), a1 + hstep, voffA);
.LBB0_378:
	ds_read_b128 v[144:147], v151
	ds_read_b128 v[156:159], v151 offset:1024
	ds_read_b128 v[160:163], v151 offset:2048
	ds_read_b128 v[164:167], v151 offset:3072
	ds_read_b128 v[168:171], v153
	ds_read_b128 v[172:175], v153 offset:1024
	ds_read_b128 v[176:179], v153 offset:2048
	ds_read_b128 v[180:183], v153 offset:3072
	ds_read_b128 v[184:187], v154
	ds_read_b128 v[188:191], v154 offset:1024
	ds_read_b128 v[192:195], v154 offset:2048
	ds_read_b128 v[196:199], v154 offset:3072
	ds_read_b128 v[200:203], v154 offset:4096
	ds_read_b128 v[204:207], v154 offset:5120
	ds_read_b128 v[208:211], v154 offset:6144
	ds_read_b128 v[212:215], v154 offset:7168
	s_add_i32 s72, s72, 1
	s_mul_i32 s0, s72, s73
	s_mul_hi_u32 s1, s72, s3
	s_add_i32 s1, s1, s0
	s_mul_i32 s0, s72, s3
	s_add_u32 s24, s0, s2
	s_addc_u32 s25, s1, s55
	v_cmp_gt_i64_e32 vcc, s[24:25], v[142:143]
	v_cmp_lt_i64_e64 s[0:1], s[24:25], v[140:141]
	s_cbranch_vccnz .LBB0_380
	s_ashr_i32 s20, s24, 31
	s_lshr_b32 s20, s20, 29
	s_add_i32 s20, s24, s20
	s_ashr_i32 s21, s20, 3
	s_and_b32 s20, s20, -8
	s_sub_i32 s20, s24, s20
	s_cmp_lt_i32 s20, 0
	s_cselect_b32 s22, s62, 0xc6
	s_mul_i32 s20, s20, s22
	s_add_i32 s20, s20, s21
	s_mul_hi_i32 s21, s20, 0x2aaaaaab
	s_lshr_b32 s22, s21, 31
	s_ashr_i32 s21, s21, 3
	s_add_i32 s21, s21, s22
	s_lshl_b32 s22, s21, 3
	s_sub_i32 s23, 0x108, s22
	s_min_i32 s23, s23, 8
	s_abs_i32 s24, s23
	v_cvt_f32_u32_e32 v0, s24
	s_sub_i32 s33, 0, s24
	s_mul_i32 s21, s21, 48
	s_sub_i32 s21, s20, s21
	v_rcp_iflag_f32_e32 v0, v0
	s_abs_i32 s20, s21
	s_xor_b32 s25, s21, s23
	s_ashr_i32 s25, s25, 31
	v_mul_f32_e32 v0, 0x4f7ffffe, v0
	v_cvt_u32_f32_e32 v0, v0
	s_nop 0
	v_readfirstlane_b32 s34, v0
	s_mul_i32 s33, s33, s34
	s_mul_hi_u32 s33, s34, s33
	s_add_i32 s34, s34, s33
	s_mul_hi_u32 s33, s20, s34
	s_mul_i32 s34, s33, s24
	s_sub_i32 s20, s20, s34
	s_add_i32 s35, s33, 1
	s_sub_i32 s34, s20, s24
	s_cmp_ge_u32 s20, s24
	s_cselect_b32 s33, s35, s33
	s_cselect_b32 s20, s34, s20
	s_add_i32 s34, s33, 1
	s_cmp_ge_u32 s20, s24
	s_cselect_b32 s20, s34, s33
	s_xor_b32 s20, s20, s25
	s_sub_i32 s20, s20, s25
	s_mul_i32 s23, s20, s23
	s_sub_i32 s21, s21, s23
	s_add_i32 s22, s22, s21
.LBB0_380:
	s_ashr_i32 s23, s22, 31
	s_lshl_b64 s[24:25], s[22:23], 19
	s_add_u32 s24, s16, s24
	s_addc_u32 s25, s17, s25
	s_and_b64 s[38:39], s[0:1], exec
	s_cselect_b32 s23, s25, s43
	s_cselect_b32 s80, s24, s42
	s_ashr_i32 s21, s20, 31
	s_lshl_b64 s[38:39], s[20:21], 19
	s_add_u32 s38, s52, s38
	s_addc_u32 s39, s53, s39
	s_and_b64 s[46:47], s[0:1], exec
	s_cselect_b32 s21, s39, s45
	s_cselect_b32 s81, s38, s44
	s_add_u32 s42, s42, 0x40080
	s_addc_u32 s43, s43, 0
	s_add_u32 s82, s44, 0x100
	s_addc_u32 s83, s45, 0
	s_mov_b32 s86, -2
	s_add_u32 s33, s42, 0xfffc0080
	s_addc_u32 s34, s43, -1
	s_cmp_eq_u32 s86, 12
	s_cselect_b32 s47, s23, s34
	s_cselect_b32 s46, s80, s33
	s_cselect_b32 s45, s21, s83
	s_cselect_b32 s44, s81, s82
	s_add_i32 m0, s41, 0xc000
	global_load_lds_dwordx4 v136, s[42:43]
	s_add_i32 m0, s41, 0xe000
	s_nop 0
	global_load_lds_dwordx4 v138, s[42:43]
	s_cmp_eq_u32 s60, 0
	s_cbranch_scc1 .LfwP2_0_s
	s_waitcnt vmcnt(24)
	s_branch .LfwP2_0_e

; #define PG8_STAGE(bufoff, gbase, voff) do { _Pragma("unroll") for (int _i = 0; _i < 2; ++_i) \
;         __builtin_amdgcn_global_load_lds((const unsigned*)((const char*)(gbase) + (voff)[_i]), (PG8_LAS unsigned*)(lds + (bufoff) + ldsw + _i * 8192), 16, 0, 0); } while (0)
; #define PG8_LDA(dst, b, h) do { _Pragma("unroll") for (int m = 0; m < 4; ++m) _Pragma("unroll") for (int k = 0; k < 2; ++k) dst[m][k] = *(const PG8_LAS bf16x8*)(lds + PG8_SA(b, h) + aoff + m * 2048 + k * 1024); } while (0)
; #define PG8_MMA(ai, bj, At, Bt) do { __builtin_amdgcn_s_setprio(1); _Pragma("unroll") for (int m = 0; m < 4; ++m) _Pragma("unroll") for (int n = 0; n < 2; ++n) _Pragma("unroll") for (int k = 0; k < 2; ++k) \
;         acc[ai][bj][m][n] = __builtin_amdgcn_mfma_f32_16x16x32_bf16(Bt[n][k], At[m][k], acc[ai][bj][m][n], 0, 0, 0); __builtin_amdgcn_s_setprio(0); } while (0)
; #define PG8_WAIT_V(n) asm volatile("s_waitcnt vmcnt(" #n ")" ::: "memory")
; #define PG8_WAIT_L(n) asm volatile("s_waitcnt lgkmcnt(" #n ")" ::: "memory")
; #define PG8_BAR __builtin_amdgcn_s_barrier()
; #define PG8_SCHED __builtin_amdgcn_sched_barrier(0)
; template <class Epi, class Sched, bool ALIGN_EPI = false, bool SP2 = false>
; __device__ __forceinline__ void gemm_phase(PG8_LAS unsigned char* lds, const Gemm g, const Sched& S, const Epi& E) {
;     ...
;             PG8_WAIT_V(8); PG8_WAIT_L(0); PG8_BAR; PG8_MMA(0, 0, At, B0); PG8_MMA(0, 1, At, B1); PG8_BAR; PG8_SCHED;
;             PG8_LDA(At, 0, 1); PG8_STAGE(PG8_SB(0, 0), b2, voffB); PG8_STAGE(PG8_SB(0, 1), b2 + hstep, voffB); PG8_STAGE(PG8_SA(0, 0), a2, voffA);
.LfwP2_0_e:
	s_waitcnt lgkmcnt(0)
	s_barrier
	s_setprio 1
	s_waitcnt lgkmcnt(0)
	v_mfma_f32_16x16x32_bf16 v[124:127], v[144:147], v[184:187], 0
	v_mfma_f32_16x16x32_bf16 v[120:123], v[160:163], v[184:187], 0
	v_mfma_f32_16x16x32_bf16 v[116:119], v[144:147], v[192:195], 0
	v_mfma_f32_16x16x32_bf16 v[108:111], v[160:163], v[192:195], 0
	v_mfma_f32_16x16x32_bf16 v[100:103], v[144:147], v[200:203], 0
	v_mfma_f32_16x16x32_bf16 v[92:95], v[160:163], v[200:203], 0
	v_mfma_f32_16x16x32_bf16 v[84:87], v[144:147], v[208:211], 0
	v_mfma_f32_16x16x32_bf16 v[76:79], v[160:163], v[208:211], 0
	v_mfma_f32_16x16x32_bf16 v[124:127], v[156:159], v[188:191], v[124:127]
	v_mfma_f32_16x16x32_bf16 v[120:123], v[164:167], v[188:191], v[120:123]
	v_mfma_f32_16x16x32_bf16 v[116:119], v[156:159], v[196:199], v[116:119]
	v_mfma_f32_16x16x32_bf16 v[108:111], v[164:167], v[196:199], v[108:111]
	v_mfma_f32_16x16x32_bf16 v[100:103], v[156:159], v[204:207], v[100:103]
	v_mfma_f32_16x16x32_bf16 v[92:95], v[164:167], v[204:207], v[92:95]
	v_mfma_f32_16x16x32_bf16 v[84:87], v[156:159], v[212:215], v[84:87]
	v_mfma_f32_16x16x32_bf16 v[76:79], v[164:167], v[212:215], v[76:79]
	s_setprio 0
	s_setprio 1
	v_mfma_f32_16x16x32_bf16 v[112:115], v[168:171], v[184:187], 0
	v_mfma_f32_16x16x32_bf16 v[104:107], v[176:179], v[184:187], 0
	v_mfma_f32_16x16x32_bf16 v[96:99], v[168:171], v[192:195], 0
	v_mfma_f32_16x16x32_bf16 v[88:91], v[176:179], v[192:195], 0
	v_mfma_f32_16x16x32_bf16 v[80:83], v[168:171], v[200:203], 0
	v_mfma_f32_16x16x32_bf16 v[72:75], v[176:179], v[200:203], 0
	v_mfma_f32_16x16x32_bf16 v[68:71], v[168:171], v[208:211], 0
	v_mfma_f32_16x16x32_bf16 v[64:67], v[176:179], v[208:211], 0
	v_mfma_f32_16x16x32_bf16 v[112:115], v[172:175], v[188:191], v[112:115]
	v_mfma_f32_16x16x32_bf16 v[104:107], v[180:183], v[188:191], v[104:107]
	v_mfma_f32_16x16x32_bf16 v[96:99], v[172:175], v[196:199], v[96:99]
	v_mfma_f32_16x16x32_bf16 v[88:91], v[180:183], v[196:199], v[88:91]
	v_mfma_f32_16x16x32_bf16 v[80:83], v[172:175], v[204:207], v[80:83]
	v_mfma_f32_16x16x32_bf16 v[72:75], v[180:183], v[204:207], v[72:75]
	v_mfma_f32_16x16x32_bf16 v[68:71], v[172:175], v[212:215], v[68:71]
	v_mfma_f32_16x16x32_bf16 v[64:67], v[180:183], v[212:215], v[64:67]
	s_setprio 0
	s_barrier
	s_add_i32 s33, s76, s54
	s_add_u32 s56, s44, s10
	s_addc_u32 s57, s45, s11
	s_mov_b32 m0, s33
	ds_read_b128 v[184:187], v154 offset:16384
	ds_read_b128 v[188:191], v154 offset:17408
	ds_read_b128 v[192:195], v154 offset:18432
	ds_read_b128 v[196:199], v154 offset:19456
	ds_read_b128 v[200:203], v154 offset:20480
	ds_read_b128 v[204:207], v154 offset:21504
	ds_read_b128 v[208:211], v154 offset:22528
	ds_read_b128 v[212:215], v154 offset:23552
	global_load_lds_dwordx4 v130, s[44:45]
	s_add_i32 m0, s33, 0x2000
	s_add_u32 s90, s44, 0x40000
	s_addc_u32 s91, s45, 0
	s_add_i32 s33, s77, s54
	global_load_lds_dwordx4 v134, s[44:45]
	s_mov_b32 m0, s33
	s_add_u32 s58, s46, s10
	s_addc_u32 s59, s47, s11
	global_load_lds_dwordx4 v130, s[90:91]
	s_add_i32 m0, s33, 0x2000
	s_nop 0
	global_load_lds_dwordx4 v134, s[90:91]
	s_mov_b32 m0, s41
	s_nop 0
	global_load_lds_dwordx4 v128, s[46:47]
	s_mov_b32 m0, s63
	s_nop 0
	global_load_lds_dwordx4 v132, s[46:47]
	s_cmp_eq_u32 s60, 0
	s_cbranch_scc1 .LfwP2_1_s
	s_waitcnt vmcnt(24)
	s_branch .LfwP2_1_e

; #define PG8_STAGE(bufoff, gbase, voff) do { _Pragma("unroll") for (int _i = 0; _i < 2; ++_i) \
;         __builtin_amdgcn_global_load_lds((const unsigned*)((const char*)(gbase) + (voff)[_i]), (PG8_LAS unsigned*)(lds + (bufoff) + ldsw + _i * 8192), 16, 0, 0); } while (0)
; #define PG8_LDA(dst, b, h) do { _Pragma("unroll") for (int m = 0; m < 4; ++m) _Pragma("unroll") for (int k = 0; k < 2; ++k) dst[m][k] = *(const PG8_LAS bf16x8*)(lds + PG8_SA(b, h) + aoff + m * 2048 + k * 1024); } while (0)
; #define PG8_LDB(dst, b, h) do { _Pragma("unroll") for (int n = 0; n < 2; ++n) _Pragma("unroll") for (int k = 0; k < 2; ++k) dst[n][k] = *(const PG8_LAS bf16x8*)(lds + PG8_SB(b, h) + boff + n * 2048 + k * 1024); } while (0)
; #define PG8_MMA(ai, bj, At, Bt) do { __builtin_amdgcn_s_setprio(1); _Pragma("unroll") for (int m = 0; m < 4; ++m) _Pragma("unroll") for (int n = 0; n < 2; ++n) _Pragma("unroll") for (int k = 0; k < 2; ++k) \
;         acc[ai][bj][m][n] = __builtin_amdgcn_mfma_f32_16x16x32_bf16(Bt[n][k], At[m][k], acc[ai][bj][m][n], 0, 0, 0); __builtin_amdgcn_s_setprio(0); } while (0)
; #define PG8_WAIT_V(n) asm volatile("s_waitcnt vmcnt(" #n ")" ::: "memory")
; #define PG8_WAIT_L(n) asm volatile("s_waitcnt lgkmcnt(" #n ")" ::: "memory")
; #define PG8_BAR __builtin_amdgcn_s_barrier()
; #define PG8_SCHED __builtin_amdgcn_sched_barrier(0)
; template <class Epi, class Sched, bool ALIGN_EPI = false, bool SP2 = false>
; __device__ __forceinline__ void gemm_phase(PG8_LAS unsigned char* lds, const Gemm g, const Sched& S, const Epi& E) {
;     ...
;             PG8_WAIT_V(8); PG8_WAIT_L(0); PG8_BAR; PG8_MMA(1, 0, At, B0); PG8_MMA(1, 1, At, B1); PG8_BAR; PG8_SCHED;
;             PG8_LDB(B0, 1, 0); PG8_LDB(B1, 1, 1); PG8_SCHED; PG8_LDA(At, 1, 0); PG8_STAGE(PG8_SA(0, 1), a2 + hstep, voffA);
;             PG8_WAIT_V(8); PG8_WAIT_L(0); PG8_BAR; PG8_MMA(0, 0, At, B0); PG8_MMA(0, 1, At, B1); PG8_BAR; PG8_SCHED;
.LfwP2_1_e:
	s_waitcnt lgkmcnt(0)
	s_barrier
	s_setprio 1
	s_waitcnt lgkmcnt(0)
	v_mfma_f32_16x16x32_bf16 v[60:63], v[144:147], v[184:187], 0
	v_mfma_f32_16x16x32_bf16 v[56:59], v[160:163], v[184:187], 0
	v_mfma_f32_16x16x32_bf16 v[52:55], v[144:147], v[192:195], 0
	v_mfma_f32_16x16x32_bf16 v[44:47], v[160:163], v[192:195], 0
	v_mfma_f32_16x16x32_bf16 v[36:39], v[144:147], v[200:203], 0
	v_mfma_f32_16x16x32_bf16 v[28:31], v[160:163], v[200:203], 0
	v_mfma_f32_16x16x32_bf16 v[20:23], v[144:147], v[208:211], 0
	v_mfma_f32_16x16x32_bf16 v[12:15], v[160:163], v[208:211], 0
	v_mfma_f32_16x16x32_bf16 v[60:63], v[156:159], v[188:191], v[60:63]
	v_mfma_f32_16x16x32_bf16 v[56:59], v[164:167], v[188:191], v[56:59]
	v_mfma_f32_16x16x32_bf16 v[52:55], v[156:159], v[196:199], v[52:55]
	v_mfma_f32_16x16x32_bf16 v[44:47], v[164:167], v[196:199], v[44:47]
	v_mfma_f32_16x16x32_bf16 v[36:39], v[156:159], v[204:207], v[36:39]
	v_mfma_f32_16x16x32_bf16 v[28:31], v[164:167], v[204:207], v[28:31]
	v_mfma_f32_16x16x32_bf16 v[20:23], v[156:159], v[212:215], v[20:23]
	v_mfma_f32_16x16x32_bf16 v[12:15], v[164:167], v[212:215], v[12:15]
	s_setprio 0
	s_setprio 1
	v_mfma_f32_16x16x32_bf16 v[48:51], v[168:171], v[184:187], 0
	v_mfma_f32_16x16x32_bf16 v[40:43], v[176:179], v[184:187], 0
	v_mfma_f32_16x16x32_bf16 v[32:35], v[168:171], v[192:195], 0
	v_mfma_f32_16x16x32_bf16 v[24:27], v[176:179], v[192:195], 0
	v_mfma_f32_16x16x32_bf16 v[16:19], v[168:171], v[200:203], 0
	v_mfma_f32_16x16x32_bf16 v[8:11], v[176:179], v[200:203], 0
	v_mfma_f32_16x16x32_bf16 v[4:7], v[168:171], v[208:211], 0
	v_mfma_f32_16x16x32_bf16 v[0:3], v[176:179], v[208:211], 0
	v_mfma_f32_16x16x32_bf16 v[48:51], v[172:175], v[188:191], v[48:51]
	v_mfma_f32_16x16x32_bf16 v[40:43], v[180:183], v[188:191], v[40:43]
	v_mfma_f32_16x16x32_bf16 v[32:35], v[172:175], v[196:199], v[32:35]
	v_mfma_f32_16x16x32_bf16 v[24:27], v[180:183], v[196:199], v[24:27]
	v_mfma_f32_16x16x32_bf16 v[16:19], v[172:175], v[204:207], v[16:19]
	v_mfma_f32_16x16x32_bf16 v[8:11], v[180:183], v[204:207], v[8:11]
	v_mfma_f32_16x16x32_bf16 v[4:7], v[172:175], v[212:215], v[4:7]
	v_mfma_f32_16x16x32_bf16 v[0:3], v[180:183], v[212:215], v[0:3]
	s_setprio 0
	s_barrier
	s_add_i32 s33, 0, 0x18000
	v_add_u32_e32 v155, s33, v149
	s_add_i32 s34, 0, 0x1c000
	ds_read_b128 v[144:147], v155
	ds_read_b128 v[156:159], v155 offset:1024
	ds_read_b128 v[160:163], v155 offset:2048
	ds_read_b128 v[164:167], v155 offset:3072
	v_add_u32_e32 v155, s34, v149
	ds_read_b128 v[168:171], v155
	ds_read_b128 v[172:175], v155 offset:1024
	ds_read_b128 v[176:179], v155 offset:2048
	ds_read_b128 v[180:183], v155 offset:3072
	s_add_u32 s46, s46, 0x40000
	s_addc_u32 s47, s47, 0
	s_mov_b32 m0, s70
	ds_read_b128 v[184:187], v154 offset:32768
	ds_read_b128 v[188:191], v154 offset:33792
	ds_read_b128 v[192:195], v154 offset:34816
	ds_read_b128 v[196:199], v154 offset:35840
	ds_read_b128 v[200:203], v154 offset:36864
	ds_read_b128 v[204:207], v154 offset:37888
	ds_read_b128 v[208:211], v154 offset:38912
	ds_read_b128 v[212:215], v154 offset:39936
	global_load_lds_dwordx4 v128, s[46:47]
	s_mov_b32 m0, s71
	s_nop 0
	global_load_lds_dwordx4 v132, s[46:47]
	s_waitcnt vmcnt(8)
	s_waitcnt lgkmcnt(0)
	s_barrier
	s_setprio 1
	s_waitcnt lgkmcnt(0)
	v_mfma_f32_16x16x32_bf16 v[124:127], v[144:147], v[184:187], v[124:127]
	v_mfma_f32_16x16x32_bf16 v[120:123], v[160:163], v[184:187], v[120:123]
	v_mfma_f32_16x16x32_bf16 v[116:119], v[144:147], v[192:195], v[116:119]
	v_mfma_f32_16x16x32_bf16 v[108:111], v[160:163], v[192:195], v[108:111]
	v_mfma_f32_16x16x32_bf16 v[100:103], v[144:147], v[200:203], v[100:103]
	v_mfma_f32_16x16x32_bf16 v[92:95], v[160:163], v[200:203], v[92:95]
	v_mfma_f32_16x16x32_bf16 v[84:87], v[144:147], v[208:211], v[84:87]
	v_mfma_f32_16x16x32_bf16 v[76:79], v[160:163], v[208:211], v[76:79]
	v_mfma_f32_16x16x32_bf16 v[124:127], v[156:159], v[188:191], v[124:127]
	v_mfma_f32_16x16x32_bf16 v[120:123], v[164:167], v[188:191], v[120:123]
	v_mfma_f32_16x16x32_bf16 v[116:119], v[156:159], v[196:199], v[116:119]
	v_mfma_f32_16x16x32_bf16 v[108:111], v[164:167], v[196:199], v[108:111]
	v_mfma_f32_16x16x32_bf16 v[100:103], v[156:159], v[204:207], v[100:103]
	v_mfma_f32_16x16x32_bf16 v[92:95], v[164:167], v[204:207], v[92:95]
	v_mfma_f32_16x16x32_bf16 v[84:87], v[156:159], v[212:215], v[84:87]
	v_mfma_f32_16x16x32_bf16 v[76:79], v[164:167], v[212:215], v[76:79]
	s_setprio 0
	s_setprio 1
	v_mfma_f32_16x16x32_bf16 v[112:115], v[168:171], v[184:187], v[112:115]
	v_mfma_f32_16x16x32_bf16 v[104:107], v[176:179], v[184:187], v[104:107]
	v_mfma_f32_16x16x32_bf16 v[96:99], v[168:171], v[192:195], v[96:99]
	v_mfma_f32_16x16x32_bf16 v[88:91], v[176:179], v[192:195], v[88:91]
	v_mfma_f32_16x16x32_bf16 v[80:83], v[168:171], v[200:203], v[80:83]
	v_mfma_f32_16x16x32_bf16 v[72:75], v[176:179], v[200:203], v[72:75]
	v_mfma_f32_16x16x32_bf16 v[68:71], v[168:171], v[208:211], v[68:71]
	v_mfma_f32_16x16x32_bf16 v[64:67], v[176:179], v[208:211], v[64:67]
	v_mfma_f32_16x16x32_bf16 v[112:115], v[172:175], v[188:191], v[112:115]
	v_mfma_f32_16x16x32_bf16 v[104:107], v[180:183], v[188:191], v[104:107]
	v_mfma_f32_16x16x32_bf16 v[96:99], v[172:175], v[196:199], v[96:99]
	v_mfma_f32_16x16x32_bf16 v[88:91], v[180:183], v[196:199], v[88:91]
	v_mfma_f32_16x16x32_bf16 v[80:83], v[172:175], v[204:207], v[80:83]
	v_mfma_f32_16x16x32_bf16 v[72:75], v[180:183], v[204:207], v[72:75]
	v_mfma_f32_16x16x32_bf16 v[68:71], v[172:175], v[212:215], v[68:71]
	v_mfma_f32_16x16x32_bf16 v[64:67], v[180:183], v[212:215], v[64:67]
	s_setprio 0
	s_barrier
; #define PG8_STAGE(bufoff, gbase, voff) do { _Pragma("unroll") for (int _i = 0; _i < 2; ++_i) \
;         __builtin_amdgcn_global_load_lds((const unsigned*)((const char*)(gbase) + (voff)[_i]), (PG8_LAS unsigned*)(lds + (bufoff) + ldsw + _i * 8192), 16, 0, 0); } while (0)
; #define PG8_LDA(dst, b, h) do { _Pragma("unroll") for (int m = 0; m < 4; ++m) _Pragma("unroll") for (int k = 0; k < 2; ++k) dst[m][k] = *(const PG8_LAS bf16x8*)(lds + PG8_SA(b, h) + aoff + m * 2048 + k * 1024); } while (0)
; #define PG8_MMA(ai, bj, At, Bt) do { __builtin_amdgcn_s_setprio(1); _Pragma("unroll") for (int m = 0; m < 4; ++m) _Pragma("unroll") for (int n = 0; n < 2; ++n) _Pragma("unroll") for (int k = 0; k < 2; ++k) \
;         acc[ai][bj][m][n] = __builtin_amdgcn_mfma_f32_16x16x32_bf16(Bt[n][k], At[m][k], acc[ai][bj][m][n], 0, 0, 0); __builtin_amdgcn_s_setprio(0); } while (0)
; #define PG8_WAIT_V(n) asm volatile("s_waitcnt vmcnt(" #n ")" ::: "memory")
; #define PG8_WAIT_L(n) asm volatile("s_waitcnt lgkmcnt(" #n ")" ::: "memory")
; #define PG8_BAR __builtin_amdgcn_s_barrier()
; #define PG8_SCHED __builtin_amdgcn_sched_barrier(0)
; template <class Epi, class Sched, bool ALIGN_EPI = false, bool SP2 = false>
; __device__ __forceinline__ void gemm_phase(PG8_LAS unsigned char* lds, const Gemm g, const Sched& S, const Epi& E) {
;     ...
;             PG8_LDA(At, 1, 1); PG8_STAGE(PG8_SB(1, 0), b3, voffB); PG8_STAGE(PG8_SB(1, 1), b3 + hstep, voffB); PG8_STAGE(PG8_SA(1, 0), a3, voffA);
;             PG8_WAIT_V(8); PG8_WAIT_L(0); PG8_BAR; PG8_MMA(1, 0, At, B0); PG8_MMA(1, 1, At, B1); PG8_BAR; PG8_SCHED;
	s_add_i32 s33, s33, s54
	s_mov_b32 m0, s33
	ds_read_b128 v[184:187], v154 offset:49152
	ds_read_b128 v[188:191], v154 offset:50176
	ds_read_b128 v[192:195], v154 offset:51200
	ds_read_b128 v[196:199], v154 offset:52224
	ds_read_b128 v[200:203], v154 offset:53248
	ds_read_b128 v[204:207], v154 offset:54272
	ds_read_b128 v[208:211], v154 offset:55296
	ds_read_b128 v[212:215], v154 offset:56320
	global_load_lds_dwordx4 v130, s[56:57]
	s_add_i32 m0, s33, 0x2000
	s_add_u32 s44, s44, 0x40080
	s_addc_u32 s45, s45, 0
	s_add_i32 s33, s34, s54
	global_load_lds_dwordx4 v134, s[56:57]
	s_mov_b32 m0, s33
	s_nop 0
	global_load_lds_dwordx4 v130, s[44:45]
	s_add_i32 m0, s33, 0x2000
	s_nop 0
	global_load_lds_dwordx4 v134, s[44:45]
	s_mov_b32 m0, s74
	s_nop 0
	global_load_lds_dwordx4 v128, s[58:59]
	s_mov_b32 m0, s75
	s_nop 0
	global_load_lds_dwordx4 v132, s[58:59]
	s_waitcnt vmcnt(8)
	s_waitcnt lgkmcnt(0)
	s_barrier
	s_setprio 1
	s_waitcnt lgkmcnt(0)
	v_mfma_f32_16x16x32_bf16 v[60:63], v[144:147], v[184:187], v[60:63]
	v_mfma_f32_16x16x32_bf16 v[56:59], v[160:163], v[184:187], v[56:59]
	v_mfma_f32_16x16x32_bf16 v[52:55], v[144:147], v[192:195], v[52:55]
	v_mfma_f32_16x16x32_bf16 v[44:47], v[160:163], v[192:195], v[44:47]
	v_mfma_f32_16x16x32_bf16 v[36:39], v[144:147], v[200:203], v[36:39]
	v_mfma_f32_16x16x32_bf16 v[28:31], v[160:163], v[200:203], v[28:31]
	v_mfma_f32_16x16x32_bf16 v[20:23], v[144:147], v[208:211], v[20:23]
	v_mfma_f32_16x16x32_bf16 v[12:15], v[160:163], v[208:211], v[12:15]
	v_mfma_f32_16x16x32_bf16 v[60:63], v[156:159], v[188:191], v[60:63]
	v_mfma_f32_16x16x32_bf16 v[56:59], v[164:167], v[188:191], v[56:59]
	v_mfma_f32_16x16x32_bf16 v[52:55], v[156:159], v[196:199], v[52:55]
	v_mfma_f32_16x16x32_bf16 v[44:47], v[164:167], v[196:199], v[44:47]
	v_mfma_f32_16x16x32_bf16 v[36:39], v[156:159], v[204:207], v[36:39]
	v_mfma_f32_16x16x32_bf16 v[28:31], v[164:167], v[204:207], v[28:31]
	v_mfma_f32_16x16x32_bf16 v[20:23], v[156:159], v[212:215], v[20:23]
	v_mfma_f32_16x16x32_bf16 v[12:15], v[164:167], v[212:215], v[12:15]
	s_setprio 0
	s_setprio 1
	v_mfma_f32_16x16x32_bf16 v[48:51], v[168:171], v[184:187], v[48:51]
	v_mfma_f32_16x16x32_bf16 v[40:43], v[176:179], v[184:187], v[40:43]
	v_mfma_f32_16x16x32_bf16 v[32:35], v[168:171], v[192:195], v[32:35]
	v_mfma_f32_16x16x32_bf16 v[24:27], v[176:179], v[192:195], v[24:27]
	v_mfma_f32_16x16x32_bf16 v[16:19], v[168:171], v[200:203], v[16:19]
	v_mfma_f32_16x16x32_bf16 v[8:11], v[176:179], v[200:203], v[8:11]
	v_mfma_f32_16x16x32_bf16 v[4:7], v[168:171], v[208:211], v[4:7]
	v_mfma_f32_16x16x32_bf16 v[0:3], v[176:179], v[208:211], v[0:3]
	v_mfma_f32_16x16x32_bf16 v[48:51], v[172:175], v[188:191], v[48:51]
	v_mfma_f32_16x16x32_bf16 v[40:43], v[180:183], v[188:191], v[40:43]
	v_mfma_f32_16x16x32_bf16 v[32:35], v[172:175], v[196:199], v[32:35]
	v_mfma_f32_16x16x32_bf16 v[24:27], v[180:183], v[196:199], v[24:27]
	v_mfma_f32_16x16x32_bf16 v[16:19], v[172:175], v[204:207], v[16:19]
	v_mfma_f32_16x16x32_bf16 v[8:11], v[180:183], v[204:207], v[8:11]
	v_mfma_f32_16x16x32_bf16 v[4:7], v[172:175], v[212:215], v[4:7]
	v_mfma_f32_16x16x32_bf16 v[0:3], v[180:183], v[212:215], v[0:3]
	s_setprio 0
	s_barrier
	s_add_i32 s86, s86, 2
	s_add_u32 s42, s42, 0x100
	s_addc_u32 s43, s43, 0
	s_add_u32 s82, s82, 0x100
	s_addc_u32 s83, s83, 0
	s_cmp_gt_u32 s86, 13

; __device__ __forceinline__ unsigned pk2(float lo, float hi) { f32x2 v = {lo, hi}; bf16x2_t b = __builtin_convertvector(v, bf16x2_t); return __builtin_bit_cast(unsigned, b); }
;     __device__ __forceinline__ void operator()(const f32x4 (&acc)[2][2][4][2], const Unit& u, int wr, int wc, int fr, int fq) const {
;         const int row0 = u.pm * BM + wr * 64 + fr; const int col0 = u.pn * BM + wc * 32 + 8 * fq;
; #pragma unroll
;         for (int ai = 0; ai < 2; ++ai)
; #pragma unroll
;             for (int m = 0; m < 4; ++m) { const int row = row0 + ai * HALF + m * 16; const float rb = rowbias ? rowbias[row] : 0.f; bf16_t* rowp = O + (size_t)row * ldc + col0;
; #pragma unroll
;                 for (int bj = 0; bj < 2; ++bj) { const f32x4 v0 = acc[ai][bj][m][0] + rb, v1 = acc[ai][bj][m][1] + rb;
;                     u32x4 w; w.x = pk2(v0[0], v0[1]); w.y = pk2(v0[2], v0[3]); w.z = pk2(v1[0], v1[1]); w.w = pk2(v1[2], v1[3]);
;                     *(u32x4*)(rowp + bj * HALF) = w; } }
.LBB0_384:
	s_mov_b32 s60, 1
	v_lshl_or_b32 v146, s79, 8, v150
	v_lshl_add_u32 v155, s40, 8, v148
	v_ashrrev_i32_e32 v147, 31, v146
	v_mov_b64_e32 v[144:145], s[8:9]
	v_mad_i64_i32 v[156:157], s[42:43], v155, s78, v[144:145]
	v_lshlrev_b64 v[146:147], 1, v[146:147]
	v_pk_add_f32 v[126:127], v[126:127], 0 op_sel_hi:[1,0]
	v_pk_add_f32 v[124:125], v[124:125], 0 op_sel_hi:[1,0]
	v_pk_add_f32 v[158:159], v[122:123], 0 op_sel_hi:[1,0]
	v_pk_add_f32 v[122:123], v[120:121], 0 op_sel_hi:[1,0]
	v_lshl_add_u64 v[156:157], v[156:157], 0, v[146:147]
	v_cvt_pk_bf16_f32 v120, v124, v125
	v_cvt_pk_bf16_f32 v121, v126, v127
	v_cvt_pk_bf16_f32 v122, v122, v123
	v_cvt_pk_bf16_f32 v123, v158, v159
	global_store_dwordx4 v[156:157], v[120:123], off
	v_pk_add_f32 v[114:115], v[114:115], 0 op_sel_hi:[1,0]
	v_pk_add_f32 v[112:113], v[112:113], 0 op_sel_hi:[1,0]
	v_pk_add_f32 v[120:121], v[106:107], 0 op_sel_hi:[1,0]
	v_pk_add_f32 v[106:107], v[104:105], 0 op_sel_hi:[1,0]
	v_cvt_pk_bf16_f32 v104, v112, v113
	v_cvt_pk_bf16_f32 v105, v114, v115
	v_cvt_pk_bf16_f32 v106, v106, v107
	v_cvt_pk_bf16_f32 v107, v120, v121
	global_store_dwordx4 v[156:157], v[104:107], off offset:256
	v_pk_add_f32 v[110:111], v[110:111], 0 op_sel_hi:[1,0]
	v_pk_add_f32 v[108:109], v[108:109], 0 op_sel_hi:[1,0]
	v_or_b32_e32 v104, 16, v155
	v_mad_i64_i32 v[104:105], s[42:43], v104, s78, v[144:145]
	v_lshl_add_u64 v[112:113], v[104:105], 0, v[146:147]
	v_pk_add_f32 v[106:107], v[118:119], 0 op_sel_hi:[1,0]
	v_pk_add_f32 v[104:105], v[116:117], 0 op_sel_hi:[1,0]
	v_pk_add_f32 v[98:99], v[98:99], 0 op_sel_hi:[1,0]
	v_cvt_pk_bf16_f32 v104, v104, v105
	v_cvt_pk_bf16_f32 v105, v106, v107
	v_cvt_pk_bf16_f32 v106, v108, v109
	v_cvt_pk_bf16_f32 v107, v110, v111
	global_store_dwordx4 v[112:113], v[104:107], off
	v_pk_add_f32 v[96:97], v[96:97], 0 op_sel_hi:[1,0]
	v_pk_add_f32 v[94:95], v[94:95], 0 op_sel_hi:[1,0]
	v_pk_add_f32 v[104:105], v[90:91], 0 op_sel_hi:[1,0]
	v_pk_add_f32 v[90:91], v[88:89], 0 op_sel_hi:[1,0]
	v_cvt_pk_bf16_f32 v88, v96, v97
	v_cvt_pk_bf16_f32 v89, v98, v99
	v_cvt_pk_bf16_f32 v90, v90, v91
	v_cvt_pk_bf16_f32 v91, v104, v105
	global_store_dwordx4 v[112:113], v[88:91], off offset:256
	v_pk_add_f32 v[92:93], v[92:93], 0 op_sel_hi:[1,0]
	v_pk_add_f32 v[82:83], v[82:83], 0 op_sel_hi:[1,0]
	v_or_b32_e32 v88, 32, v155
	v_mad_i64_i32 v[88:89], s[42:43], v88, s78, v[144:145]
	v_lshl_add_u64 v[96:97], v[88:89], 0, v[146:147]
	v_pk_add_f32 v[90:91], v[102:103], 0 op_sel_hi:[1,0]
	v_pk_add_f32 v[88:89], v[100:101], 0 op_sel_hi:[1,0]
	v_pk_add_f32 v[80:81], v[80:81], 0 op_sel_hi:[1,0]
	v_cvt_pk_bf16_f32 v88, v88, v89
	v_cvt_pk_bf16_f32 v89, v90, v91
	v_cvt_pk_bf16_f32 v90, v92, v93
	v_cvt_pk_bf16_f32 v91, v94, v95
	global_store_dwordx4 v[96:97], v[88:91], off
	v_pk_add_f32 v[78:79], v[78:79], 0 op_sel_hi:[1,0]
	v_pk_add_f32 v[76:77], v[76:77], 0 op_sel_hi:[1,0]
	v_pk_add_f32 v[88:89], v[74:75], 0 op_sel_hi:[1,0]
	v_pk_add_f32 v[74:75], v[72:73], 0 op_sel_hi:[1,0]
	v_cvt_pk_bf16_f32 v72, v80, v81
	v_cvt_pk_bf16_f32 v73, v82, v83
	v_cvt_pk_bf16_f32 v74, v74, v75
	v_cvt_pk_bf16_f32 v75, v88, v89
	global_store_dwordx4 v[96:97], v[72:75], off offset:256
	v_pk_add_f32 v[70:71], v[70:71], 0 op_sel_hi:[1,0]
	v_pk_add_f32 v[68:69], v[68:69], 0 op_sel_hi:[1,0]
	v_or_b32_e32 v72, 48, v155
	v_mad_i64_i32 v[72:73], s[42:43], v72, s78, v[144:145]
	v_lshl_add_u64 v[80:81], v[72:73], 0, v[146:147]
	v_pk_add_f32 v[74:75], v[86:87], 0 op_sel_hi:[1,0]
	v_pk_add_f32 v[72:73], v[84:85], 0 op_sel_hi:[1,0]
	v_pk_add_f32 v[62:63], v[62:63], 0 op_sel_hi:[1,0]
	v_cvt_pk_bf16_f32 v72, v72, v73
	v_cvt_pk_bf16_f32 v73, v74, v75
	v_cvt_pk_bf16_f32 v74, v76, v77
	v_cvt_pk_bf16_f32 v75, v78, v79
	global_store_dwordx4 v[80:81], v[72:75], off
	v_pk_add_f32 v[60:61], v[60:61], 0 op_sel_hi:[1,0]
	v_pk_add_f32 v[50:51], v[50:51], 0 op_sel_hi:[1,0]
	v_pk_add_f32 v[72:73], v[66:67], 0 op_sel_hi:[1,0]
; __device__ __forceinline__ unsigned pk2(float lo, float hi) { f32x2 v = {lo, hi}; bf16x2_t b = __builtin_convertvector(v, bf16x2_t); return __builtin_bit_cast(unsigned, b); }
;     __device__ __forceinline__ void operator()(const f32x4 (&acc)[2][2][4][2], const Unit& u, int wr, int wc, int fr, int fq) const {
;     ...
;             for (int m = 0; m < 4; ++m) { const int row = row0 + ai * HALF + m * 16; const float rb = rowbias ? rowbias[row] : 0.f; bf16_t* rowp = O + (size_t)row * ldc + col0;
; #pragma unroll
;                 for (int bj = 0; bj < 2; ++bj) { const f32x4 v0 = acc[ai][bj][m][0] + rb, v1 = acc[ai][bj][m][1] + rb;
;                     u32x4 w; w.x = pk2(v0[0], v0[1]); w.y = pk2(v0[2], v0[3]); w.z = pk2(v1[0], v1[1]); w.w = pk2(v1[2], v1[3]);
;                     *(u32x4*)(rowp + bj * HALF) = w; } }
	v_pk_add_f32 v[66:67], v[64:65], 0 op_sel_hi:[1,0]
	v_cvt_pk_bf16_f32 v64, v68, v69
	v_cvt_pk_bf16_f32 v65, v70, v71
	v_cvt_pk_bf16_f32 v66, v66, v67
	v_cvt_pk_bf16_f32 v67, v72, v73
	global_store_dwordx4 v[80:81], v[64:67], off offset:256
	v_pk_add_f32 v[48:49], v[48:49], 0 op_sel_hi:[1,0]
	v_pk_add_f32 v[46:47], v[46:47], 0 op_sel_hi:[1,0]
	v_add_u32_e32 v64, 0x80, v155
	v_mad_i64_i32 v[64:65], s[42:43], v64, s78, v[144:145]
	v_pk_add_f32 v[66:67], v[58:59], 0 op_sel_hi:[1,0]
	v_pk_add_f32 v[58:59], v[56:57], 0 op_sel_hi:[1,0]
	v_lshl_add_u64 v[64:65], v[64:65], 0, v[146:147]
	v_cvt_pk_bf16_f32 v56, v60, v61
	v_cvt_pk_bf16_f32 v57, v62, v63
	v_cvt_pk_bf16_f32 v58, v58, v59
	v_cvt_pk_bf16_f32 v59, v66, v67
	global_store_dwordx4 v[64:65], v[56:59], off
	v_pk_add_f32 v[44:45], v[44:45], 0 op_sel_hi:[1,0]
	v_pk_add_f32 v[34:35], v[34:35], 0 op_sel_hi:[1,0]
	v_pk_add_f32 v[56:57], v[42:43], 0 op_sel_hi:[1,0]
	v_pk_add_f32 v[42:43], v[40:41], 0 op_sel_hi:[1,0]
	v_cvt_pk_bf16_f32 v40, v48, v49
	v_cvt_pk_bf16_f32 v41, v50, v51
	v_cvt_pk_bf16_f32 v42, v42, v43
	v_cvt_pk_bf16_f32 v43, v56, v57
	global_store_dwordx4 v[64:65], v[40:43], off offset:256
	v_pk_add_f32 v[32:33], v[32:33], 0 op_sel_hi:[1,0]
	v_pk_add_f32 v[30:31], v[30:31], 0 op_sel_hi:[1,0]
	v_add_u32_e32 v40, 0x90, v155
	v_mad_i64_i32 v[40:41], s[42:43], v40, s78, v[144:145]
	v_lshl_add_u64 v[48:49], v[40:41], 0, v[146:147]
	v_pk_add_f32 v[42:43], v[54:55], 0 op_sel_hi:[1,0]
	v_pk_add_f32 v[40:41], v[52:53], 0 op_sel_hi:[1,0]
	v_pk_add_f32 v[28:29], v[28:29], 0 op_sel_hi:[1,0]
	v_cvt_pk_bf16_f32 v40, v40, v41
	v_cvt_pk_bf16_f32 v41, v42, v43
	v_cvt_pk_bf16_f32 v42, v44, v45
	v_cvt_pk_bf16_f32 v43, v46, v47
	global_store_dwordx4 v[48:49], v[40:43], off
	v_pk_add_f32 v[18:19], v[18:19], 0 op_sel_hi:[1,0]
	v_pk_add_f32 v[16:17], v[16:17], 0 op_sel_hi:[1,0]
	v_pk_add_f32 v[40:41], v[26:27], 0 op_sel_hi:[1,0]
	v_pk_add_f32 v[26:27], v[24:25], 0 op_sel_hi:[1,0]
	v_cvt_pk_bf16_f32 v24, v32, v33
	v_cvt_pk_bf16_f32 v25, v34, v35
	v_cvt_pk_bf16_f32 v26, v26, v27
	v_cvt_pk_bf16_f32 v27, v40, v41
	global_store_dwordx4 v[48:49], v[24:27], off offset:256
	v_pk_add_f32 v[14:15], v[14:15], 0 op_sel_hi:[1,0]
	v_pk_add_f32 v[12:13], v[12:13], 0 op_sel_hi:[1,0]
	v_add_u32_e32 v24, 0xa0, v155
	v_mad_i64_i32 v[24:25], s[42:43], v24, s78, v[144:145]
	v_lshl_add_u64 v[32:33], v[24:25], 0, v[146:147]
	v_pk_add_f32 v[26:27], v[38:39], 0 op_sel_hi:[1,0]
	v_pk_add_f32 v[24:25], v[36:37], 0 op_sel_hi:[1,0]
	v_pk_add_f32 v[6:7], v[6:7], 0 op_sel_hi:[1,0]
	v_cvt_pk_bf16_f32 v24, v24, v25
	v_cvt_pk_bf16_f32 v25, v26, v27
	v_cvt_pk_bf16_f32 v26, v28, v29
	v_cvt_pk_bf16_f32 v27, v30, v31
	global_store_dwordx4 v[32:33], v[24:27], off
	v_pk_add_f32 v[4:5], v[4:5], 0 op_sel_hi:[1,0]
	s_andn2_b64 vcc, exec, s[0:1]
	v_pk_add_f32 v[24:25], v[10:11], 0 op_sel_hi:[1,0]
	v_pk_add_f32 v[10:11], v[8:9], 0 op_sel_hi:[1,0]
	v_cvt_pk_bf16_f32 v8, v16, v17
	v_cvt_pk_bf16_f32 v9, v18, v19
	v_cvt_pk_bf16_f32 v10, v10, v11
	v_cvt_pk_bf16_f32 v11, v24, v25
	global_store_dwordx4 v[32:33], v[8:11], off offset:256
	s_mov_b64 s[0:1], -1
	s_nop 0
	v_add_u32_e32 v8, 0xb0, v155
	v_mad_i64_i32 v[8:9], s[42:43], v8, s78, v[144:145]
	v_lshl_add_u64 v[16:17], v[8:9], 0, v[146:147]
	v_pk_add_f32 v[10:11], v[22:23], 0 op_sel_hi:[1,0]
	v_pk_add_f32 v[8:9], v[20:21], 0 op_sel_hi:[1,0]
	s_nop 0
	v_cvt_pk_bf16_f32 v8, v8, v9
	v_cvt_pk_bf16_f32 v9, v10, v11
	v_cvt_pk_bf16_f32 v10, v12, v13
	v_cvt_pk_bf16_f32 v11, v14, v15
	global_store_dwordx4 v[16:17], v[8:11], off
	s_nop 1
	v_pk_add_f32 v[8:9], v[2:3], 0 op_sel_hi:[1,0]
	v_pk_add_f32 v[2:3], v[0:1], 0 op_sel_hi:[1,0]
	v_cvt_pk_bf16_f32 v0, v4, v5
	v_cvt_pk_bf16_f32 v1, v6, v7
	v_cvt_pk_bf16_f32 v2, v2, v3
	v_cvt_pk_bf16_f32 v3, v8, v9
	global_store_dwordx4 v[16:17], v[0:3], off offset:256
	s_cbranch_vccnz .LBB0_377
	s_andn2_b64 vcc, exec, s[6:7]
	s_cbranch_vccnz .LBB0_376
	s_barrier
	s_branch .LBB0_376

; #define PG8_STAGE(bufoff, gbase, voff) do { _Pragma("unroll") for (int _i = 0; _i < 2; ++_i) \
;         __builtin_amdgcn_global_load_lds((const unsigned*)((const char*)(gbase) + (voff)[_i]), (PG8_LAS unsigned*)(lds + (bufoff) + ldsw + _i * 8192), 16, 0, 0); } while (0)
; #define PG8_LDA(dst, b, h) do { _Pragma("unroll") for (int m = 0; m < 4; ++m) _Pragma("unroll") for (int k = 0; k < 2; ++k) dst[m][k] = *(const PG8_LAS bf16x8*)(lds + PG8_SA(b, h) + aoff + m * 2048 + k * 1024); } while (0)
; #define PG8_LDB(dst, b, h) do { _Pragma("unroll") for (int n = 0; n < 2; ++n) _Pragma("unroll") for (int k = 0; k < 2; ++k) dst[n][k] = *(const PG8_LAS bf16x8*)(lds + PG8_SB(b, h) + boff + n * 2048 + k * 1024); } while (0)
; #define PG8_SCHED __builtin_amdgcn_sched_barrier(0)
;     __host__ __device__ bool next(int i, Unit& u) const {
;         const long L = (long)i * G + c; if (L >= nwg) return false;
;         int wgid = (int)L; { const int q = nwg / NXCD, r = nwg % NXCD, xcd = wgid % NXCD, off = wgid / NXCD; wgid = (xcd < r ? xcd * (q + 1) : r * (q + 1) + (xcd - r) * q) + off; }
;         const int nig = WGM * nN, gid = wgid / nig, fm = gid * WGM, gsz = (nM - fm) < WGM ? (nM - fm) : WGM;
;         u.pm = fm + ((wgid % nig) % gsz); u.pn = (wgid % nig) / gsz; return true;
;     }
; template <class Epi, class Sched, bool ALIGN_EPI = false, bool SP2 = false>
; __device__ __forceinline__ void gemm_phase(PG8_LAS unsigned char* lds, const Gemm g, const Sched& S, const Epi& E) {
;     ...
;         const bool has_next = S.next(ui + 1, nxt);
;         const char* nA = has_next ? (const char*)g.A + (size_t)nxt.pm * tstep : cA; const char* nB = has_next ? (const char*)g.Bt + (size_t)nxt.pn * tstep : cB;
;         for (int t = 0; t < nt; t += 2) {
;             const bool last = (t == nt - 2);
;             const char* a1 = cA + (size_t)(t + 1) * kstep;
;             const char* a2 = last ? nA : cA + (size_t)(t + 2) * kstep; const char* b2 = last ? nB : cB + (size_t)(t + 2) * kstep;
;             const char* a3 = a2 + kstep; const char* b3 = b2 + kstep;
;             if (last && has_next) S.a_ready(nxt);
;             if constexpr (SP2) {
;             PG8_LDB(B0, 0, 0); PG8_LDB(B1, 0, 1); PG8_SCHED; PG8_LDA(At, 0, 0); PG8_STAGE(PG8_SA(1, 1), a1 + hstep, voffA);
.LBB0_583:
	ds_read_b128 v[128:131], v165
	ds_read_b128 v[132:135], v165 offset:1024
	ds_read_b128 v[154:157], v165 offset:2048
	ds_read_b128 v[158:161], v165 offset:3072
	ds_read_b128 v[168:171], v166
	ds_read_b128 v[172:175], v166 offset:1024
	ds_read_b128 v[176:179], v166 offset:2048
	ds_read_b128 v[180:183], v166 offset:3072
	ds_read_b128 v[184:187], v167
	ds_read_b128 v[188:191], v167 offset:1024
	ds_read_b128 v[192:195], v167 offset:2048
	ds_read_b128 v[196:199], v167 offset:3072
	ds_read_b128 v[200:203], v167 offset:4096
	ds_read_b128 v[204:207], v167 offset:5120
	ds_read_b128 v[208:211], v167 offset:6144
	ds_read_b128 v[212:215], v167 offset:7168
	s_add_i32 s75, s75, 1
	s_mul_i32 s0, s75, s78
	s_mul_hi_u32 s1, s75, s3
	s_add_i32 s1, s1, s0
	s_mul_i32 s0, s75, s3
	s_add_u32 s44, s0, s2
	s_addc_u32 s45, s1, s71
	v_cmp_gt_i64_e32 vcc, s[44:45], v[150:151]
	v_cmp_lt_i64_e64 s[0:1], s[44:45], v[148:149]
	s_cbranch_vccnz .LBB0_589
	s_ashr_i32 s33, s44, 31
	s_lshr_b32 s33, s33, 29
	s_add_i32 s42, s44, s33
	s_and_b32 s33, s42, -8
	s_sub_i32 s43, s44, s33
	s_cmp_gt_i32 s43, -1
	s_mov_b64 s[40:41], -1
	s_cbranch_scc0 .LBB0_586
	s_lshl_b32 s44, s43, 7
	s_mov_b64 s[40:41], 0

; #define PG8_STAGE(bufoff, gbase, voff) do { _Pragma("unroll") for (int _i = 0; _i < 2; ++_i) \
;         __builtin_amdgcn_global_load_lds((const unsigned*)((const char*)(gbase) + (voff)[_i]), (PG8_LAS unsigned*)(lds + (bufoff) + ldsw + _i * 8192), 16, 0, 0); } while (0)
; #define PG8_LDA(dst, b, h) do { _Pragma("unroll") for (int m = 0; m < 4; ++m) _Pragma("unroll") for (int k = 0; k < 2; ++k) dst[m][k] = *(const PG8_LAS bf16x8*)(lds + PG8_SA(b, h) + aoff + m * 2048 + k * 1024); } while (0)
; #define PG8_LDB(dst, b, h) do { _Pragma("unroll") for (int n = 0; n < 2; ++n) _Pragma("unroll") for (int k = 0; k < 2; ++k) dst[n][k] = *(const PG8_LAS bf16x8*)(lds + PG8_SB(b, h) + boff + n * 2048 + k * 1024); } while (0)
; #define PG8_WAIT_V(n) asm volatile("s_waitcnt vmcnt(" #n ")" ::: "memory")
; #define PG8_WAIT_L(n) asm volatile("s_waitcnt lgkmcnt(" #n ")" ::: "memory")
; #define PG8_BAR __builtin_amdgcn_s_barrier()
; #define PG8_SCHED __builtin_amdgcn_sched_barrier(0)
; template <class Epi, class Sched, bool ALIGN_EPI = false, bool SP2 = false>
; __device__ __forceinline__ void gemm_phase(PG8_LAS unsigned char* lds, const Gemm g, const Sched& S, const Epi& E) {
;     ...
;         const char* nA = has_next ? (const char*)g.A + (size_t)nxt.pm * tstep : cA; const char* nB = has_next ? (const char*)g.Bt + (size_t)nxt.pn * tstep : cB;
;         for (int t = 0; t < nt; t += 2) {
;             const bool last = (t == nt - 2);
;             const char* a1 = cA + (size_t)(t + 1) * kstep;
;             const char* a2 = last ? nA : cA + (size_t)(t + 2) * kstep; const char* b2 = last ? nB : cB + (size_t)(t + 2) * kstep;
;             const char* a3 = a2 + kstep; const char* b3 = b2 + kstep;
;             if (last && has_next) S.a_ready(nxt);
;             if constexpr (SP2) {
;             PG8_LDB(B0, 0, 0); PG8_LDB(B1, 0, 1); PG8_SCHED; PG8_LDA(At, 0, 0); PG8_STAGE(PG8_SA(1, 1), a1 + hstep, voffA);
;             PG8_WAIT_V(8); PG8_WAIT_L(0); PG8_BAR; PG8_MMA(0, 0, At, B0); PG8_MMA(0, 1, At, B1); PG8_BAR; PG8_SCHED;
;             PG8_LDA(At, 0, 1); PG8_STAGE(PG8_SB(0, 0), b2, voffB); PG8_STAGE(PG8_SB(0, 1), b2 + hstep, voffB); PG8_STAGE(PG8_SA(0, 0), a2, voffA);
;             PG8_WAIT_V(8); PG8_WAIT_L(0); PG8_BAR; PG8_MMA(1, 0, At, B0); PG8_MMA(1, 1, At, B1); PG8_BAR; PG8_SCHED;
.LBB0_589:
	s_ashr_i32 s43, s42, 31
	s_lshl_b64 s[44:45], s[42:43], 19
	s_add_u32 s44, s60, s44
	s_addc_u32 s45, s61, s45
	s_and_b64 s[46:47], s[0:1], exec
	s_cselect_b32 s43, s45, s55
	s_cselect_b32 s86, s44, s54
	s_ashr_i32 s41, s40, 31
	s_lshl_b64 s[46:47], s[40:41], 19
	s_add_u32 s46, s62, s46
	s_addc_u32 s47, s63, s47
	s_and_b64 s[58:59], s[0:1], exec
	s_cselect_b32 s41, s47, s57
	s_cselect_b32 s87, s46, s56
	s_add_u32 s54, s54, 0x40080
	s_addc_u32 s55, s55, 0
	s_add_u32 s90, s56, 0x100
	s_addc_u32 s91, s57, 0
	s_mov_b32 s92, -2
	s_waitcnt lgkmcnt(0)
	s_add_u32 s33, s54, 0xfffc0080
	s_addc_u32 s34, s55, -1
	s_cmp_eq_u32 s92, 12
	s_cselect_b32 s59, s43, s34
	s_cselect_b32 s58, s86, s33
	s_cselect_b32 s57, s41, s91
	s_cselect_b32 s56, s87, s90
	s_add_i32 m0, s53, 0xc000
	global_load_lds_dwordx4 v144, s[54:55]
	s_add_i32 m0, s53, 0xe000
	s_nop 0
	global_load_lds_dwordx4 v146, s[54:55]
	s_waitcnt vmcnt(8)
	s_waitcnt lgkmcnt(0)
	s_barrier
	s_setprio 1
	s_waitcnt lgkmcnt(0)
	v_mfma_f32_16x16x32_bf16 v[124:127], v[128:131], v[184:187], 0
	v_mfma_f32_16x16x32_bf16 v[120:123], v[154:157], v[184:187], 0
	v_mfma_f32_16x16x32_bf16 v[116:119], v[128:131], v[192:195], 0
	v_mfma_f32_16x16x32_bf16 v[112:115], v[154:157], v[192:195], 0
	v_mfma_f32_16x16x32_bf16 v[108:111], v[128:131], v[200:203], 0
	v_mfma_f32_16x16x32_bf16 v[104:107], v[154:157], v[200:203], 0
	v_mfma_f32_16x16x32_bf16 v[100:103], v[128:131], v[208:211], 0
	v_mfma_f32_16x16x32_bf16 v[96:99], v[154:157], v[208:211], 0
	v_mfma_f32_16x16x32_bf16 v[124:127], v[132:135], v[188:191], v[124:127]
	v_mfma_f32_16x16x32_bf16 v[120:123], v[158:161], v[188:191], v[120:123]
	v_mfma_f32_16x16x32_bf16 v[116:119], v[132:135], v[196:199], v[116:119]
	v_mfma_f32_16x16x32_bf16 v[112:115], v[158:161], v[196:199], v[112:115]
	v_mfma_f32_16x16x32_bf16 v[108:111], v[132:135], v[204:207], v[108:111]
	v_mfma_f32_16x16x32_bf16 v[104:107], v[158:161], v[204:207], v[104:107]
	v_mfma_f32_16x16x32_bf16 v[100:103], v[132:135], v[212:215], v[100:103]
	v_mfma_f32_16x16x32_bf16 v[96:99], v[158:161], v[212:215], v[96:99]
	s_setprio 0
	s_setprio 1
	v_mfma_f32_16x16x32_bf16 v[68:71], v[168:171], v[184:187], 0
	v_mfma_f32_16x16x32_bf16 v[60:63], v[176:179], v[184:187], 0
	v_mfma_f32_16x16x32_bf16 v[52:55], v[168:171], v[192:195], 0
	v_mfma_f32_16x16x32_bf16 v[48:51], v[176:179], v[192:195], 0
	v_mfma_f32_16x16x32_bf16 v[44:47], v[168:171], v[200:203], 0
	v_mfma_f32_16x16x32_bf16 v[40:43], v[176:179], v[200:203], 0
	v_mfma_f32_16x16x32_bf16 v[36:39], v[168:171], v[208:211], 0
	v_mfma_f32_16x16x32_bf16 v[32:35], v[176:179], v[208:211], 0
	v_mfma_f32_16x16x32_bf16 v[68:71], v[172:175], v[188:191], v[68:71]
	v_mfma_f32_16x16x32_bf16 v[60:63], v[180:183], v[188:191], v[60:63]
	v_mfma_f32_16x16x32_bf16 v[52:55], v[172:175], v[196:199], v[52:55]
	v_mfma_f32_16x16x32_bf16 v[48:51], v[180:183], v[196:199], v[48:51]
	v_mfma_f32_16x16x32_bf16 v[44:47], v[172:175], v[204:207], v[44:47]
	v_mfma_f32_16x16x32_bf16 v[40:43], v[180:183], v[204:207], v[40:43]
	v_mfma_f32_16x16x32_bf16 v[36:39], v[172:175], v[212:215], v[36:39]
	v_mfma_f32_16x16x32_bf16 v[32:35], v[180:183], v[212:215], v[32:35]
	s_setprio 0
	s_barrier
	s_add_i32 s33, s81, s70
	s_add_u32 s64, s56, s10
	s_addc_u32 s65, s57, s11
	s_mov_b32 m0, s33
	ds_read_b128 v[184:187], v167 offset:16384
	ds_read_b128 v[188:191], v167 offset:17408
	ds_read_b128 v[192:195], v167 offset:18432
	ds_read_b128 v[196:199], v167 offset:19456
	ds_read_b128 v[200:203], v167 offset:20480
	ds_read_b128 v[204:207], v167 offset:21504
	ds_read_b128 v[208:211], v167 offset:22528
	ds_read_b128 v[212:215], v167 offset:23552
	global_load_lds_dwordx4 v138, s[56:57]
	s_add_i32 m0, s33, 0x2000
	s_add_u32 s94, s56, 0x40000
	s_addc_u32 s95, s57, 0
	s_add_i32 s33, s82, s70
	global_load_lds_dwordx4 v142, s[56:57]
	s_mov_b32 m0, s33
	s_add_u32 s84, s58, s10
	s_addc_u32 s85, s59, s11
	global_load_lds_dwordx4 v138, s[94:95]
	s_add_i32 m0, s33, 0x2000
	s_nop 0
	global_load_lds_dwordx4 v142, s[94:95]
	s_mov_b32 m0, s53
	s_nop 0
	global_load_lds_dwordx4 v136, s[58:59]
	s_mov_b32 m0, s72
	s_nop 0
	global_load_lds_dwordx4 v140, s[58:59]
	s_waitcnt vmcnt(8)
	s_waitcnt lgkmcnt(0)
	s_barrier
	s_setprio 1
	s_waitcnt lgkmcnt(0)
	v_mfma_f32_16x16x32_bf16 v[92:95], v[128:131], v[184:187], 0
	v_mfma_f32_16x16x32_bf16 v[88:91], v[154:157], v[184:187], 0
	v_mfma_f32_16x16x32_bf16 v[84:87], v[128:131], v[192:195], 0
	v_mfma_f32_16x16x32_bf16 v[80:83], v[154:157], v[192:195], 0
	v_mfma_f32_16x16x32_bf16 v[76:79], v[128:131], v[200:203], 0
	v_mfma_f32_16x16x32_bf16 v[72:75], v[154:157], v[200:203], 0
	v_mfma_f32_16x16x32_bf16 v[64:67], v[128:131], v[208:211], 0
	v_mfma_f32_16x16x32_bf16 v[56:59], v[154:157], v[208:211], 0
	v_mfma_f32_16x16x32_bf16 v[92:95], v[132:135], v[188:191], v[92:95]
	v_mfma_f32_16x16x32_bf16 v[88:91], v[158:161], v[188:191], v[88:91]
	v_mfma_f32_16x16x32_bf16 v[84:87], v[132:135], v[196:199], v[84:87]
	v_mfma_f32_16x16x32_bf16 v[80:83], v[158:161], v[196:199], v[80:83]
	v_mfma_f32_16x16x32_bf16 v[76:79], v[132:135], v[204:207], v[76:79]
	v_mfma_f32_16x16x32_bf16 v[72:75], v[158:161], v[204:207], v[72:75]
	v_mfma_f32_16x16x32_bf16 v[64:67], v[132:135], v[212:215], v[64:67]
	v_mfma_f32_16x16x32_bf16 v[56:59], v[158:161], v[212:215], v[56:59]
	s_setprio 0
	s_setprio 1
	v_mfma_f32_16x16x32_bf16 v[28:31], v[168:171], v[184:187], 0
	v_mfma_f32_16x16x32_bf16 v[24:27], v[176:179], v[184:187], 0
	v_mfma_f32_16x16x32_bf16 v[20:23], v[168:171], v[192:195], 0
	v_mfma_f32_16x16x32_bf16 v[16:19], v[176:179], v[192:195], 0
	v_mfma_f32_16x16x32_bf16 v[12:15], v[168:171], v[200:203], 0
	v_mfma_f32_16x16x32_bf16 v[8:11], v[176:179], v[200:203], 0
	v_mfma_f32_16x16x32_bf16 v[4:7], v[168:171], v[208:211], 0
	v_mfma_f32_16x16x32_bf16 v[0:3], v[176:179], v[208:211], 0
	v_mfma_f32_16x16x32_bf16 v[28:31], v[172:175], v[188:191], v[28:31]
	v_mfma_f32_16x16x32_bf16 v[24:27], v[180:183], v[188:191], v[24:27]
	v_mfma_f32_16x16x32_bf16 v[20:23], v[172:175], v[196:199], v[20:23]
	v_mfma_f32_16x16x32_bf16 v[16:19], v[180:183], v[196:199], v[16:19]
	v_mfma_f32_16x16x32_bf16 v[12:15], v[172:175], v[204:207], v[12:15]
	v_mfma_f32_16x16x32_bf16 v[8:11], v[180:183], v[204:207], v[8:11]
	v_mfma_f32_16x16x32_bf16 v[4:7], v[172:175], v[212:215], v[4:7]
	v_mfma_f32_16x16x32_bf16 v[0:3], v[180:183], v[212:215], v[0:3]
	s_setprio 0
	s_barrier
; #define PG8_STAGE(bufoff, gbase, voff) do { _Pragma("unroll") for (int _i = 0; _i < 2; ++_i) \
;         __builtin_amdgcn_global_load_lds((const unsigned*)((const char*)(gbase) + (voff)[_i]), (PG8_LAS unsigned*)(lds + (bufoff) + ldsw + _i * 8192), 16, 0, 0); } while (0)
; #define PG8_LDA(dst, b, h) do { _Pragma("unroll") for (int m = 0; m < 4; ++m) _Pragma("unroll") for (int k = 0; k < 2; ++k) dst[m][k] = *(const PG8_LAS bf16x8*)(lds + PG8_SA(b, h) + aoff + m * 2048 + k * 1024); } while (0)
; #define PG8_LDB(dst, b, h) do { _Pragma("unroll") for (int n = 0; n < 2; ++n) _Pragma("unroll") for (int k = 0; k < 2; ++k) dst[n][k] = *(const PG8_LAS bf16x8*)(lds + PG8_SB(b, h) + boff + n * 2048 + k * 1024); } while (0)
; #define PG8_MMA(ai, bj, At, Bt) do { __builtin_amdgcn_s_setprio(1); _Pragma("unroll") for (int m = 0; m < 4; ++m) _Pragma("unroll") for (int n = 0; n < 2; ++n) _Pragma("unroll") for (int k = 0; k < 2; ++k) \
;         acc[ai][bj][m][n] = __builtin_amdgcn_mfma_f32_16x16x32_bf16(Bt[n][k], At[m][k], acc[ai][bj][m][n], 0, 0, 0); __builtin_amdgcn_s_setprio(0); } while (0)
; #define PG8_WAIT_V(n) asm volatile("s_waitcnt vmcnt(" #n ")" ::: "memory")
; #define PG8_WAIT_L(n) asm volatile("s_waitcnt lgkmcnt(" #n ")" ::: "memory")
; #define PG8_BAR __builtin_amdgcn_s_barrier()
; #define PG8_SCHED __builtin_amdgcn_sched_barrier(0)
; template <class Epi, class Sched, bool ALIGN_EPI = false, bool SP2 = false>
; __device__ __forceinline__ void gemm_phase(PG8_LAS unsigned char* lds, const Gemm g, const Sched& S, const Epi& E) {
;     ...
;             PG8_LDB(B0, 1, 0); PG8_LDB(B1, 1, 1); PG8_SCHED; PG8_LDA(At, 1, 0); PG8_STAGE(PG8_SA(0, 1), a2 + hstep, voffA);
;             PG8_WAIT_V(8); PG8_WAIT_L(0); PG8_BAR; PG8_MMA(0, 0, At, B0); PG8_MMA(0, 1, At, B1); PG8_BAR; PG8_SCHED;
;             PG8_LDA(At, 1, 1); PG8_STAGE(PG8_SB(1, 0), b3, voffB); PG8_STAGE(PG8_SB(1, 1), b3 + hstep, voffB); PG8_STAGE(PG8_SA(1, 0), a3, voffA);
;             PG8_WAIT_V(8); PG8_WAIT_L(0); PG8_BAR; PG8_MMA(1, 0, At, B0); PG8_MMA(1, 1, At, B1); PG8_BAR; PG8_SCHED;
	s_add_i32 s33, 0, 0x18000
	v_add_u32_e32 v153, s33, v163
	s_add_i32 s34, 0, 0x1c000
	ds_read_b128 v[128:131], v153
	ds_read_b128 v[132:135], v153 offset:1024
	ds_read_b128 v[154:157], v153 offset:2048
	ds_read_b128 v[158:161], v153 offset:3072
	v_add_u32_e32 v153, s34, v163
	ds_read_b128 v[168:171], v153
	ds_read_b128 v[172:175], v153 offset:1024
	ds_read_b128 v[176:179], v153 offset:2048
	ds_read_b128 v[180:183], v153 offset:3072
	s_add_u32 s58, s58, 0x40000
	s_addc_u32 s59, s59, 0
	s_mov_b32 m0, s73
	ds_read_b128 v[184:187], v167 offset:32768
	ds_read_b128 v[188:191], v167 offset:33792
	ds_read_b128 v[192:195], v167 offset:34816
	ds_read_b128 v[196:199], v167 offset:35840
	ds_read_b128 v[200:203], v167 offset:36864
	ds_read_b128 v[204:207], v167 offset:37888
	ds_read_b128 v[208:211], v167 offset:38912
	ds_read_b128 v[212:215], v167 offset:39936
	global_load_lds_dwordx4 v136, s[58:59]
	s_mov_b32 m0, s74
	s_nop 0
	global_load_lds_dwordx4 v140, s[58:59]
	s_waitcnt vmcnt(8)
	s_waitcnt lgkmcnt(0)
	s_barrier
	s_setprio 1
	s_waitcnt lgkmcnt(0)
	v_mfma_f32_16x16x32_bf16 v[124:127], v[128:131], v[184:187], v[124:127]
	v_mfma_f32_16x16x32_bf16 v[120:123], v[154:157], v[184:187], v[120:123]
	v_mfma_f32_16x16x32_bf16 v[116:119], v[128:131], v[192:195], v[116:119]
	v_mfma_f32_16x16x32_bf16 v[112:115], v[154:157], v[192:195], v[112:115]
	v_mfma_f32_16x16x32_bf16 v[108:111], v[128:131], v[200:203], v[108:111]
	v_mfma_f32_16x16x32_bf16 v[104:107], v[154:157], v[200:203], v[104:107]
	v_mfma_f32_16x16x32_bf16 v[100:103], v[128:131], v[208:211], v[100:103]
	v_mfma_f32_16x16x32_bf16 v[96:99], v[154:157], v[208:211], v[96:99]
	v_mfma_f32_16x16x32_bf16 v[124:127], v[132:135], v[188:191], v[124:127]
	v_mfma_f32_16x16x32_bf16 v[120:123], v[158:161], v[188:191], v[120:123]
	v_mfma_f32_16x16x32_bf16 v[116:119], v[132:135], v[196:199], v[116:119]
	v_mfma_f32_16x16x32_bf16 v[112:115], v[158:161], v[196:199], v[112:115]
	v_mfma_f32_16x16x32_bf16 v[108:111], v[132:135], v[204:207], v[108:111]
	v_mfma_f32_16x16x32_bf16 v[104:107], v[158:161], v[204:207], v[104:107]
	v_mfma_f32_16x16x32_bf16 v[100:103], v[132:135], v[212:215], v[100:103]
	v_mfma_f32_16x16x32_bf16 v[96:99], v[158:161], v[212:215], v[96:99]
	s_setprio 0
	s_setprio 1
	v_mfma_f32_16x16x32_bf16 v[68:71], v[168:171], v[184:187], v[68:71]
	v_mfma_f32_16x16x32_bf16 v[60:63], v[176:179], v[184:187], v[60:63]
	v_mfma_f32_16x16x32_bf16 v[52:55], v[168:171], v[192:195], v[52:55]
	v_mfma_f32_16x16x32_bf16 v[48:51], v[176:179], v[192:195], v[48:51]
	v_mfma_f32_16x16x32_bf16 v[44:47], v[168:171], v[200:203], v[44:47]
	v_mfma_f32_16x16x32_bf16 v[40:43], v[176:179], v[200:203], v[40:43]
	v_mfma_f32_16x16x32_bf16 v[36:39], v[168:171], v[208:211], v[36:39]
	v_mfma_f32_16x16x32_bf16 v[32:35], v[176:179], v[208:211], v[32:35]
	v_mfma_f32_16x16x32_bf16 v[68:71], v[172:175], v[188:191], v[68:71]
	v_mfma_f32_16x16x32_bf16 v[60:63], v[180:183], v[188:191], v[60:63]
	v_mfma_f32_16x16x32_bf16 v[52:55], v[172:175], v[196:199], v[52:55]
	v_mfma_f32_16x16x32_bf16 v[48:51], v[180:183], v[196:199], v[48:51]
	v_mfma_f32_16x16x32_bf16 v[44:47], v[172:175], v[204:207], v[44:47]
	v_mfma_f32_16x16x32_bf16 v[40:43], v[180:183], v[204:207], v[40:43]
	v_mfma_f32_16x16x32_bf16 v[36:39], v[172:175], v[212:215], v[36:39]
	v_mfma_f32_16x16x32_bf16 v[32:35], v[180:183], v[212:215], v[32:35]
	s_setprio 0
	s_barrier
	s_add_i32 s33, s33, s70
	s_mov_b32 m0, s33
	ds_read_b128 v[184:187], v167 offset:49152
	ds_read_b128 v[188:191], v167 offset:50176
	ds_read_b128 v[192:195], v167 offset:51200
	ds_read_b128 v[196:199], v167 offset:52224
	ds_read_b128 v[200:203], v167 offset:53248
	ds_read_b128 v[204:207], v167 offset:54272
	ds_read_b128 v[208:211], v167 offset:55296
	ds_read_b128 v[212:215], v167 offset:56320
	global_load_lds_dwordx4 v138, s[64:65]
	s_add_i32 m0, s33, 0x2000
	s_add_u32 s56, s56, 0x40080
	s_addc_u32 s57, s57, 0
	s_add_i32 s33, s34, s70
	global_load_lds_dwordx4 v142, s[64:65]
	s_mov_b32 m0, s33
	s_nop 0
	global_load_lds_dwordx4 v138, s[56:57]
	s_add_i32 m0, s33, 0x2000
	s_nop 0
	global_load_lds_dwordx4 v142, s[56:57]
	s_mov_b32 m0, s79
	s_nop 0
	global_load_lds_dwordx4 v136, s[84:85]
	s_mov_b32 m0, s80
	s_nop 0
	global_load_lds_dwordx4 v140, s[84:85]
	s_waitcnt vmcnt(8)
	s_waitcnt lgkmcnt(0)
	s_barrier
	s_setprio 1
	s_waitcnt lgkmcnt(0)
	v_mfma_f32_16x16x32_bf16 v[92:95], v[128:131], v[184:187], v[92:95]
	v_mfma_f32_16x16x32_bf16 v[88:91], v[154:157], v[184:187], v[88:91]
	v_mfma_f32_16x16x32_bf16 v[84:87], v[128:131], v[192:195], v[84:87]
	v_mfma_f32_16x16x32_bf16 v[80:83], v[154:157], v[192:195], v[80:83]
	v_mfma_f32_16x16x32_bf16 v[76:79], v[128:131], v[200:203], v[76:79]
	v_mfma_f32_16x16x32_bf16 v[72:75], v[154:157], v[200:203], v[72:75]
	v_mfma_f32_16x16x32_bf16 v[64:67], v[128:131], v[208:211], v[64:67]
	v_mfma_f32_16x16x32_bf16 v[56:59], v[154:157], v[208:211], v[56:59]
	v_mfma_f32_16x16x32_bf16 v[92:95], v[132:135], v[188:191], v[92:95]
	v_mfma_f32_16x16x32_bf16 v[88:91], v[158:161], v[188:191], v[88:91]
	v_mfma_f32_16x16x32_bf16 v[84:87], v[132:135], v[196:199], v[84:87]
	v_mfma_f32_16x16x32_bf16 v[80:83], v[158:161], v[196:199], v[80:83]
	v_mfma_f32_16x16x32_bf16 v[76:79], v[132:135], v[204:207], v[76:79]
	v_mfma_f32_16x16x32_bf16 v[72:75], v[158:161], v[204:207], v[72:75]
	v_mfma_f32_16x16x32_bf16 v[64:67], v[132:135], v[212:215], v[64:67]
	v_mfma_f32_16x16x32_bf16 v[56:59], v[158:161], v[212:215], v[56:59]
	s_setprio 0
	s_setprio 1
	v_mfma_f32_16x16x32_bf16 v[28:31], v[168:171], v[184:187], v[28:31]
	v_mfma_f32_16x16x32_bf16 v[24:27], v[176:179], v[184:187], v[24:27]
	v_mfma_f32_16x16x32_bf16 v[20:23], v[168:171], v[192:195], v[20:23]
	v_mfma_f32_16x16x32_bf16 v[16:19], v[176:179], v[192:195], v[16:19]
	v_mfma_f32_16x16x32_bf16 v[12:15], v[168:171], v[200:203], v[12:15]
	v_mfma_f32_16x16x32_bf16 v[8:11], v[176:179], v[200:203], v[8:11]
	v_mfma_f32_16x16x32_bf16 v[4:7], v[168:171], v[208:211], v[4:7]
	v_mfma_f32_16x16x32_bf16 v[0:3], v[176:179], v[208:211], v[0:3]
	v_mfma_f32_16x16x32_bf16 v[28:31], v[172:175], v[188:191], v[28:31]
	v_mfma_f32_16x16x32_bf16 v[24:27], v[180:183], v[188:191], v[24:27]
	v_mfma_f32_16x16x32_bf16 v[20:23], v[172:175], v[196:199], v[20:23]
	v_mfma_f32_16x16x32_bf16 v[16:19], v[180:183], v[196:199], v[16:19]
	v_mfma_f32_16x16x32_bf16 v[12:15], v[172:175], v[204:207], v[12:15]
	v_mfma_f32_16x16x32_bf16 v[8:11], v[180:183], v[204:207], v[8:11]
	v_mfma_f32_16x16x32_bf16 v[4:7], v[172:175], v[212:215], v[4:7]
	v_mfma_f32_16x16x32_bf16 v[0:3], v[180:183], v[212:215], v[0:3]
	s_setprio 0
	s_barrier
	s_add_i32 s92, s92, 2
	s_add_u32 s54, s54, 0x100
	s_addc_u32 s55, s55, 0
	s_add_u32 s90, s90, 0x100
	s_addc_u32 s91, s91, 0
	s_cmp_gt_u32 s92, 13

; #define PG8_STAGE(bufoff, gbase, voff) do { _Pragma("unroll") for (int _i = 0; _i < 2; ++_i) \
;         __builtin_amdgcn_global_load_lds((const unsigned*)((const char*)(gbase) + (voff)[_i]), (PG8_LAS unsigned*)(lds + (bufoff) + ldsw + _i * 8192), 16, 0, 0); } while (0)
; #define PG8_WAIT_V(n) asm volatile("s_waitcnt vmcnt(" #n ")" ::: "memory")
; #define PG8_BAR __builtin_amdgcn_s_barrier()
; template <class Epi, class Sched, bool ALIGN_EPI = false, bool SP2 = false>
; __device__ __forceinline__ void gemm_phase(PG8_LAS unsigned char* lds, const Gemm g, const Sched& S, const Epi& E) {
;     ...
;     for (int i = 0; i < 2; ++i) { int R, C; stage_rc(tid * 16 + i * 8192, R, C); const int Rb = Epi::PERM ? ((R & ~31) + perm32(R & 31)) : R;
;         voffA[i] = (unsigned)(R * K + C) * 2u; voffB[i] = (unsigned)(Rb * K + C) * 2u; }
;     const size_t kstep = (size_t)(BK * 2);
;     const size_t hstep = (size_t)HALF * K * 2;
;     const size_t tstep = 2 * hstep;
;     const unsigned ldsw = (unsigned)wid * 1024u;
;     const int aoff = lds_byte(wr * 64 + fr, fq * 8), boff = lds_byte(wc * 32 + fr, fq * 8);
;     ...
;     if constexpr (SP2) {
;         PG8_STAGE(PG8_SB(0, 0), cB, voffB); PG8_STAGE(PG8_SB(0, 1), cB + hstep, voffB); PG8_STAGE(PG8_SA(0, 0), cA, voffA); PG8_STAGE(PG8_SA(0, 1), cA + hstep, voffA);
;         if (wr == 1) PG8_BAR;
;         PG8_WAIT_V(2); PG8_BAR;
;         PG8_STAGE(PG8_SB(1, 0), cB + kstep, voffB); PG8_STAGE(PG8_SA(1, 0), cA + kstep, voffA); PG8_STAGE(PG8_SB(1, 1), cB + hstep + kstep, voffB);
;         PG8_WAIT_V(6); PG8_BAR;
.LBB0_708:
	s_add_u32 s8, s28, 0xfa00000
	s_addc_u32 s9, s29, 0
	s_lshl_b32 s10, s10, 5
	s_and_b32 s22, s10, 0x60
	s_mov_b64 s[10:11], 0x80
	s_add_i32 m0, s39, 0x18000
	v_lshl_add_u64 v[6:7], v[6:7], 0, s[10:11]
	s_ashr_i32 s59, s3, 31
	s_lshl_b32 s13, s12, 13
	s_lshl_b32 s23, s22, 7
	s_waitcnt vmcnt(2)
	s_barrier
	global_load_lds_dwordx4 v[6:7], off
	v_lshl_add_u64 v[4:5], v[4:5], 0, s[10:11]
	s_add_i32 m0, s39, 0x1a000
	s_add_i32 s60, s39, 0x8000
	s_add_i32 s61, s39, 0xa000
	global_load_lds_dwordx4 v[4:5], off
	v_lshl_add_u64 v[0:1], v[0:1], 0, s[10:11]
	s_mov_b32 m0, s60
	s_add_u32 s20, s42, 0x40080
	global_load_lds_dwordx4 v[0:1], off
	v_lshl_add_u64 v[0:1], v[2:3], 0, s[10:11]
	s_mov_b32 m0, s61
	s_addc_u32 s21, s43, 0
	global_load_lds_dwordx4 v[0:1], off
	s_add_i32 m0, s39, 0x1c000
	v_lshl_add_u64 v[0:1], s[20:21], 0, v[130:131]
	global_load_lds_dwordx4 v[0:1], off
	v_lshl_add_u64 v[0:1], s[20:21], 0, v[134:135]
	s_add_i32 m0, s39, 0x1e000
	s_sext_i32_i16 s71, s0
	global_load_lds_dwordx4 v[0:1], off
	v_and_b32_e32 v0, 15, v152
	v_lshlrev_b32_e32 v1, 1, v11
	v_lshlrev_b32_e32 v2, 6, v152
	s_movk_i32 s0, 0x3c0
	v_lshlrev_b32_e32 v3, 2, v152
	v_and_or_b32 v2, v2, s0, v1
	v_and_b32_e32 v3, 32, v3
	v_lshl_or_b32 v144, s12, 6, v0
	v_lshl_or_b32 v0, v0, 6, v1
	v_lshlrev_b32_e32 v1, 8, v152
	v_bitop3_b32 v145, s23, v2, v3 bitop3:0xf6
	v_and_b32_e32 v1, 0x38000, v1
	v_lshlrev_b32_e32 v2, 11, v10
	v_or3_b32 v1, v8, v1, v2
	s_waitcnt vmcnt(0)
	v_add_u32_e32 v136, v1, v9
	v_lshlrev_b32_e32 v1, 4, v12
	s_waitcnt vmcnt(6)
	s_cmpk_lt_u32 s1, 0x100
	v_and_b32_e32 v1, 0x78000, v1
	v_bitop3_b32 v0, v0, s13, v3 bitop3:0xde
	s_cselect_b64 s[12:13], -1, 0
	v_or3_b32 v1, v8, v1, v2
	s_add_i32 s62, 0, 0x10000
	s_add_i32 s63, 0, 0x14000
	v_or_b32_e32 v146, s22, v11
	v_mov_b32_e32 v137, v131
	v_add_u32_e32 v138, v1, v9
	v_mov_b32_e32 v139, v131
	v_mov_b64_e32 v[140:141], 0x1600
	v_mov_b64_e32 v[142:143], 0x15ff
	v_add_u32_e32 v147, s62, v145
	v_add_u32_e32 v148, s63, v145
	v_add_u32_e32 v149, 0, v0
	s_movk_i32 s70, 0x1600
	s_barrier
	s_mov_b32 s77, 0
	s_branch .LBB0_711

; #define PG8_STAGE(bufoff, gbase, voff) do { _Pragma("unroll") for (int _i = 0; _i < 2; ++_i) \
;         __builtin_amdgcn_global_load_lds((const unsigned*)((const char*)(gbase) + (voff)[_i]), (PG8_LAS unsigned*)(lds + (bufoff) + ldsw + _i * 8192), 16, 0, 0); } while (0)
; #define PG8_LDA(dst, b, h) do { _Pragma("unroll") for (int m = 0; m < 4; ++m) _Pragma("unroll") for (int k = 0; k < 2; ++k) dst[m][k] = *(const PG8_LAS bf16x8*)(lds + PG8_SA(b, h) + aoff + m * 2048 + k * 1024); } while (0)
; #define PG8_LDB(dst, b, h) do { _Pragma("unroll") for (int n = 0; n < 2; ++n) _Pragma("unroll") for (int k = 0; k < 2; ++k) dst[n][k] = *(const PG8_LAS bf16x8*)(lds + PG8_SB(b, h) + boff + n * 2048 + k * 1024); } while (0)
; #define PG8_SCHED __builtin_amdgcn_sched_barrier(0)
;     __host__ __device__ bool next(int i, Unit& u) const {
;         const long L = (long)i * G + c; if (L >= nwg) return false;
;         int wgid = (int)L; { const int q = nwg / NXCD, r = nwg % NXCD, xcd = wgid % NXCD, off = wgid / NXCD; wgid = (xcd < r ? xcd * (q + 1) : r * (q + 1) + (xcd - r) * q) + off; }
;         const int nig = WGM * nN, gid = wgid / nig, fm = gid * WGM, gsz = (nM - fm) < WGM ? (nM - fm) : WGM;
;         u.pm = fm + ((wgid % nig) % gsz); u.pn = (wgid % nig) / gsz; return true;
;     }
; template <class Epi, class Sched, bool ALIGN_EPI = false, bool SP2 = false>
; __device__ __forceinline__ void gemm_phase(PG8_LAS unsigned char* lds, const Gemm g, const Sched& S, const Epi& E) {
;     ...
;         const bool has_next = S.next(ui + 1, nxt);
;         const char* nA = has_next ? (const char*)g.A + (size_t)nxt.pm * tstep : cA; const char* nB = has_next ? (const char*)g.Bt + (size_t)nxt.pn * tstep : cB;
;         for (int t = 0; t < nt; t += 2) {
;             const bool last = (t == nt - 2);
;             const char* a1 = cA + (size_t)(t + 1) * kstep;
;             const char* a2 = last ? nA : cA + (size_t)(t + 2) * kstep; const char* b2 = last ? nB : cB + (size_t)(t + 2) * kstep;
;             const char* a3 = a2 + kstep; const char* b3 = b2 + kstep;
;             if (last && has_next) S.a_ready(nxt);
;             if constexpr (SP2) {
;             PG8_LDB(B0, 0, 0); PG8_LDB(B1, 0, 1); PG8_SCHED; PG8_LDA(At, 0, 0); PG8_STAGE(PG8_SA(1, 1), a1 + hstep, voffA);
.LBB0_711:
	ds_read_b128 v[154:157], v147
	ds_read_b128 v[158:161], v147 offset:1024
	ds_read_b128 v[162:165], v147 offset:2048
	ds_read_b128 v[166:169], v147 offset:3072
	ds_read_b128 v[170:173], v148
	ds_read_b128 v[174:177], v148 offset:1024
	ds_read_b128 v[178:181], v148 offset:2048
	ds_read_b128 v[182:185], v148 offset:3072
	ds_read_b128 v[186:189], v149
	ds_read_b128 v[190:193], v149 offset:1024
	ds_read_b128 v[194:197], v149 offset:2048
	ds_read_b128 v[198:201], v149 offset:3072
	ds_read_b128 v[202:205], v149 offset:4096
	ds_read_b128 v[206:209], v149 offset:5120
	ds_read_b128 v[210:213], v149 offset:6144
	ds_read_b128 v[214:217], v149 offset:7168
	s_add_i32 s58, s58, 1
	s_mul_i32 s0, s58, s59
	s_mul_hi_u32 s1, s58, s3
	s_add_i32 s1, s1, s0
	s_mul_i32 s0, s58, s3
	s_add_u32 s24, s0, s2
	s_addc_u32 s25, s1, s53
	v_cmp_gt_i64_e32 vcc, s[24:25], v[142:143]
	v_cmp_lt_i64_e64 s[0:1], s[24:25], v[140:141]
	s_cbranch_vccnz .LBB0_713
	s_ashr_i32 s20, s24, 31
	s_lshr_b32 s20, s20, 29
	s_add_i32 s20, s24, s20
	s_ashr_i32 s21, s20, 3
	s_and_b32 s20, s20, -8
	s_sub_i32 s20, s24, s20
	s_cmp_lt_i32 s20, 0
	s_cselect_b32 s22, s54, 0x2c0
	s_mul_i32 s20, s20, s22
	s_add_i32 s20, s20, s21
	s_mul_hi_i32 s21, s20, 0x2e8ba2e9
	s_lshr_b32 s22, s21, 31
	s_ashr_i32 s21, s21, 5
	s_add_i32 s21, s21, s22
	s_lshl_b32 s22, s21, 3
	s_sub_i32 s23, 0x100, s22
	s_min_i32 s23, s23, 8
	s_abs_i32 s24, s23
	v_cvt_f32_u32_e32 v0, s24
	s_sub_i32 s33, 0, s24
	s_mulk_i32 s21, 0xb0
	s_sub_i32 s21, s20, s21
	v_rcp_iflag_f32_e32 v0, v0
	s_abs_i32 s20, s21
	s_xor_b32 s25, s21, s23
	s_ashr_i32 s25, s25, 31
	v_mul_f32_e32 v0, 0x4f7ffffe, v0
	v_cvt_u32_f32_e32 v0, v0
	s_nop 0
	v_readfirstlane_b32 s34, v0
	s_mul_i32 s33, s33, s34
	s_mul_hi_u32 s33, s34, s33
	s_add_i32 s34, s34, s33
	s_mul_hi_u32 s33, s20, s34
	s_mul_i32 s34, s33, s24
	s_sub_i32 s20, s20, s34
	s_add_i32 s35, s33, 1
	s_sub_i32 s34, s20, s24
	s_cmp_ge_u32 s20, s24
	s_cselect_b32 s33, s35, s33
	s_cselect_b32 s20, s34, s20
	s_add_i32 s34, s33, 1
	s_cmp_ge_u32 s20, s24
	s_cselect_b32 s20, s34, s33
	s_xor_b32 s20, s20, s25
	s_sub_i32 s20, s20, s25
	s_mul_i32 s23, s20, s23
	s_sub_i32 s21, s21, s23
	s_add_i32 s22, s22, s21
.LBB0_713:
	s_ashr_i32 s23, s22, 31
	s_lshl_b64 s[24:25], s[22:23], 19
	s_add_u32 s24, s16, s24
	s_addc_u32 s25, s17, s25
	s_and_b64 s[36:37], s[0:1], exec
	s_cselect_b32 s23, s25, s41
	s_cselect_b32 s72, s24, s40
	s_ashr_i32 s21, s20, 31
	s_lshl_b64 s[36:37], s[20:21], 19
	s_add_u32 s36, s46, s36
	s_addc_u32 s37, s47, s37
	s_and_b64 s[44:45], s[0:1], exec
	s_cselect_b32 s21, s37, s43
	s_cselect_b32 s73, s36, s42
	s_add_u32 s40, s40, 0x40080
	s_addc_u32 s41, s41, 0
	s_add_u32 s74, s42, 0x100
	s_addc_u32 s75, s43, 0
	s_mov_b32 s76, -2
	s_waitcnt lgkmcnt(0)
	s_add_u32 s33, s40, 0xfffc0080
	s_addc_u32 s34, s41, -1
	s_cmp_eq_u32 s76, 12
	s_cselect_b32 s45, s23, s34
	s_cselect_b32 s44, s72, s33
	s_cselect_b32 s43, s21, s75
	s_cselect_b32 s42, s73, s74
	s_add_i32 m0, s39, 0xc000
	global_load_lds_dwordx4 v136, s[40:41]
	s_add_i32 m0, s39, 0xe000
	s_nop 0
	global_load_lds_dwordx4 v138, s[40:41]
	s_cmp_eq_u32 s77, 0
	s_cbranch_scc1 .LfwP7_0_s
	s_waitcnt vmcnt(16)
	s_branch .LfwP7_0_e

; #define PG8_STAGE(bufoff, gbase, voff) do { _Pragma("unroll") for (int _i = 0; _i < 2; ++_i) \
;         __builtin_amdgcn_global_load_lds((const unsigned*)((const char*)(gbase) + (voff)[_i]), (PG8_LAS unsigned*)(lds + (bufoff) + ldsw + _i * 8192), 16, 0, 0); } while (0)
; #define PG8_LDA(dst, b, h) do { _Pragma("unroll") for (int m = 0; m < 4; ++m) _Pragma("unroll") for (int k = 0; k < 2; ++k) dst[m][k] = *(const PG8_LAS bf16x8*)(lds + PG8_SA(b, h) + aoff + m * 2048 + k * 1024); } while (0)
; #define PG8_MMA(ai, bj, At, Bt) do { __builtin_amdgcn_s_setprio(1); _Pragma("unroll") for (int m = 0; m < 4; ++m) _Pragma("unroll") for (int n = 0; n < 2; ++n) _Pragma("unroll") for (int k = 0; k < 2; ++k) \
;         acc[ai][bj][m][n] = __builtin_amdgcn_mfma_f32_16x16x32_bf16(Bt[n][k], At[m][k], acc[ai][bj][m][n], 0, 0, 0); __builtin_amdgcn_s_setprio(0); } while (0)
; #define PG8_WAIT_V(n) asm volatile("s_waitcnt vmcnt(" #n ")" ::: "memory")
; #define PG8_WAIT_L(n) asm volatile("s_waitcnt lgkmcnt(" #n ")" ::: "memory")
; #define PG8_BAR __builtin_amdgcn_s_barrier()
; #define PG8_SCHED __builtin_amdgcn_sched_barrier(0)
; template <class Epi, class Sched, bool ALIGN_EPI = false, bool SP2 = false>
; __device__ __forceinline__ void gemm_phase(PG8_LAS unsigned char* lds, const Gemm g, const Sched& S, const Epi& E) {
;     ...
;             PG8_WAIT_V(8); PG8_WAIT_L(0); PG8_BAR; PG8_MMA(0, 0, At, B0); PG8_MMA(0, 1, At, B1); PG8_BAR; PG8_SCHED;
;             PG8_LDA(At, 0, 1); PG8_STAGE(PG8_SB(0, 0), b2, voffB); PG8_STAGE(PG8_SB(0, 1), b2 + hstep, voffB); PG8_STAGE(PG8_SA(0, 0), a2, voffA);
.LfwP7_0_e:
	s_waitcnt lgkmcnt(0)
	s_barrier
	s_setprio 1
	s_waitcnt lgkmcnt(0)
	v_mfma_f32_16x16x32_bf16 v[124:127], v[154:157], v[186:189], 0
	v_mfma_f32_16x16x32_bf16 v[116:119], v[162:165], v[186:189], 0
	v_mfma_f32_16x16x32_bf16 v[108:111], v[154:157], v[194:197], 0
	v_mfma_f32_16x16x32_bf16 v[100:103], v[162:165], v[194:197], 0
	v_mfma_f32_16x16x32_bf16 v[92:95], v[154:157], v[202:205], 0
	v_mfma_f32_16x16x32_bf16 v[84:87], v[162:165], v[202:205], 0
	v_mfma_f32_16x16x32_bf16 v[76:79], v[154:157], v[210:213], 0
	v_mfma_f32_16x16x32_bf16 v[68:71], v[162:165], v[210:213], 0
	v_mfma_f32_16x16x32_bf16 v[124:127], v[158:161], v[190:193], v[124:127]
	v_mfma_f32_16x16x32_bf16 v[116:119], v[166:169], v[190:193], v[116:119]
	v_mfma_f32_16x16x32_bf16 v[108:111], v[158:161], v[198:201], v[108:111]
	v_mfma_f32_16x16x32_bf16 v[100:103], v[166:169], v[198:201], v[100:103]
	v_mfma_f32_16x16x32_bf16 v[92:95], v[158:161], v[206:209], v[92:95]
	v_mfma_f32_16x16x32_bf16 v[84:87], v[166:169], v[206:209], v[84:87]
	v_mfma_f32_16x16x32_bf16 v[76:79], v[158:161], v[214:217], v[76:79]
	v_mfma_f32_16x16x32_bf16 v[68:71], v[166:169], v[214:217], v[68:71]
	s_setprio 0
	s_setprio 1
	v_mfma_f32_16x16x32_bf16 v[120:123], v[170:173], v[186:189], 0
	v_mfma_f32_16x16x32_bf16 v[112:115], v[178:181], v[186:189], 0
	v_mfma_f32_16x16x32_bf16 v[104:107], v[170:173], v[194:197], 0
	v_mfma_f32_16x16x32_bf16 v[96:99], v[178:181], v[194:197], 0
	v_mfma_f32_16x16x32_bf16 v[88:91], v[170:173], v[202:205], 0
	v_mfma_f32_16x16x32_bf16 v[80:83], v[178:181], v[202:205], 0
	v_mfma_f32_16x16x32_bf16 v[72:75], v[170:173], v[210:213], 0
	v_mfma_f32_16x16x32_bf16 v[64:67], v[178:181], v[210:213], 0
	v_mfma_f32_16x16x32_bf16 v[120:123], v[174:177], v[190:193], v[120:123]
	v_mfma_f32_16x16x32_bf16 v[112:115], v[182:185], v[190:193], v[112:115]
	v_mfma_f32_16x16x32_bf16 v[104:107], v[174:177], v[198:201], v[104:107]
	v_mfma_f32_16x16x32_bf16 v[96:99], v[182:185], v[198:201], v[96:99]
	v_mfma_f32_16x16x32_bf16 v[88:91], v[174:177], v[206:209], v[88:91]
	v_mfma_f32_16x16x32_bf16 v[80:83], v[182:185], v[206:209], v[80:83]
	v_mfma_f32_16x16x32_bf16 v[72:75], v[174:177], v[214:217], v[72:75]
	v_mfma_f32_16x16x32_bf16 v[64:67], v[182:185], v[214:217], v[64:67]
	s_setprio 0
	s_barrier
	s_add_i32 s33, s62, s52
	s_add_u32 s82, s42, s10
	s_addc_u32 s83, s43, s11
	s_mov_b32 m0, s33
	ds_read_b128 v[186:189], v149 offset:16384
	ds_read_b128 v[190:193], v149 offset:17408
	ds_read_b128 v[194:197], v149 offset:18432
	ds_read_b128 v[198:201], v149 offset:19456
	ds_read_b128 v[202:205], v149 offset:20480
	ds_read_b128 v[206:209], v149 offset:21504
	ds_read_b128 v[210:213], v149 offset:22528
	ds_read_b128 v[214:217], v149 offset:23552
	global_load_lds_dwordx4 v130, s[42:43]
	s_add_i32 m0, s33, 0x2000
	s_add_u32 s78, s42, 0x40000
	s_addc_u32 s79, s43, 0
	s_add_i32 s33, s63, s52
	global_load_lds_dwordx4 v134, s[42:43]
	s_mov_b32 m0, s33
	s_add_u32 s84, s44, s10
	s_addc_u32 s85, s45, s11
	global_load_lds_dwordx4 v130, s[78:79]
	s_add_i32 m0, s33, 0x2000
	s_nop 0
	global_load_lds_dwordx4 v134, s[78:79]
	s_mov_b32 m0, s39
	s_nop 0
	global_load_lds_dwordx4 v128, s[44:45]
	s_mov_b32 m0, s55
	s_nop 0
	global_load_lds_dwordx4 v132, s[44:45]
	s_cmp_eq_u32 s77, 0
	s_cbranch_scc1 .LfwP7_1_s
	s_waitcnt vmcnt(16)
	s_branch .LfwP7_1_e

; #define PG8_STAGE(bufoff, gbase, voff) do { _Pragma("unroll") for (int _i = 0; _i < 2; ++_i) \
;         __builtin_amdgcn_global_load_lds((const unsigned*)((const char*)(gbase) + (voff)[_i]), (PG8_LAS unsigned*)(lds + (bufoff) + ldsw + _i * 8192), 16, 0, 0); } while (0)
; #define PG8_LDA(dst, b, h) do { _Pragma("unroll") for (int m = 0; m < 4; ++m) _Pragma("unroll") for (int k = 0; k < 2; ++k) dst[m][k] = *(const PG8_LAS bf16x8*)(lds + PG8_SA(b, h) + aoff + m * 2048 + k * 1024); } while (0)
; #define PG8_LDB(dst, b, h) do { _Pragma("unroll") for (int n = 0; n < 2; ++n) _Pragma("unroll") for (int k = 0; k < 2; ++k) dst[n][k] = *(const PG8_LAS bf16x8*)(lds + PG8_SB(b, h) + boff + n * 2048 + k * 1024); } while (0)
; #define PG8_MMA(ai, bj, At, Bt) do { __builtin_amdgcn_s_setprio(1); _Pragma("unroll") for (int m = 0; m < 4; ++m) _Pragma("unroll") for (int n = 0; n < 2; ++n) _Pragma("unroll") for (int k = 0; k < 2; ++k) \
;         acc[ai][bj][m][n] = __builtin_amdgcn_mfma_f32_16x16x32_bf16(Bt[n][k], At[m][k], acc[ai][bj][m][n], 0, 0, 0); __builtin_amdgcn_s_setprio(0); } while (0)
; #define PG8_WAIT_V(n) asm volatile("s_waitcnt vmcnt(" #n ")" ::: "memory")
; #define PG8_WAIT_L(n) asm volatile("s_waitcnt lgkmcnt(" #n ")" ::: "memory")
; #define PG8_BAR __builtin_amdgcn_s_barrier()
; #define PG8_SCHED __builtin_amdgcn_sched_barrier(0)
; template <class Epi, class Sched, bool ALIGN_EPI = false, bool SP2 = false>
; __device__ __forceinline__ void gemm_phase(PG8_LAS unsigned char* lds, const Gemm g, const Sched& S, const Epi& E) {
;     ...
;             PG8_WAIT_V(8); PG8_WAIT_L(0); PG8_BAR; PG8_MMA(1, 0, At, B0); PG8_MMA(1, 1, At, B1); PG8_BAR; PG8_SCHED;
;             PG8_LDB(B0, 1, 0); PG8_LDB(B1, 1, 1); PG8_SCHED; PG8_LDA(At, 1, 0); PG8_STAGE(PG8_SA(0, 1), a2 + hstep, voffA);
;             PG8_WAIT_V(8); PG8_WAIT_L(0); PG8_BAR; PG8_MMA(0, 0, At, B0); PG8_MMA(0, 1, At, B1); PG8_BAR; PG8_SCHED;
.LfwP7_1_e:
	s_waitcnt lgkmcnt(0)
	s_barrier
	s_setprio 1
	s_waitcnt lgkmcnt(0)
	v_mfma_f32_16x16x32_bf16 v[60:63], v[154:157], v[186:189], 0
	v_mfma_f32_16x16x32_bf16 v[52:55], v[162:165], v[186:189], 0
	v_mfma_f32_16x16x32_bf16 v[44:47], v[154:157], v[194:197], 0
	v_mfma_f32_16x16x32_bf16 v[36:39], v[162:165], v[194:197], 0
	v_mfma_f32_16x16x32_bf16 v[28:31], v[154:157], v[202:205], 0
	v_mfma_f32_16x16x32_bf16 v[20:23], v[162:165], v[202:205], 0
	v_mfma_f32_16x16x32_bf16 v[12:15], v[154:157], v[210:213], 0
	v_mfma_f32_16x16x32_bf16 v[4:7], v[162:165], v[210:213], 0
	v_mfma_f32_16x16x32_bf16 v[60:63], v[158:161], v[190:193], v[60:63]
	v_mfma_f32_16x16x32_bf16 v[52:55], v[166:169], v[190:193], v[52:55]
	v_mfma_f32_16x16x32_bf16 v[44:47], v[158:161], v[198:201], v[44:47]
	v_mfma_f32_16x16x32_bf16 v[36:39], v[166:169], v[198:201], v[36:39]
	v_mfma_f32_16x16x32_bf16 v[28:31], v[158:161], v[206:209], v[28:31]
	v_mfma_f32_16x16x32_bf16 v[20:23], v[166:169], v[206:209], v[20:23]
	v_mfma_f32_16x16x32_bf16 v[12:15], v[158:161], v[214:217], v[12:15]
	v_mfma_f32_16x16x32_bf16 v[4:7], v[166:169], v[214:217], v[4:7]
	s_setprio 0
	s_setprio 1
	v_mfma_f32_16x16x32_bf16 v[56:59], v[170:173], v[186:189], 0
	v_mfma_f32_16x16x32_bf16 v[48:51], v[178:181], v[186:189], 0
	v_mfma_f32_16x16x32_bf16 v[40:43], v[170:173], v[194:197], 0
	v_mfma_f32_16x16x32_bf16 v[32:35], v[178:181], v[194:197], 0
	v_mfma_f32_16x16x32_bf16 v[24:27], v[170:173], v[202:205], 0
	v_mfma_f32_16x16x32_bf16 v[16:19], v[178:181], v[202:205], 0
	v_mfma_f32_16x16x32_bf16 v[8:11], v[170:173], v[210:213], 0
	v_mfma_f32_16x16x32_bf16 v[0:3], v[178:181], v[210:213], 0
	v_mfma_f32_16x16x32_bf16 v[56:59], v[174:177], v[190:193], v[56:59]
	v_mfma_f32_16x16x32_bf16 v[48:51], v[182:185], v[190:193], v[48:51]
	v_mfma_f32_16x16x32_bf16 v[40:43], v[174:177], v[198:201], v[40:43]
	v_mfma_f32_16x16x32_bf16 v[32:35], v[182:185], v[198:201], v[32:35]
	v_mfma_f32_16x16x32_bf16 v[24:27], v[174:177], v[206:209], v[24:27]
	v_mfma_f32_16x16x32_bf16 v[16:19], v[182:185], v[206:209], v[16:19]
	v_mfma_f32_16x16x32_bf16 v[8:11], v[174:177], v[214:217], v[8:11]
	v_mfma_f32_16x16x32_bf16 v[0:3], v[182:185], v[214:217], v[0:3]
	s_setprio 0
	s_barrier
	s_add_i32 s33, 0, 0x18000
	v_add_u32_e32 v153, s33, v145
	s_add_i32 s34, 0, 0x1c000
	ds_read_b128 v[154:157], v153
	ds_read_b128 v[158:161], v153 offset:1024
	ds_read_b128 v[162:165], v153 offset:2048
	ds_read_b128 v[166:169], v153 offset:3072
	v_add_u32_e32 v153, s34, v145
	ds_read_b128 v[170:173], v153
	ds_read_b128 v[174:177], v153 offset:1024
	ds_read_b128 v[178:181], v153 offset:2048
	ds_read_b128 v[182:185], v153 offset:3072
	s_add_u32 s44, s44, 0x40000
	s_addc_u32 s45, s45, 0
	s_mov_b32 m0, s56
	ds_read_b128 v[186:189], v149 offset:32768
	ds_read_b128 v[190:193], v149 offset:33792
	ds_read_b128 v[194:197], v149 offset:34816
	ds_read_b128 v[198:201], v149 offset:35840
	ds_read_b128 v[202:205], v149 offset:36864
	ds_read_b128 v[206:209], v149 offset:37888
	ds_read_b128 v[210:213], v149 offset:38912
	ds_read_b128 v[214:217], v149 offset:39936
	global_load_lds_dwordx4 v128, s[44:45]
	s_mov_b32 m0, s57
	s_nop 0
	global_load_lds_dwordx4 v132, s[44:45]
	s_waitcnt vmcnt(8)
	s_waitcnt lgkmcnt(0)
	s_barrier
	s_setprio 1
	s_waitcnt lgkmcnt(0)
	v_mfma_f32_16x16x32_bf16 v[124:127], v[154:157], v[186:189], v[124:127]
	v_mfma_f32_16x16x32_bf16 v[116:119], v[162:165], v[186:189], v[116:119]
	v_mfma_f32_16x16x32_bf16 v[108:111], v[154:157], v[194:197], v[108:111]
	v_mfma_f32_16x16x32_bf16 v[100:103], v[162:165], v[194:197], v[100:103]
	v_mfma_f32_16x16x32_bf16 v[92:95], v[154:157], v[202:205], v[92:95]
	v_mfma_f32_16x16x32_bf16 v[84:87], v[162:165], v[202:205], v[84:87]
	v_mfma_f32_16x16x32_bf16 v[76:79], v[154:157], v[210:213], v[76:79]
	v_mfma_f32_16x16x32_bf16 v[68:71], v[162:165], v[210:213], v[68:71]
	v_mfma_f32_16x16x32_bf16 v[124:127], v[158:161], v[190:193], v[124:127]
	v_mfma_f32_16x16x32_bf16 v[116:119], v[166:169], v[190:193], v[116:119]
	v_mfma_f32_16x16x32_bf16 v[108:111], v[158:161], v[198:201], v[108:111]
	v_mfma_f32_16x16x32_bf16 v[100:103], v[166:169], v[198:201], v[100:103]
	v_mfma_f32_16x16x32_bf16 v[92:95], v[158:161], v[206:209], v[92:95]
	v_mfma_f32_16x16x32_bf16 v[84:87], v[166:169], v[206:209], v[84:87]
	v_mfma_f32_16x16x32_bf16 v[76:79], v[158:161], v[214:217], v[76:79]
	v_mfma_f32_16x16x32_bf16 v[68:71], v[166:169], v[214:217], v[68:71]
	s_setprio 0
	s_setprio 1
	v_mfma_f32_16x16x32_bf16 v[120:123], v[170:173], v[186:189], v[120:123]
	v_mfma_f32_16x16x32_bf16 v[112:115], v[178:181], v[186:189], v[112:115]
	v_mfma_f32_16x16x32_bf16 v[104:107], v[170:173], v[194:197], v[104:107]
	v_mfma_f32_16x16x32_bf16 v[96:99], v[178:181], v[194:197], v[96:99]
	v_mfma_f32_16x16x32_bf16 v[88:91], v[170:173], v[202:205], v[88:91]
	v_mfma_f32_16x16x32_bf16 v[80:83], v[178:181], v[202:205], v[80:83]
	v_mfma_f32_16x16x32_bf16 v[72:75], v[170:173], v[210:213], v[72:75]
	v_mfma_f32_16x16x32_bf16 v[64:67], v[178:181], v[210:213], v[64:67]
	v_mfma_f32_16x16x32_bf16 v[120:123], v[174:177], v[190:193], v[120:123]
	v_mfma_f32_16x16x32_bf16 v[112:115], v[182:185], v[190:193], v[112:115]
	v_mfma_f32_16x16x32_bf16 v[104:107], v[174:177], v[198:201], v[104:107]
	v_mfma_f32_16x16x32_bf16 v[96:99], v[182:185], v[198:201], v[96:99]
	v_mfma_f32_16x16x32_bf16 v[88:91], v[174:177], v[206:209], v[88:91]
	v_mfma_f32_16x16x32_bf16 v[80:83], v[182:185], v[206:209], v[80:83]
	v_mfma_f32_16x16x32_bf16 v[72:75], v[174:177], v[214:217], v[72:75]
	v_mfma_f32_16x16x32_bf16 v[64:67], v[182:185], v[214:217], v[64:67]
	s_setprio 0
	s_barrier
; #define PG8_STAGE(bufoff, gbase, voff) do { _Pragma("unroll") for (int _i = 0; _i < 2; ++_i) \
;         __builtin_amdgcn_global_load_lds((const unsigned*)((const char*)(gbase) + (voff)[_i]), (PG8_LAS unsigned*)(lds + (bufoff) + ldsw + _i * 8192), 16, 0, 0); } while (0)
; #define PG8_LDA(dst, b, h) do { _Pragma("unroll") for (int m = 0; m < 4; ++m) _Pragma("unroll") for (int k = 0; k < 2; ++k) dst[m][k] = *(const PG8_LAS bf16x8*)(lds + PG8_SA(b, h) + aoff + m * 2048 + k * 1024); } while (0)
; #define PG8_MMA(ai, bj, At, Bt) do { __builtin_amdgcn_s_setprio(1); _Pragma("unroll") for (int m = 0; m < 4; ++m) _Pragma("unroll") for (int n = 0; n < 2; ++n) _Pragma("unroll") for (int k = 0; k < 2; ++k) \
;         acc[ai][bj][m][n] = __builtin_amdgcn_mfma_f32_16x16x32_bf16(Bt[n][k], At[m][k], acc[ai][bj][m][n], 0, 0, 0); __builtin_amdgcn_s_setprio(0); } while (0)
; #define PG8_WAIT_V(n) asm volatile("s_waitcnt vmcnt(" #n ")" ::: "memory")
; #define PG8_WAIT_L(n) asm volatile("s_waitcnt lgkmcnt(" #n ")" ::: "memory")
; #define PG8_BAR __builtin_amdgcn_s_barrier()
; #define PG8_SCHED __builtin_amdgcn_sched_barrier(0)
; template <class Epi, class Sched, bool ALIGN_EPI = false, bool SP2 = false>
; __device__ __forceinline__ void gemm_phase(PG8_LAS unsigned char* lds, const Gemm g, const Sched& S, const Epi& E) {
;     ...
;             PG8_LDA(At, 1, 1); PG8_STAGE(PG8_SB(1, 0), b3, voffB); PG8_STAGE(PG8_SB(1, 1), b3 + hstep, voffB); PG8_STAGE(PG8_SA(1, 0), a3, voffA);
;             PG8_WAIT_V(8); PG8_WAIT_L(0); PG8_BAR; PG8_MMA(1, 0, At, B0); PG8_MMA(1, 1, At, B1); PG8_BAR; PG8_SCHED;
	s_add_i32 s33, s33, s52
	s_mov_b32 m0, s33
	ds_read_b128 v[186:189], v149 offset:49152
	ds_read_b128 v[190:193], v149 offset:50176
	ds_read_b128 v[194:197], v149 offset:51200
	ds_read_b128 v[198:201], v149 offset:52224
	ds_read_b128 v[202:205], v149 offset:53248
	ds_read_b128 v[206:209], v149 offset:54272
	ds_read_b128 v[210:213], v149 offset:55296
	ds_read_b128 v[214:217], v149 offset:56320
	global_load_lds_dwordx4 v130, s[82:83]
	s_add_i32 m0, s33, 0x2000
	s_add_u32 s42, s42, 0x40080
	s_addc_u32 s43, s43, 0
	s_add_i32 s33, s34, s52
	global_load_lds_dwordx4 v134, s[82:83]
	s_mov_b32 m0, s33
	s_nop 0
	global_load_lds_dwordx4 v130, s[42:43]
	s_add_i32 m0, s33, 0x2000
	s_nop 0
	global_load_lds_dwordx4 v134, s[42:43]
	s_mov_b32 m0, s60
	s_nop 0
	global_load_lds_dwordx4 v128, s[84:85]
	s_mov_b32 m0, s61
	s_nop 0
	global_load_lds_dwordx4 v132, s[84:85]
	s_waitcnt vmcnt(8)
	s_waitcnt lgkmcnt(0)
	s_barrier
	s_setprio 1
	s_waitcnt lgkmcnt(0)
	v_mfma_f32_16x16x32_bf16 v[60:63], v[154:157], v[186:189], v[60:63]
	v_mfma_f32_16x16x32_bf16 v[52:55], v[162:165], v[186:189], v[52:55]
	v_mfma_f32_16x16x32_bf16 v[44:47], v[154:157], v[194:197], v[44:47]
	v_mfma_f32_16x16x32_bf16 v[36:39], v[162:165], v[194:197], v[36:39]
	v_mfma_f32_16x16x32_bf16 v[28:31], v[154:157], v[202:205], v[28:31]
	v_mfma_f32_16x16x32_bf16 v[20:23], v[162:165], v[202:205], v[20:23]
	v_mfma_f32_16x16x32_bf16 v[12:15], v[154:157], v[210:213], v[12:15]
	v_mfma_f32_16x16x32_bf16 v[4:7], v[162:165], v[210:213], v[4:7]
	v_mfma_f32_16x16x32_bf16 v[60:63], v[158:161], v[190:193], v[60:63]
	v_mfma_f32_16x16x32_bf16 v[52:55], v[166:169], v[190:193], v[52:55]
	v_mfma_f32_16x16x32_bf16 v[44:47], v[158:161], v[198:201], v[44:47]
	v_mfma_f32_16x16x32_bf16 v[36:39], v[166:169], v[198:201], v[36:39]
	v_mfma_f32_16x16x32_bf16 v[28:31], v[158:161], v[206:209], v[28:31]
	v_mfma_f32_16x16x32_bf16 v[20:23], v[166:169], v[206:209], v[20:23]
	v_mfma_f32_16x16x32_bf16 v[12:15], v[158:161], v[214:217], v[12:15]
	v_mfma_f32_16x16x32_bf16 v[4:7], v[166:169], v[214:217], v[4:7]
	s_setprio 0
	s_setprio 1
	v_mfma_f32_16x16x32_bf16 v[56:59], v[170:173], v[186:189], v[56:59]
	v_mfma_f32_16x16x32_bf16 v[48:51], v[178:181], v[186:189], v[48:51]
	v_mfma_f32_16x16x32_bf16 v[40:43], v[170:173], v[194:197], v[40:43]
	v_mfma_f32_16x16x32_bf16 v[32:35], v[178:181], v[194:197], v[32:35]
	v_mfma_f32_16x16x32_bf16 v[24:27], v[170:173], v[202:205], v[24:27]
	v_mfma_f32_16x16x32_bf16 v[16:19], v[178:181], v[202:205], v[16:19]
	v_mfma_f32_16x16x32_bf16 v[8:11], v[170:173], v[210:213], v[8:11]
	v_mfma_f32_16x16x32_bf16 v[0:3], v[178:181], v[210:213], v[0:3]
	v_mfma_f32_16x16x32_bf16 v[56:59], v[174:177], v[190:193], v[56:59]
	v_mfma_f32_16x16x32_bf16 v[48:51], v[182:185], v[190:193], v[48:51]
	v_mfma_f32_16x16x32_bf16 v[40:43], v[174:177], v[198:201], v[40:43]
	v_mfma_f32_16x16x32_bf16 v[32:35], v[182:185], v[198:201], v[32:35]
	v_mfma_f32_16x16x32_bf16 v[24:27], v[174:177], v[206:209], v[24:27]
	v_mfma_f32_16x16x32_bf16 v[16:19], v[182:185], v[206:209], v[16:19]
	v_mfma_f32_16x16x32_bf16 v[8:11], v[174:177], v[214:217], v[8:11]
	v_mfma_f32_16x16x32_bf16 v[0:3], v[182:185], v[214:217], v[0:3]
	s_setprio 0
	s_barrier
	s_add_i32 s76, s76, 2
	s_add_u32 s40, s40, 0x100
	s_addc_u32 s41, s41, 0
	s_add_u32 s74, s74, 0x100
	s_addc_u32 s75, s75, 0
	s_cmp_gt_u32 s76, 13

; __device__ __forceinline__ unsigned pk2(float lo, float hi) { f32x2 v = {lo, hi}; bf16x2_t b = __builtin_convertvector(v, bf16x2_t); return __builtin_bit_cast(unsigned, b); }
; __device__ __forceinline__ float silu_f(float a) { return a * __builtin_amdgcn_rcpf(1.0f + __expf(-a)); }
;     __device__ __forceinline__ void operator()(const f32x4 (&acc)[2][2][4][2], const Unit& u, int wr, int wc, int fr, int fq) const {
;         const int row0 = u.pm * BM + wr * 64 + fr; const int col0 = u.pn * HALF + wc * 32 + 8 * fq;
; #pragma unroll
;         for (int ai = 0; ai < 2; ++ai)
; #pragma unroll
;             for (int m = 0; m < 4; ++m) { const int row = row0 + ai * HALF + m * 16;
;                 const f32x4 a0 = acc[ai][0][m][0], a1 = acc[ai][0][m][1], b0 = acc[ai][1][m][0], b1 = acc[ai][1][m][1];
;                 u32x4 w; w.x = pk2(silu_f(a0[0]) * b0[0], silu_f(a0[1]) * b0[1]); w.y = pk2(silu_f(a0[2]) * b0[2], silu_f(a0[3]) * b0[3]);
;                 w.z = pk2(silu_f(a1[0]) * b1[0], silu_f(a1[1]) * b1[1]); w.w = pk2(silu_f(a1[2]) * b1[2], silu_f(a1[3]) * b1[3]);
;                 *(u32x4*)(H + (size_t)row * ldh + col0) = w; }
;     }
.LBB0_717:
	s_mov_b32 s77, 1
	v_mul_f32_e32 v151, 0xbfb8aa3b, v124
	v_exp_f32_e32 v151, v151
	v_mul_f32_e32 v153, 0xbfb8aa3b, v125
	v_exp_f32_e32 v153, v153
	v_mul_f32_e32 v157, 0xbfb8aa3b, v127
	v_add_f32_e32 v151, 1.0, v151
	v_rcp_f32_e32 v156, v151
	v_add_f32_e32 v151, 1.0, v153
	v_mul_f32_e32 v153, 0xbfb8aa3b, v126
	v_exp_f32_e32 v153, v153
	v_exp_f32_e32 v159, v157
	v_rcp_f32_e32 v157, v151
	v_lshl_or_b32 v154, s71, 7, v146
	v_add_f32_e32 v151, 1.0, v153
	v_rcp_f32_e32 v158, v151
	v_add_f32_e32 v151, 1.0, v159
	v_rcp_f32_e32 v159, v151
	v_pk_mul_f32 v[124:125], v[124:125], v[156:157]
	v_lshl_add_u32 v150, s38, 8, v144
	v_pk_mul_f32 v[120:121], v[124:125], v[120:121]
	v_pk_mul_f32 v[124:125], v[126:127], v[158:159]
	v_cvt_pk_bf16_f32 v120, v120, v121
	v_mul_f32_e32 v121, 0xbfb8aa3b, v116
	v_pk_mul_f32 v[122:123], v[124:125], v[122:123]
	v_exp_f32_e32 v124, v121
	v_mul_f32_e32 v121, 0xbfb8aa3b, v117
	v_exp_f32_e32 v125, v121
	v_cvt_pk_bf16_f32 v121, v122, v123
	v_add_f32_e32 v122, 1.0, v124
	v_mul_f32_e32 v124, 0xbfb8aa3b, v118
	v_add_f32_e32 v123, 1.0, v125
	v_mul_f32_e32 v125, 0xbfb8aa3b, v119
	v_exp_f32_e32 v124, v124
	v_exp_f32_e32 v125, v125
	v_rcp_f32_e32 v122, v122
	v_rcp_f32_e32 v123, v123
	v_add_f32_e32 v124, 1.0, v124
	v_add_f32_e32 v125, 1.0, v125
	v_rcp_f32_e32 v124, v124
	v_rcp_f32_e32 v125, v125
	v_pk_mul_f32 v[116:117], v[116:117], v[122:123]
	v_ashrrev_i32_e32 v155, 31, v154
	v_pk_mul_f32 v[112:113], v[116:117], v[112:113]
	s_andn2_b64 vcc, exec, s[0:1]
	v_cvt_pk_bf16_f32 v122, v112, v113
	v_pk_mul_f32 v[112:113], v[118:119], v[124:125]
	v_mul_f32_e32 v118, 0xbfb8aa3b, v110
	v_pk_mul_f32 v[112:113], v[112:113], v[114:115]
	v_lshlrev_b64 v[114:115], 1, v[154:155]
	v_cvt_pk_bf16_f32 v123, v112, v113
	v_mov_b64_e32 v[112:113], s[8:9]
	v_mad_i64_i32 v[116:117], s[40:41], v150, s70, v[112:113]
	v_lshl_add_u64 v[116:117], v[116:117], 0, v[114:115]
	global_store_dwordx4 v[116:117], v[120:123], off
	v_mul_f32_e32 v116, 0xbfb8aa3b, v108
	v_mul_f32_e32 v117, 0xbfb8aa3b, v109
	v_exp_f32_e32 v116, v116
	v_exp_f32_e32 v117, v117
	v_mul_f32_e32 v119, 0xbfb8aa3b, v111
	v_exp_f32_e32 v118, v118
	v_exp_f32_e32 v119, v119
	v_add_f32_e32 v116, 1.0, v116
	v_add_f32_e32 v117, 1.0, v117
	v_rcp_f32_e32 v116, v116
	v_rcp_f32_e32 v117, v117
	v_add_f32_e32 v118, 1.0, v118
	v_add_f32_e32 v119, 1.0, v119
	v_rcp_f32_e32 v118, v118
	v_rcp_f32_e32 v119, v119
	v_pk_mul_f32 v[108:109], v[108:109], v[116:117]
	v_or_b32_e32 v120, 16, v150
	v_pk_mul_f32 v[104:105], v[108:109], v[104:105]
	v_pk_mul_f32 v[108:109], v[110:111], v[118:119]
	v_cvt_pk_bf16_f32 v104, v104, v105
	v_mul_f32_e32 v105, 0xbfb8aa3b, v100
	v_pk_mul_f32 v[106:107], v[108:109], v[106:107]
	v_exp_f32_e32 v108, v105
	v_mul_f32_e32 v105, 0xbfb8aa3b, v101
	v_exp_f32_e32 v109, v105
	v_cvt_pk_bf16_f32 v105, v106, v107
	v_add_f32_e32 v106, 1.0, v108
	v_mul_f32_e32 v108, 0xbfb8aa3b, v102
	v_add_f32_e32 v107, 1.0, v109
	v_mul_f32_e32 v109, 0xbfb8aa3b, v103
	v_exp_f32_e32 v108, v108
	v_exp_f32_e32 v109, v109
	v_rcp_f32_e32 v106, v106
	v_rcp_f32_e32 v107, v107
	v_add_f32_e32 v108, 1.0, v108
	v_add_f32_e32 v109, 1.0, v109
	v_rcp_f32_e32 v108, v108
	v_rcp_f32_e32 v109, v109
	v_pk_mul_f32 v[100:101], v[100:101], v[106:107]
	s_mov_b64 s[0:1], -1
	v_pk_mul_f32 v[96:97], v[100:101], v[96:97]
	v_or_b32_e32 v100, 32, v150
	v_cvt_pk_bf16_f32 v106, v96, v97
	v_pk_mul_f32 v[96:97], v[102:103], v[108:109]
	s_nop 0
	v_pk_mul_f32 v[96:97], v[96:97], v[98:99]
	v_mul_f32_e32 v98, 0xbfb8aa3b, v94
	v_cvt_pk_bf16_f32 v107, v96, v97
	v_mad_i64_i32 v[96:97], s[40:41], v120, s70, v[112:113]
	v_lshl_add_u64 v[96:97], v[96:97], 0, v[114:115]
	global_store_dwordx4 v[96:97], v[104:107], off
	v_mul_f32_e32 v96, 0xbfb8aa3b, v92
	v_mul_f32_e32 v97, 0xbfb8aa3b, v93
	v_exp_f32_e32 v96, v96
	v_exp_f32_e32 v97, v97
	v_mul_f32_e32 v99, 0xbfb8aa3b, v95
	v_exp_f32_e32 v98, v98
	v_exp_f32_e32 v99, v99
	v_add_f32_e32 v96, 1.0, v96
	v_add_f32_e32 v97, 1.0, v97
	v_rcp_f32_e32 v96, v96
	v_rcp_f32_e32 v97, v97
	v_add_f32_e32 v98, 1.0, v98
	v_add_f32_e32 v99, 1.0, v99
	v_rcp_f32_e32 v98, v98
	v_rcp_f32_e32 v99, v99
	v_pk_mul_f32 v[92:93], v[92:93], v[96:97]
	s_nop 0
	v_pk_mul_f32 v[88:89], v[92:93], v[88:89]
	v_pk_mul_f32 v[92:93], v[94:95], v[98:99]
	v_cvt_pk_bf16_f32 v88, v88, v89
	v_mul_f32_e32 v89, 0xbfb8aa3b, v84
	v_pk_mul_f32 v[90:91], v[92:93], v[90:91]
	v_exp_f32_e32 v92, v89
	v_mul_f32_e32 v89, 0xbfb8aa3b, v85
	v_exp_f32_e32 v93, v89
	v_cvt_pk_bf16_f32 v89, v90, v91
	v_add_f32_e32 v90, 1.0, v92
	v_mul_f32_e32 v92, 0xbfb8aa3b, v86
	v_add_f32_e32 v91, 1.0, v93
	v_mul_f32_e32 v93, 0xbfb8aa3b, v87
	v_exp_f32_e32 v92, v92
	v_exp_f32_e32 v93, v93
	v_rcp_f32_e32 v90, v90
	v_rcp_f32_e32 v91, v91
	v_add_f32_e32 v92, 1.0, v92
	v_add_f32_e32 v93, 1.0, v93
	v_rcp_f32_e32 v92, v92
	v_rcp_f32_e32 v93, v93
	v_pk_mul_f32 v[84:85], v[84:85], v[90:91]
	s_nop 0
	v_pk_mul_f32 v[80:81], v[84:85], v[80:81]
	v_or_b32_e32 v84, 48, v150
	v_cvt_pk_bf16_f32 v90, v80, v81
	v_pk_mul_f32 v[80:81], v[86:87], v[92:93]
	s_nop 0
	v_pk_mul_f32 v[80:81], v[80:81], v[82:83]
	v_mul_f32_e32 v82, 0xbfb8aa3b, v78
	v_cvt_pk_bf16_f32 v91, v80, v81
	v_mad_i64_i32 v[80:81], s[40:41], v100, s70, v[112:113]
	v_lshl_add_u64 v[80:81], v[80:81], 0, v[114:115]
	global_store_dwordx4 v[80:81], v[88:91], off
	v_mul_f32_e32 v80, 0xbfb8aa3b, v76
	v_mul_f32_e32 v81, 0xbfb8aa3b, v77
	v_exp_f32_e32 v80, v80
	v_exp_f32_e32 v81, v81
	v_mul_f32_e32 v83, 0xbfb8aa3b, v79
	v_exp_f32_e32 v82, v82
	v_exp_f32_e32 v83, v83
	v_add_f32_e32 v80, 1.0, v80
	v_add_f32_e32 v81, 1.0, v81
	v_rcp_f32_e32 v80, v80
	v_rcp_f32_e32 v81, v81
	v_add_f32_e32 v82, 1.0, v82
	v_add_f32_e32 v83, 1.0, v83
; __device__ __forceinline__ unsigned pk2(float lo, float hi) { f32x2 v = {lo, hi}; bf16x2_t b = __builtin_convertvector(v, bf16x2_t); return __builtin_bit_cast(unsigned, b); }
; __device__ __forceinline__ float silu_f(float a) { return a * __builtin_amdgcn_rcpf(1.0f + __expf(-a)); }
;     __device__ __forceinline__ void operator()(const f32x4 (&acc)[2][2][4][2], const Unit& u, int wr, int wc, int fr, int fq) const {
;     ...
;             for (int m = 0; m < 4; ++m) { const int row = row0 + ai * HALF + m * 16;
;                 const f32x4 a0 = acc[ai][0][m][0], a1 = acc[ai][0][m][1], b0 = acc[ai][1][m][0], b1 = acc[ai][1][m][1];
;                 u32x4 w; w.x = pk2(silu_f(a0[0]) * b0[0], silu_f(a0[1]) * b0[1]); w.y = pk2(silu_f(a0[2]) * b0[2], silu_f(a0[3]) * b0[3]);
;                 w.z = pk2(silu_f(a1[0]) * b1[0], silu_f(a1[1]) * b1[1]); w.w = pk2(silu_f(a1[2]) * b1[2], silu_f(a1[3]) * b1[3]);
;                 *(u32x4*)(H + (size_t)row * ldh + col0) = w; }
	v_rcp_f32_e32 v82, v82
	v_rcp_f32_e32 v83, v83
	v_pk_mul_f32 v[76:77], v[76:77], v[80:81]
	s_nop 0
	v_pk_mul_f32 v[72:73], v[76:77], v[72:73]
	v_pk_mul_f32 v[76:77], v[78:79], v[82:83]
	v_cvt_pk_bf16_f32 v72, v72, v73
	v_mul_f32_e32 v73, 0xbfb8aa3b, v68
	v_pk_mul_f32 v[74:75], v[76:77], v[74:75]
	v_exp_f32_e32 v76, v73
	v_mul_f32_e32 v73, 0xbfb8aa3b, v69
	v_exp_f32_e32 v77, v73
	v_cvt_pk_bf16_f32 v73, v74, v75
	v_add_f32_e32 v74, 1.0, v76
	v_mul_f32_e32 v76, 0xbfb8aa3b, v70
	v_add_f32_e32 v75, 1.0, v77
	v_mul_f32_e32 v77, 0xbfb8aa3b, v71
	v_exp_f32_e32 v76, v76
	v_exp_f32_e32 v77, v77
	v_rcp_f32_e32 v74, v74
	v_rcp_f32_e32 v75, v75
	v_add_f32_e32 v76, 1.0, v76
	v_add_f32_e32 v77, 1.0, v77
	v_rcp_f32_e32 v76, v76
	v_rcp_f32_e32 v77, v77
	v_pk_mul_f32 v[68:69], v[68:69], v[74:75]
	s_nop 0
	v_pk_mul_f32 v[64:65], v[68:69], v[64:65]
	v_add_u32_e32 v68, 0x80, v150
	v_cvt_pk_bf16_f32 v74, v64, v65
	v_pk_mul_f32 v[64:65], v[70:71], v[76:77]
	s_nop 0
	v_pk_mul_f32 v[64:65], v[64:65], v[66:67]
	v_mul_f32_e32 v66, 0xbfb8aa3b, v62
	v_cvt_pk_bf16_f32 v75, v64, v65
	v_mad_i64_i32 v[64:65], s[40:41], v84, s70, v[112:113]
	v_lshl_add_u64 v[64:65], v[64:65], 0, v[114:115]
	global_store_dwordx4 v[64:65], v[72:75], off
	v_mul_f32_e32 v64, 0xbfb8aa3b, v60
	v_mul_f32_e32 v65, 0xbfb8aa3b, v61
	v_exp_f32_e32 v64, v64
	v_exp_f32_e32 v65, v65
	v_mul_f32_e32 v67, 0xbfb8aa3b, v63
	v_exp_f32_e32 v66, v66
	v_exp_f32_e32 v67, v67
	v_add_f32_e32 v64, 1.0, v64
	v_add_f32_e32 v65, 1.0, v65
	v_rcp_f32_e32 v64, v64
	v_rcp_f32_e32 v65, v65
	v_add_f32_e32 v66, 1.0, v66
	v_add_f32_e32 v67, 1.0, v67
	v_rcp_f32_e32 v66, v66
	v_rcp_f32_e32 v67, v67
	v_pk_mul_f32 v[60:61], v[60:61], v[64:65]
	s_nop 0
	v_pk_mul_f32 v[56:57], v[60:61], v[56:57]
	v_pk_mul_f32 v[60:61], v[62:63], v[66:67]
	v_cvt_pk_bf16_f32 v56, v56, v57
	v_mul_f32_e32 v57, 0xbfb8aa3b, v52
	v_pk_mul_f32 v[58:59], v[60:61], v[58:59]
	v_exp_f32_e32 v60, v57
	v_mul_f32_e32 v57, 0xbfb8aa3b, v53
	v_exp_f32_e32 v61, v57
	v_cvt_pk_bf16_f32 v57, v58, v59
	v_add_f32_e32 v58, 1.0, v60
	v_mul_f32_e32 v60, 0xbfb8aa3b, v54
	v_add_f32_e32 v59, 1.0, v61
	v_mul_f32_e32 v61, 0xbfb8aa3b, v55
	v_exp_f32_e32 v60, v60
	v_exp_f32_e32 v61, v61
	v_rcp_f32_e32 v58, v58
	v_rcp_f32_e32 v59, v59
	v_add_f32_e32 v60, 1.0, v60
	v_add_f32_e32 v61, 1.0, v61
	v_rcp_f32_e32 v60, v60
	v_rcp_f32_e32 v61, v61
	v_pk_mul_f32 v[52:53], v[52:53], v[58:59]
	s_nop 0
	v_pk_mul_f32 v[48:49], v[52:53], v[48:49]
	v_add_u32_e32 v52, 0x90, v150
	v_cvt_pk_bf16_f32 v58, v48, v49
	v_pk_mul_f32 v[48:49], v[54:55], v[60:61]
	s_nop 0
	v_pk_mul_f32 v[48:49], v[48:49], v[50:51]
	v_mul_f32_e32 v50, 0xbfb8aa3b, v46
	v_cvt_pk_bf16_f32 v59, v48, v49
	v_mad_i64_i32 v[48:49], s[40:41], v68, s70, v[112:113]
	v_lshl_add_u64 v[48:49], v[48:49], 0, v[114:115]
	global_store_dwordx4 v[48:49], v[56:59], off
	v_mul_f32_e32 v48, 0xbfb8aa3b, v44
	v_mul_f32_e32 v49, 0xbfb8aa3b, v45
	v_exp_f32_e32 v48, v48
	v_exp_f32_e32 v49, v49
	v_mul_f32_e32 v51, 0xbfb8aa3b, v47
	v_exp_f32_e32 v50, v50
	v_exp_f32_e32 v51, v51
	v_add_f32_e32 v48, 1.0, v48
	v_add_f32_e32 v49, 1.0, v49
	v_rcp_f32_e32 v48, v48
	v_rcp_f32_e32 v49, v49
	v_add_f32_e32 v50, 1.0, v50
	v_add_f32_e32 v51, 1.0, v51
	v_rcp_f32_e32 v50, v50
	v_rcp_f32_e32 v51, v51
	v_pk_mul_f32 v[44:45], v[44:45], v[48:49]
	s_nop 0
	v_pk_mul_f32 v[40:41], v[44:45], v[40:41]
	v_pk_mul_f32 v[44:45], v[46:47], v[50:51]
	v_cvt_pk_bf16_f32 v40, v40, v41
	v_mul_f32_e32 v41, 0xbfb8aa3b, v36
	v_pk_mul_f32 v[42:43], v[44:45], v[42:43]
	v_exp_f32_e32 v44, v41
	v_mul_f32_e32 v41, 0xbfb8aa3b, v37
	v_exp_f32_e32 v45, v41
	v_cvt_pk_bf16_f32 v41, v42, v43
	v_add_f32_e32 v42, 1.0, v44
	v_mul_f32_e32 v44, 0xbfb8aa3b, v38
	v_add_f32_e32 v43, 1.0, v45
	v_mul_f32_e32 v45, 0xbfb8aa3b, v39
	v_exp_f32_e32 v44, v44
	v_exp_f32_e32 v45, v45
	v_rcp_f32_e32 v42, v42
; __device__ __forceinline__ unsigned pk2(float lo, float hi) { f32x2 v = {lo, hi}; bf16x2_t b = __builtin_convertvector(v, bf16x2_t); return __builtin_bit_cast(unsigned, b); }
; __device__ __forceinline__ float silu_f(float a) { return a * __builtin_amdgcn_rcpf(1.0f + __expf(-a)); }
;     __device__ __forceinline__ void operator()(const f32x4 (&acc)[2][2][4][2], const Unit& u, int wr, int wc, int fr, int fq) const {
;     ...
;             for (int m = 0; m < 4; ++m) { const int row = row0 + ai * HALF + m * 16;
;                 const f32x4 a0 = acc[ai][0][m][0], a1 = acc[ai][0][m][1], b0 = acc[ai][1][m][0], b1 = acc[ai][1][m][1];
;                 u32x4 w; w.x = pk2(silu_f(a0[0]) * b0[0], silu_f(a0[1]) * b0[1]); w.y = pk2(silu_f(a0[2]) * b0[2], silu_f(a0[3]) * b0[3]);
;                 w.z = pk2(silu_f(a1[0]) * b1[0], silu_f(a1[1]) * b1[1]); w.w = pk2(silu_f(a1[2]) * b1[2], silu_f(a1[3]) * b1[3]);
;                 *(u32x4*)(H + (size_t)row * ldh + col0) = w; }
	v_rcp_f32_e32 v43, v43
	v_add_f32_e32 v44, 1.0, v44
	v_add_f32_e32 v45, 1.0, v45
	v_rcp_f32_e32 v44, v44
	v_rcp_f32_e32 v45, v45
	v_pk_mul_f32 v[36:37], v[36:37], v[42:43]
	s_nop 0
	v_pk_mul_f32 v[32:33], v[36:37], v[32:33]
	v_add_u32_e32 v36, 0xa0, v150
	v_cvt_pk_bf16_f32 v42, v32, v33
	v_pk_mul_f32 v[32:33], v[38:39], v[44:45]
	s_nop 0
	v_pk_mul_f32 v[32:33], v[32:33], v[34:35]
	v_mul_f32_e32 v34, 0xbfb8aa3b, v30
	v_cvt_pk_bf16_f32 v43, v32, v33
	v_mad_i64_i32 v[32:33], s[40:41], v52, s70, v[112:113]
	v_lshl_add_u64 v[32:33], v[32:33], 0, v[114:115]
	global_store_dwordx4 v[32:33], v[40:43], off
	v_mul_f32_e32 v32, 0xbfb8aa3b, v28
	v_mul_f32_e32 v33, 0xbfb8aa3b, v29
	v_exp_f32_e32 v32, v32
	v_exp_f32_e32 v33, v33
	v_mul_f32_e32 v35, 0xbfb8aa3b, v31
	v_exp_f32_e32 v34, v34
	v_exp_f32_e32 v35, v35
	v_add_f32_e32 v32, 1.0, v32
	v_add_f32_e32 v33, 1.0, v33
	v_rcp_f32_e32 v32, v32
	v_rcp_f32_e32 v33, v33
	v_add_f32_e32 v34, 1.0, v34
	v_add_f32_e32 v35, 1.0, v35
	v_rcp_f32_e32 v34, v34
	v_rcp_f32_e32 v35, v35
	v_pk_mul_f32 v[28:29], v[28:29], v[32:33]
	s_nop 0
	v_pk_mul_f32 v[24:25], v[28:29], v[24:25]
	v_pk_mul_f32 v[28:29], v[30:31], v[34:35]
	v_cvt_pk_bf16_f32 v24, v24, v25
	v_mul_f32_e32 v25, 0xbfb8aa3b, v20
	v_pk_mul_f32 v[26:27], v[28:29], v[26:27]
	v_exp_f32_e32 v28, v25
	v_mul_f32_e32 v25, 0xbfb8aa3b, v21
	v_exp_f32_e32 v29, v25
	v_cvt_pk_bf16_f32 v25, v26, v27
	v_add_f32_e32 v26, 1.0, v28
	v_mul_f32_e32 v28, 0xbfb8aa3b, v22
	v_add_f32_e32 v27, 1.0, v29
	v_mul_f32_e32 v29, 0xbfb8aa3b, v23
	v_exp_f32_e32 v28, v28
	v_exp_f32_e32 v29, v29
	v_rcp_f32_e32 v26, v26
	v_rcp_f32_e32 v27, v27
	v_add_f32_e32 v28, 1.0, v28
	v_add_f32_e32 v29, 1.0, v29
	v_rcp_f32_e32 v28, v28
	v_rcp_f32_e32 v29, v29
	v_pk_mul_f32 v[20:21], v[20:21], v[26:27]
	s_nop 0
	v_pk_mul_f32 v[16:17], v[20:21], v[16:17]
	v_add_u32_e32 v20, 0xb0, v150
	v_cvt_pk_bf16_f32 v26, v16, v17
	v_pk_mul_f32 v[16:17], v[22:23], v[28:29]
	s_nop 0
	v_pk_mul_f32 v[16:17], v[16:17], v[18:19]
	v_mul_f32_e32 v18, 0xbfb8aa3b, v14
	v_cvt_pk_bf16_f32 v27, v16, v17
	v_mad_i64_i32 v[16:17], s[40:41], v36, s70, v[112:113]
	v_lshl_add_u64 v[16:17], v[16:17], 0, v[114:115]
	global_store_dwordx4 v[16:17], v[24:27], off
	v_mul_f32_e32 v16, 0xbfb8aa3b, v12
	v_mul_f32_e32 v17, 0xbfb8aa3b, v13
	v_exp_f32_e32 v16, v16
	v_exp_f32_e32 v17, v17
	v_mul_f32_e32 v19, 0xbfb8aa3b, v15
	v_exp_f32_e32 v18, v18
	v_exp_f32_e32 v19, v19
	v_add_f32_e32 v16, 1.0, v16
	v_add_f32_e32 v17, 1.0, v17
	v_rcp_f32_e32 v16, v16
	v_rcp_f32_e32 v17, v17
	v_add_f32_e32 v18, 1.0, v18
	v_add_f32_e32 v19, 1.0, v19
	v_rcp_f32_e32 v18, v18
	v_rcp_f32_e32 v19, v19
	v_pk_mul_f32 v[12:13], v[12:13], v[16:17]
	s_nop 0
	v_pk_mul_f32 v[8:9], v[12:13], v[8:9]
	v_pk_mul_f32 v[12:13], v[14:15], v[18:19]
	v_cvt_pk_bf16_f32 v8, v8, v9
	v_mul_f32_e32 v9, 0xbfb8aa3b, v4
	v_pk_mul_f32 v[10:11], v[12:13], v[10:11]
	v_exp_f32_e32 v12, v9
	v_mul_f32_e32 v9, 0xbfb8aa3b, v5
	v_exp_f32_e32 v13, v9
	v_cvt_pk_bf16_f32 v9, v10, v11
	v_add_f32_e32 v10, 1.0, v12
	v_mul_f32_e32 v12, 0xbfb8aa3b, v6
	v_add_f32_e32 v11, 1.0, v13
	v_mul_f32_e32 v13, 0xbfb8aa3b, v7
	v_exp_f32_e32 v12, v12
	v_exp_f32_e32 v13, v13
	v_rcp_f32_e32 v10, v10
	v_rcp_f32_e32 v11, v11
	v_add_f32_e32 v12, 1.0, v12
	v_add_f32_e32 v13, 1.0, v13
	v_rcp_f32_e32 v12, v12
	v_rcp_f32_e32 v13, v13
	v_pk_mul_f32 v[4:5], v[4:5], v[10:11]
	s_nop 0
	v_pk_mul_f32 v[0:1], v[4:5], v[0:1]
	s_nop 0
	v_cvt_pk_bf16_f32 v10, v0, v1
	v_pk_mul_f32 v[0:1], v[6:7], v[12:13]
	s_nop 0
	v_pk_mul_f32 v[0:1], v[0:1], v[2:3]
	s_nop 0
	v_cvt_pk_bf16_f32 v11, v0, v1
	v_mad_i64_i32 v[0:1], s[40:41], v20, s70, v[112:113]
	v_lshl_add_u64 v[0:1], v[0:1], 0, v[114:115]
	global_store_dwordx4 v[0:1], v[8:11], off
	s_cbranch_vccnz .LBB0_710
	s_andn2_b64 vcc, exec, s[6:7]
	s_cbranch_vccnz .LBB0_709
	s_barrier
	s_branch .LBB0_709

; #define PG8_STAGE(bufoff, gbase, voff) do { _Pragma("unroll") for (int _i = 0; _i < 2; ++_i) \
;         __builtin_amdgcn_global_load_lds((const unsigned*)((const char*)(gbase) + (voff)[_i]), (PG8_LAS unsigned*)(lds + (bufoff) + ldsw + _i * 8192), 16, 0, 0); } while (0)
; #define PG8_LDA(dst, b, h) do { _Pragma("unroll") for (int m = 0; m < 4; ++m) _Pragma("unroll") for (int k = 0; k < 2; ++k) dst[m][k] = *(const PG8_LAS bf16x8*)(lds + PG8_SA(b, h) + aoff + m * 2048 + k * 1024); } while (0)
; #define PG8_LDB(dst, b, h) do { _Pragma("unroll") for (int n = 0; n < 2; ++n) _Pragma("unroll") for (int k = 0; k < 2; ++k) dst[n][k] = *(const PG8_LAS bf16x8*)(lds + PG8_SB(b, h) + boff + n * 2048 + k * 1024); } while (0)
; #define PG8_SCHED __builtin_amdgcn_sched_barrier(0)
;     __host__ __device__ bool next(int i, Unit& u) const {
;         const long L = (long)i * G + c; if (L >= nwg) return false;
;         int wgid = (int)L; { const int q = nwg / NXCD, r = nwg % NXCD, xcd = wgid % NXCD, off = wgid / NXCD; wgid = (xcd < r ? xcd * (q + 1) : r * (q + 1) + (xcd - r) * q) + off; }
;         const int nig = WGM * nN, gid = wgid / nig, fm = gid * WGM, gsz = (nM - fm) < WGM ? (nM - fm) : WGM;
;         u.pm = fm + ((wgid % nig) % gsz); u.pn = (wgid % nig) / gsz; return true;
;     }
; template <class Epi, class Sched, bool ALIGN_EPI = false, bool SP2 = false>
; __device__ __forceinline__ void gemm_phase(PG8_LAS unsigned char* lds, const Gemm g, const Sched& S, const Epi& E) {
;     ...
;             PG8_LDB(B0, 0, 0); PG8_LDB(B1, 0, 1); PG8_SCHED; PG8_LDA(At, 0, 0); PG8_STAGE(PG8_SA(1, 1), a1 + hstep, voffA);
.LBB0_778:
	ds_read_b128 v[128:131], v203
	ds_read_b128 v[132:135], v203 offset:1024
	ds_read_b128 v[136:139], v203 offset:2048
	ds_read_b128 v[140:143], v203 offset:3072
	ds_read_b128 v[144:147], v204
	ds_read_b128 v[148:151], v204 offset:1024
	ds_read_b128 v[170:173], v204 offset:2048
	ds_read_b128 v[174:177], v204 offset:3072
	ds_read_b128 v[178:181], v205
	ds_read_b128 v[182:185], v205 offset:1024
	ds_read_b128 v[186:189], v205 offset:2048
	ds_read_b128 v[190:193], v205 offset:3072
	ds_read_b128 v[194:197], v205 offset:4096
	ds_read_b128 v[206:209], v205 offset:5120
	ds_read_b128 v[210:213], v205 offset:6144
	ds_read_b128 v[214:217], v205 offset:7168
	s_add_i32 s62, s62, 1
	s_mul_i32 s0, s62, s71
	s_mul_hi_u32 s1, s62, s3
	s_add_i32 s1, s1, s0
	s_mul_i32 s0, s62, s3
	s_add_u32 s0, s0, s2
	s_addc_u32 s1, s1, s57
	v_cmp_gt_i64_e32 vcc, s[0:1], v[168:169]
	v_cmp_lt_i64_e64 s[4:5], s[0:1], v[166:167]
	s_cbranch_vccnz .LBB0_784
	s_ashr_i32 s1, s0, 31
	s_lshr_b32 s1, s1, 29
	s_add_i32 s40, s0, s1
	s_and_b32 s1, s40, -8
	s_sub_i32 s41, s0, s1
	s_cmp_gt_i32 s41, -1
	s_mov_b64 s[0:1], -1
	s_cbranch_scc0 .LBB0_781
	s_lshl_b32 s46, s41, 7
	s_mov_b64 s[0:1], 0

; #define PG8_STAGE(bufoff, gbase, voff) do { _Pragma("unroll") for (int _i = 0; _i < 2; ++_i) \
;         __builtin_amdgcn_global_load_lds((const unsigned*)((const char*)(gbase) + (voff)[_i]), (PG8_LAS unsigned*)(lds + (bufoff) + ldsw + _i * 8192), 16, 0, 0); } while (0)
; #define PG8_LDA(dst, b, h) do { _Pragma("unroll") for (int m = 0; m < 4; ++m) _Pragma("unroll") for (int k = 0; k < 2; ++k) dst[m][k] = *(const PG8_LAS bf16x8*)(lds + PG8_SA(b, h) + aoff + m * 2048 + k * 1024); } while (0)
; #define PG8_LDB(dst, b, h) do { _Pragma("unroll") for (int n = 0; n < 2; ++n) _Pragma("unroll") for (int k = 0; k < 2; ++k) dst[n][k] = *(const PG8_LAS bf16x8*)(lds + PG8_SB(b, h) + boff + n * 2048 + k * 1024); } while (0)
; #define PG8_WAIT_V(n) asm volatile("s_waitcnt vmcnt(" #n ")" ::: "memory")
; #define PG8_WAIT_L(n) asm volatile("s_waitcnt lgkmcnt(" #n ")" ::: "memory")
; #define PG8_BAR __builtin_amdgcn_s_barrier()
; #define PG8_SCHED __builtin_amdgcn_sched_barrier(0)
; template <class Epi, class Sched, bool ALIGN_EPI = false, bool SP2 = false>
; __device__ __forceinline__ void gemm_phase(PG8_LAS unsigned char* lds, const Gemm g, const Sched& S, const Epi& E) {
;     ...
;         const char* nA = has_next ? (const char*)g.A + (size_t)nxt.pm * tstep : cA; const char* nB = has_next ? (const char*)g.Bt + (size_t)nxt.pn * tstep : cB;
;         for (int t = 0; t < nt; t += 2) {
;             const bool last = (t == nt - 2);
;             const char* a1 = cA + (size_t)(t + 1) * kstep;
;             const char* a2 = last ? nA : cA + (size_t)(t + 2) * kstep; const char* b2 = last ? nB : cB + (size_t)(t + 2) * kstep;
;             const char* a3 = a2 + kstep; const char* b3 = b2 + kstep;
;             if (last && has_next) S.a_ready(nxt);
;             if constexpr (SP2) {
;             PG8_LDB(B0, 0, 0); PG8_LDB(B1, 0, 1); PG8_SCHED; PG8_LDA(At, 0, 0); PG8_STAGE(PG8_SA(1, 1), a1 + hstep, voffA);
;             PG8_WAIT_V(8); PG8_WAIT_L(0); PG8_BAR; PG8_MMA(0, 0, At, B0); PG8_MMA(0, 1, At, B1); PG8_BAR; PG8_SCHED;
;             PG8_LDA(At, 0, 1); PG8_STAGE(PG8_SB(0, 0), b2, voffB); PG8_STAGE(PG8_SB(0, 1), b2 + hstep, voffB); PG8_STAGE(PG8_SA(0, 0), a2, voffA);
;             PG8_WAIT_V(8); PG8_WAIT_L(0); PG8_BAR; PG8_MMA(1, 0, At, B0); PG8_MMA(1, 1, At, B1); PG8_BAR; PG8_SCHED;
.LBB0_788:
	s_add_u32 s42, s42, 0xb0080
	s_addc_u32 s43, s43, 0
	s_add_u32 s86, s44, 0x100
	s_addc_u32 s87, s45, 0
	s_mov_b32 s90, -2
	s_waitcnt lgkmcnt(0)
	s_waitcnt vmcnt(0)
	s_add_u32 s33, s42, 0xfff50080
	s_addc_u32 s34, s43, -1
	s_cmp_eq_u32 s90, 40
	s_cselect_b32 s47, s5, s34
	s_cselect_b32 s46, s4, s33
	s_cselect_b32 s45, s41, s87
	s_cselect_b32 s44, s40, s86
	s_add_i32 m0, s58, 0xc000
	global_load_lds_dwordx4 v162, s[42:43]
	s_add_i32 m0, s58, 0xe000
	s_nop 0
	global_load_lds_dwordx4 v164, s[42:43]
	s_waitcnt vmcnt(8)
	s_waitcnt lgkmcnt(0)
	s_barrier
	s_setprio 1
	s_waitcnt lgkmcnt(0)
	v_mfma_f32_16x16x32_bf16 v[124:127], v[128:131], v[178:181], 0
	v_mfma_f32_16x16x32_bf16 v[120:123], v[136:139], v[178:181], 0
	v_mfma_f32_16x16x32_bf16 v[116:119], v[128:131], v[186:189], 0
	v_mfma_f32_16x16x32_bf16 v[112:115], v[136:139], v[186:189], 0
	v_mfma_f32_16x16x32_bf16 v[108:111], v[128:131], v[194:197], 0
	v_mfma_f32_16x16x32_bf16 v[104:107], v[136:139], v[194:197], 0
	v_mfma_f32_16x16x32_bf16 v[100:103], v[128:131], v[210:213], 0
	v_mfma_f32_16x16x32_bf16 v[96:99], v[136:139], v[210:213], 0
	v_mfma_f32_16x16x32_bf16 v[124:127], v[132:135], v[182:185], v[124:127]
	v_mfma_f32_16x16x32_bf16 v[120:123], v[140:143], v[182:185], v[120:123]
	v_mfma_f32_16x16x32_bf16 v[116:119], v[132:135], v[190:193], v[116:119]
	v_mfma_f32_16x16x32_bf16 v[112:115], v[140:143], v[190:193], v[112:115]
	v_mfma_f32_16x16x32_bf16 v[108:111], v[132:135], v[206:209], v[108:111]
	v_mfma_f32_16x16x32_bf16 v[104:107], v[140:143], v[206:209], v[104:107]
	v_mfma_f32_16x16x32_bf16 v[100:103], v[132:135], v[214:217], v[100:103]
	v_mfma_f32_16x16x32_bf16 v[96:99], v[140:143], v[214:217], v[96:99]
	s_setprio 0
	s_setprio 1
	v_mfma_f32_16x16x32_bf16 v[68:71], v[144:147], v[178:181], 0
	v_mfma_f32_16x16x32_bf16 v[64:67], v[170:173], v[178:181], 0
	v_mfma_f32_16x16x32_bf16 v[60:63], v[144:147], v[186:189], 0
	v_mfma_f32_16x16x32_bf16 v[52:55], v[170:173], v[186:189], 0
	v_mfma_f32_16x16x32_bf16 v[44:47], v[144:147], v[194:197], 0
	v_mfma_f32_16x16x32_bf16 v[40:43], v[170:173], v[194:197], 0
	v_mfma_f32_16x16x32_bf16 v[36:39], v[144:147], v[210:213], 0
	v_mfma_f32_16x16x32_bf16 v[32:35], v[170:173], v[210:213], 0
	v_mfma_f32_16x16x32_bf16 v[68:71], v[148:151], v[182:185], v[68:71]
	v_mfma_f32_16x16x32_bf16 v[64:67], v[174:177], v[182:185], v[64:67]
	v_mfma_f32_16x16x32_bf16 v[60:63], v[148:151], v[190:193], v[60:63]
	v_mfma_f32_16x16x32_bf16 v[52:55], v[174:177], v[190:193], v[52:55]
	v_mfma_f32_16x16x32_bf16 v[44:47], v[148:151], v[206:209], v[44:47]
	v_mfma_f32_16x16x32_bf16 v[40:43], v[174:177], v[206:209], v[40:43]
	v_mfma_f32_16x16x32_bf16 v[36:39], v[148:151], v[214:217], v[36:39]
	v_mfma_f32_16x16x32_bf16 v[32:35], v[174:177], v[214:217], v[32:35]
	s_setprio 0
	s_barrier
	s_add_i32 s33, s74, s56
	s_add_u32 s64, s44, s12
	s_addc_u32 s65, s45, s13
	s_mov_b32 m0, s33
	ds_read_b128 v[178:181], v205 offset:16384
	ds_read_b128 v[182:185], v205 offset:17408
	ds_read_b128 v[186:189], v205 offset:18432
	ds_read_b128 v[190:193], v205 offset:19456
	ds_read_b128 v[194:197], v205 offset:20480
	ds_read_b128 v[206:209], v205 offset:21504
	ds_read_b128 v[210:213], v205 offset:22528
	ds_read_b128 v[214:217], v205 offset:23552
	global_load_lds_dwordx4 v156, s[44:45]
	s_add_i32 m0, s33, 0x2000
	s_add_u32 s92, s44, 0xb0000
	s_addc_u32 s93, s45, 0
	s_add_i32 s33, s75, s56
	global_load_lds_dwordx4 v160, s[44:45]
	s_mov_b32 m0, s33
	s_add_u32 s84, s46, s12
	s_addc_u32 s85, s47, s13
	global_load_lds_dwordx4 v156, s[92:93]
	s_add_i32 m0, s33, 0x2000
	s_nop 0
	global_load_lds_dwordx4 v160, s[92:93]
	s_mov_b32 m0, s58
	s_nop 0
	global_load_lds_dwordx4 v154, s[46:47]
	s_mov_b32 m0, s59
	s_nop 0
	global_load_lds_dwordx4 v158, s[46:47]
	s_waitcnt vmcnt(8)
	s_waitcnt lgkmcnt(0)
	s_barrier
	s_setprio 1
	s_waitcnt lgkmcnt(0)
	v_mfma_f32_16x16x32_bf16 v[92:95], v[128:131], v[178:181], 0
	v_mfma_f32_16x16x32_bf16 v[88:91], v[136:139], v[178:181], 0
	v_mfma_f32_16x16x32_bf16 v[84:87], v[128:131], v[186:189], 0
	v_mfma_f32_16x16x32_bf16 v[80:83], v[136:139], v[186:189], 0
	v_mfma_f32_16x16x32_bf16 v[76:79], v[128:131], v[194:197], 0
	v_mfma_f32_16x16x32_bf16 v[72:75], v[136:139], v[194:197], 0
	v_mfma_f32_16x16x32_bf16 v[56:59], v[128:131], v[210:213], 0
	v_mfma_f32_16x16x32_bf16 v[48:51], v[136:139], v[210:213], 0
	v_mfma_f32_16x16x32_bf16 v[92:95], v[132:135], v[182:185], v[92:95]
	v_mfma_f32_16x16x32_bf16 v[88:91], v[140:143], v[182:185], v[88:91]
	v_mfma_f32_16x16x32_bf16 v[84:87], v[132:135], v[190:193], v[84:87]
	v_mfma_f32_16x16x32_bf16 v[80:83], v[140:143], v[190:193], v[80:83]
	v_mfma_f32_16x16x32_bf16 v[76:79], v[132:135], v[206:209], v[76:79]
	v_mfma_f32_16x16x32_bf16 v[72:75], v[140:143], v[206:209], v[72:75]
	v_mfma_f32_16x16x32_bf16 v[56:59], v[132:135], v[214:217], v[56:59]
	v_mfma_f32_16x16x32_bf16 v[48:51], v[140:143], v[214:217], v[48:51]
	s_setprio 0
	s_setprio 1
	v_mfma_f32_16x16x32_bf16 v[28:31], v[144:147], v[178:181], 0
	v_mfma_f32_16x16x32_bf16 v[24:27], v[170:173], v[178:181], 0
	v_mfma_f32_16x16x32_bf16 v[20:23], v[144:147], v[186:189], 0
	v_mfma_f32_16x16x32_bf16 v[16:19], v[170:173], v[186:189], 0
	v_mfma_f32_16x16x32_bf16 v[12:15], v[144:147], v[194:197], 0
	v_mfma_f32_16x16x32_bf16 v[8:11], v[170:173], v[194:197], 0
	v_mfma_f32_16x16x32_bf16 v[4:7], v[144:147], v[210:213], 0
	v_mfma_f32_16x16x32_bf16 v[0:3], v[170:173], v[210:213], 0
	v_mfma_f32_16x16x32_bf16 v[28:31], v[148:151], v[182:185], v[28:31]
	v_mfma_f32_16x16x32_bf16 v[24:27], v[174:177], v[182:185], v[24:27]
	v_mfma_f32_16x16x32_bf16 v[20:23], v[148:151], v[190:193], v[20:23]
	v_mfma_f32_16x16x32_bf16 v[16:19], v[174:177], v[190:193], v[16:19]
	v_mfma_f32_16x16x32_bf16 v[12:15], v[148:151], v[206:209], v[12:15]
	v_mfma_f32_16x16x32_bf16 v[8:11], v[174:177], v[206:209], v[8:11]
	v_mfma_f32_16x16x32_bf16 v[4:7], v[148:151], v[214:217], v[4:7]
	v_mfma_f32_16x16x32_bf16 v[0:3], v[174:177], v[214:217], v[0:3]
	s_setprio 0
	s_barrier
; #define PG8_STAGE(bufoff, gbase, voff) do { _Pragma("unroll") for (int _i = 0; _i < 2; ++_i) \
;         __builtin_amdgcn_global_load_lds((const unsigned*)((const char*)(gbase) + (voff)[_i]), (PG8_LAS unsigned*)(lds + (bufoff) + ldsw + _i * 8192), 16, 0, 0); } while (0)
; #define PG8_LDA(dst, b, h) do { _Pragma("unroll") for (int m = 0; m < 4; ++m) _Pragma("unroll") for (int k = 0; k < 2; ++k) dst[m][k] = *(const PG8_LAS bf16x8*)(lds + PG8_SA(b, h) + aoff + m * 2048 + k * 1024); } while (0)
; #define PG8_LDB(dst, b, h) do { _Pragma("unroll") for (int n = 0; n < 2; ++n) _Pragma("unroll") for (int k = 0; k < 2; ++k) dst[n][k] = *(const PG8_LAS bf16x8*)(lds + PG8_SB(b, h) + boff + n * 2048 + k * 1024); } while (0)
; #define PG8_MMA(ai, bj, At, Bt) do { __builtin_amdgcn_s_setprio(1); _Pragma("unroll") for (int m = 0; m < 4; ++m) _Pragma("unroll") for (int n = 0; n < 2; ++n) _Pragma("unroll") for (int k = 0; k < 2; ++k) \
;         acc[ai][bj][m][n] = __builtin_amdgcn_mfma_f32_16x16x32_bf16(Bt[n][k], At[m][k], acc[ai][bj][m][n], 0, 0, 0); __builtin_amdgcn_s_setprio(0); } while (0)
; #define PG8_WAIT_V(n) asm volatile("s_waitcnt vmcnt(" #n ")" ::: "memory")
; #define PG8_WAIT_L(n) asm volatile("s_waitcnt lgkmcnt(" #n ")" ::: "memory")
; #define PG8_BAR __builtin_amdgcn_s_barrier()
; #define PG8_SCHED __builtin_amdgcn_sched_barrier(0)
; template <class Epi, class Sched, bool ALIGN_EPI = false, bool SP2 = false>
; __device__ __forceinline__ void gemm_phase(PG8_LAS unsigned char* lds, const Gemm g, const Sched& S, const Epi& E) {
;     ...
;             PG8_LDB(B0, 1, 0); PG8_LDB(B1, 1, 1); PG8_SCHED; PG8_LDA(At, 1, 0); PG8_STAGE(PG8_SA(0, 1), a2 + hstep, voffA);
;             PG8_WAIT_V(8); PG8_WAIT_L(0); PG8_BAR; PG8_MMA(0, 0, At, B0); PG8_MMA(0, 1, At, B1); PG8_BAR; PG8_SCHED;
;             PG8_LDA(At, 1, 1); PG8_STAGE(PG8_SB(1, 0), b3, voffB); PG8_STAGE(PG8_SB(1, 1), b3 + hstep, voffB); PG8_STAGE(PG8_SA(1, 0), a3, voffA);
;             PG8_WAIT_V(8); PG8_WAIT_L(0); PG8_BAR; PG8_MMA(1, 0, At, B0); PG8_MMA(1, 1, At, B1); PG8_BAR; PG8_SCHED;
	s_add_i32 s33, 0, 0x18000
	s_add_i32 s34, 0, 0x1c000
	v_add_u32_e32 v140, s33, v201
	v_add_u32_e32 v153, s34, v201
	ds_read_b128 v[128:131], v140
	ds_read_b128 v[132:135], v140 offset:1024
	ds_read_b128 v[136:139], v140 offset:2048
	ds_read_b128 v[140:143], v140 offset:3072
	ds_read_b128 v[144:147], v153
	ds_read_b128 v[148:151], v153 offset:1024
	ds_read_b128 v[170:173], v153 offset:2048
	ds_read_b128 v[174:177], v153 offset:3072
	s_add_u32 s46, s46, 0xb0000
	s_addc_u32 s47, s47, 0
	s_mov_b32 m0, s60
	ds_read_b128 v[178:181], v205 offset:32768
	ds_read_b128 v[182:185], v205 offset:33792
	ds_read_b128 v[186:189], v205 offset:34816
	ds_read_b128 v[190:193], v205 offset:35840
	ds_read_b128 v[194:197], v205 offset:36864
	ds_read_b128 v[206:209], v205 offset:37888
	ds_read_b128 v[210:213], v205 offset:38912
	ds_read_b128 v[214:217], v205 offset:39936
	global_load_lds_dwordx4 v154, s[46:47]
	s_mov_b32 m0, s61
	s_nop 0
	global_load_lds_dwordx4 v158, s[46:47]
	s_waitcnt vmcnt(8)
	s_waitcnt lgkmcnt(0)
	s_barrier
	s_setprio 1
	s_waitcnt lgkmcnt(0)
	v_mfma_f32_16x16x32_bf16 v[124:127], v[128:131], v[178:181], v[124:127]
	v_mfma_f32_16x16x32_bf16 v[120:123], v[136:139], v[178:181], v[120:123]
	v_mfma_f32_16x16x32_bf16 v[116:119], v[128:131], v[186:189], v[116:119]
	v_mfma_f32_16x16x32_bf16 v[112:115], v[136:139], v[186:189], v[112:115]
	v_mfma_f32_16x16x32_bf16 v[108:111], v[128:131], v[194:197], v[108:111]
	v_mfma_f32_16x16x32_bf16 v[104:107], v[136:139], v[194:197], v[104:107]
	v_mfma_f32_16x16x32_bf16 v[100:103], v[128:131], v[210:213], v[100:103]
	v_mfma_f32_16x16x32_bf16 v[96:99], v[136:139], v[210:213], v[96:99]
	v_mfma_f32_16x16x32_bf16 v[124:127], v[132:135], v[182:185], v[124:127]
	v_mfma_f32_16x16x32_bf16 v[120:123], v[140:143], v[182:185], v[120:123]
	v_mfma_f32_16x16x32_bf16 v[116:119], v[132:135], v[190:193], v[116:119]
	v_mfma_f32_16x16x32_bf16 v[112:115], v[140:143], v[190:193], v[112:115]
	v_mfma_f32_16x16x32_bf16 v[108:111], v[132:135], v[206:209], v[108:111]
	v_mfma_f32_16x16x32_bf16 v[104:107], v[140:143], v[206:209], v[104:107]
	v_mfma_f32_16x16x32_bf16 v[100:103], v[132:135], v[214:217], v[100:103]
	v_mfma_f32_16x16x32_bf16 v[96:99], v[140:143], v[214:217], v[96:99]
	s_setprio 0
	s_setprio 1
	v_mfma_f32_16x16x32_bf16 v[68:71], v[144:147], v[178:181], v[68:71]
	v_mfma_f32_16x16x32_bf16 v[64:67], v[170:173], v[178:181], v[64:67]
	v_mfma_f32_16x16x32_bf16 v[60:63], v[144:147], v[186:189], v[60:63]
	v_mfma_f32_16x16x32_bf16 v[52:55], v[170:173], v[186:189], v[52:55]
	v_mfma_f32_16x16x32_bf16 v[44:47], v[144:147], v[194:197], v[44:47]
	v_mfma_f32_16x16x32_bf16 v[40:43], v[170:173], v[194:197], v[40:43]
	v_mfma_f32_16x16x32_bf16 v[36:39], v[144:147], v[210:213], v[36:39]
	v_mfma_f32_16x16x32_bf16 v[32:35], v[170:173], v[210:213], v[32:35]
	v_mfma_f32_16x16x32_bf16 v[68:71], v[148:151], v[182:185], v[68:71]
	v_mfma_f32_16x16x32_bf16 v[64:67], v[174:177], v[182:185], v[64:67]
	v_mfma_f32_16x16x32_bf16 v[60:63], v[148:151], v[190:193], v[60:63]
	v_mfma_f32_16x16x32_bf16 v[52:55], v[174:177], v[190:193], v[52:55]
	v_mfma_f32_16x16x32_bf16 v[44:47], v[148:151], v[206:209], v[44:47]
	v_mfma_f32_16x16x32_bf16 v[40:43], v[174:177], v[206:209], v[40:43]
	v_mfma_f32_16x16x32_bf16 v[36:39], v[148:151], v[214:217], v[36:39]
	v_mfma_f32_16x16x32_bf16 v[32:35], v[174:177], v[214:217], v[32:35]
	s_setprio 0
	s_barrier
	s_add_i32 s33, s33, s56
	s_mov_b32 m0, s33
	ds_read_b128 v[178:181], v205 offset:49152
	ds_read_b128 v[182:185], v205 offset:50176
	ds_read_b128 v[186:189], v205 offset:51200
	ds_read_b128 v[190:193], v205 offset:52224
	ds_read_b128 v[194:197], v205 offset:53248
	ds_read_b128 v[206:209], v205 offset:54272
	ds_read_b128 v[210:213], v205 offset:55296
	ds_read_b128 v[214:217], v205 offset:56320
	global_load_lds_dwordx4 v156, s[64:65]
	s_add_i32 m0, s33, 0x2000
	s_add_u32 s44, s44, 0xb0080
	s_addc_u32 s45, s45, 0
	s_add_i32 s33, s34, s56
	global_load_lds_dwordx4 v160, s[64:65]
	s_mov_b32 m0, s33
	s_nop 0
	global_load_lds_dwordx4 v156, s[44:45]
	s_add_i32 m0, s33, 0x2000
	s_nop 0
	global_load_lds_dwordx4 v160, s[44:45]
	s_mov_b32 m0, s72
	s_nop 0
	global_load_lds_dwordx4 v154, s[84:85]
	s_mov_b32 m0, s73
	s_nop 0
	global_load_lds_dwordx4 v158, s[84:85]
	s_waitcnt vmcnt(8)
	s_waitcnt lgkmcnt(0)
	s_barrier
	s_setprio 1
	s_waitcnt lgkmcnt(0)
	v_mfma_f32_16x16x32_bf16 v[92:95], v[128:131], v[178:181], v[92:95]
	v_mfma_f32_16x16x32_bf16 v[88:91], v[136:139], v[178:181], v[88:91]
	v_mfma_f32_16x16x32_bf16 v[84:87], v[128:131], v[186:189], v[84:87]
	v_mfma_f32_16x16x32_bf16 v[80:83], v[136:139], v[186:189], v[80:83]
	v_mfma_f32_16x16x32_bf16 v[76:79], v[128:131], v[194:197], v[76:79]
	v_mfma_f32_16x16x32_bf16 v[72:75], v[136:139], v[194:197], v[72:75]
	v_mfma_f32_16x16x32_bf16 v[56:59], v[128:131], v[210:213], v[56:59]
	v_mfma_f32_16x16x32_bf16 v[48:51], v[136:139], v[210:213], v[48:51]
	v_mfma_f32_16x16x32_bf16 v[92:95], v[132:135], v[182:185], v[92:95]
	v_mfma_f32_16x16x32_bf16 v[88:91], v[140:143], v[182:185], v[88:91]
	v_mfma_f32_16x16x32_bf16 v[84:87], v[132:135], v[190:193], v[84:87]
	v_mfma_f32_16x16x32_bf16 v[80:83], v[140:143], v[190:193], v[80:83]
	v_mfma_f32_16x16x32_bf16 v[76:79], v[132:135], v[206:209], v[76:79]
	v_mfma_f32_16x16x32_bf16 v[72:75], v[140:143], v[206:209], v[72:75]
	v_mfma_f32_16x16x32_bf16 v[56:59], v[132:135], v[214:217], v[56:59]
	v_mfma_f32_16x16x32_bf16 v[48:51], v[140:143], v[214:217], v[48:51]
	s_setprio 0
	s_setprio 1
	v_mfma_f32_16x16x32_bf16 v[28:31], v[144:147], v[178:181], v[28:31]
	v_mfma_f32_16x16x32_bf16 v[24:27], v[170:173], v[178:181], v[24:27]
	v_mfma_f32_16x16x32_bf16 v[20:23], v[144:147], v[186:189], v[20:23]
	v_mfma_f32_16x16x32_bf16 v[16:19], v[170:173], v[186:189], v[16:19]
	v_mfma_f32_16x16x32_bf16 v[12:15], v[144:147], v[194:197], v[12:15]
	v_mfma_f32_16x16x32_bf16 v[8:11], v[170:173], v[194:197], v[8:11]
	v_mfma_f32_16x16x32_bf16 v[4:7], v[144:147], v[210:213], v[4:7]
	v_mfma_f32_16x16x32_bf16 v[0:3], v[170:173], v[210:213], v[0:3]
	v_mfma_f32_16x16x32_bf16 v[28:31], v[148:151], v[182:185], v[28:31]
	v_mfma_f32_16x16x32_bf16 v[24:27], v[174:177], v[182:185], v[24:27]
	v_mfma_f32_16x16x32_bf16 v[20:23], v[148:151], v[190:193], v[20:23]
	v_mfma_f32_16x16x32_bf16 v[16:19], v[174:177], v[190:193], v[16:19]
	v_mfma_f32_16x16x32_bf16 v[12:15], v[148:151], v[206:209], v[12:15]
	v_mfma_f32_16x16x32_bf16 v[8:11], v[174:177], v[206:209], v[8:11]
	v_mfma_f32_16x16x32_bf16 v[4:7], v[148:151], v[214:217], v[4:7]
	v_mfma_f32_16x16x32_bf16 v[0:3], v[174:177], v[214:217], v[0:3]
	s_setprio 0
	s_barrier
	s_add_i32 s90, s90, 2
	s_add_u32 s42, s42, 0x100
	s_addc_u32 s43, s43, 0
	s_add_u32 s86, s86, 0x100
	s_addc_u32 s87, s87, 0
	s_cmp_gt_u32 s90, 41

; #define PG8_STAGE(bufoff, gbase, voff) do { _Pragma("unroll") for (int _i = 0; _i < 2; ++_i) \
;         __builtin_amdgcn_global_load_lds((const unsigned*)((const char*)(gbase) + (voff)[_i]), (PG8_LAS unsigned*)(lds + (bufoff) + ldsw + _i * 8192), 16, 0, 0); } while (0)
; #define PG8_WAIT_V(n) asm volatile("s_waitcnt vmcnt(" #n ")" ::: "memory")
; #define PG8_BAR __builtin_amdgcn_s_barrier()
; template <class Epi, class Sched, bool ALIGN_EPI = false, bool SP2 = false>
; __device__ __forceinline__ void gemm_phase(PG8_LAS unsigned char* lds, const Gemm g, const Sched& S, const Epi& E) {
;     ...
;     for (int i = 0; i < 2; ++i) { int R, C; stage_rc(tid * 16 + i * 8192, R, C); const int Rb = Epi::PERM ? ((R & ~31) + perm32(R & 31)) : R;
;         voffA[i] = (unsigned)(R * K + C) * 2u; voffB[i] = (unsigned)(Rb * K + C) * 2u; }
;     const size_t kstep = (size_t)(BK * 2);
;     const size_t hstep = (size_t)HALF * K * 2;
;     const size_t tstep = 2 * hstep;
;     const unsigned ldsw = (unsigned)wid * 1024u;
;     const int aoff = lds_byte(wr * 64 + fr, fq * 8), boff = lds_byte(wc * 32 + fr, fq * 8);
;     ...
;         PG8_STAGE(PG8_SB(1, 0), cB + kstep, voffB); PG8_STAGE(PG8_SA(1, 0), cA + kstep, voffA); PG8_STAGE(PG8_SB(1, 1), cB + hstep + kstep, voffB);
;         PG8_WAIT_V(6); PG8_BAR;
.LBB0_909:
	s_add_u32 s10, s28, 0xfa00000
	v_readlane_b32 s76, v255, 4
	s_addc_u32 s11, s29, 0
	s_ashr_i32 s73, s3, 31
	s_ashr_i32 s74, s2, 31
	v_readlane_b32 s88, v255, 16
	v_readlane_b32 s89, v255, 17
	s_cmp_lg_u64 s[88:89], 0
	s_cselect_b64 s[12:13], -1, 0
	s_lshl_b32 s1, s1, 5
	s_mov_b64 s[20:21], 0x80
	s_and_b32 s1, s1, 0x60
	s_add_i32 m0, s53, 0x18000
	v_lshl_add_u64 v[6:7], v[6:7], 0, s[20:21]
	s_lshl_b32 s5, s0, 13
	s_lshl_b32 s23, s1, 7
	s_waitcnt vmcnt(2)
	s_barrier
	global_load_lds_dwordx4 v[6:7], off
	v_lshl_add_u64 v[4:5], v[4:5], 0, s[20:21]
	s_add_i32 m0, s53, 0x1a000
	s_add_i32 s75, s53, 0x8000
	s_add_i32 s76, s53, 0xa000
	global_load_lds_dwordx4 v[4:5], off
	v_lshl_add_u64 v[0:1], v[0:1], 0, s[20:21]
	s_mov_b32 m0, s75
	s_add_u32 s24, s56, 0x40080
	global_load_lds_dwordx4 v[0:1], off
	v_lshl_add_u64 v[0:1], v[2:3], 0, s[20:21]
	s_mov_b32 m0, s76
	s_addc_u32 s25, s57, 0
	global_load_lds_dwordx4 v[0:1], off
	s_add_i32 m0, s53, 0x1c000
	v_lshl_add_u64 v[0:1], s[24:25], 0, v[130:131]
	global_load_lds_dwordx4 v[0:1], off
	v_lshl_add_u64 v[0:1], s[24:25], 0, v[134:135]
	s_add_i32 m0, s53, 0x1e000
	v_lshlrev_b32_e32 v2, 6, v152
	global_load_lds_dwordx4 v[0:1], off
	v_and_b32_e32 v0, 15, v152
	v_lshlrev_b32_e32 v1, 1, v11
	s_movk_i32 s24, 0x3c0
	v_lshlrev_b32_e32 v3, 2, v152
	v_and_or_b32 v2, v2, s24, v1
	v_and_b32_e32 v3, 32, v3
	v_lshl_or_b32 v155, s0, 6, v0
	v_lshl_or_b32 v0, v0, 6, v1
	v_lshlrev_b32_e32 v1, 8, v152
	v_bitop3_b32 v157, s23, v2, v3 bitop3:0xf6
	v_and_b32_e32 v1, 0x38000, v1
	v_lshlrev_b32_e32 v2, 11, v10
	v_or3_b32 v1, v8, v1, v2
	s_waitcnt vmcnt(0)
	v_add_u32_e32 v136, v1, v9
	v_lshlrev_b32_e32 v1, 4, v12
	v_readlane_b32 s78, v255, 6
	v_readlane_b32 s79, v255, 7
	s_waitcnt vmcnt(6)
	s_cmpk_lt_u32 s22, 0x100
	v_and_b32_e32 v1, 0x78000, v1
	v_readlane_b32 s77, v255, 5
	v_bitop3_b32 v0, v0, s5, v3 bitop3:0xde
	s_cselect_b64 s[22:23], -1, 0
	v_or3_b32 v1, v8, v1, v2
	s_add_i32 s78, 0, 0x10000
	s_add_i32 s79, 0, 0x14000
	v_or_b32_e32 v158, s1, v11
	v_mov_b32_e32 v137, v131
	v_add_u32_e32 v138, v1, v9
	v_mov_b32_e32 v139, v131
	v_mov_b64_e32 v[140:141], 0xc00
	v_mov_b64_e32 v[142:143], 0xbff
	s_movk_i32 s77, 0x181
	v_add_u32_e32 v159, s78, v157
	v_add_u32_e32 v160, s79, v157
	v_add_u32_e32 v161, 0, v0
	s_mov_b64 s[24:25], 0x1000000
	s_mov_b32 s64, 0x1000000
	s_mov_b64 s[36:37], 0x1200000
	s_mov_b32 s65, 0x1200000
	s_mov_b64 s[38:39], 0x1400000
	s_mov_b32 s66, 0x1400000
	s_mov_b64 s[40:41], 0x1600000
	s_mov_b32 s67, 0x1600000
	v_readlane_b32 s80, v255, 8
	v_readlane_b32 s81, v255, 9
	v_readlane_b32 s82, v255, 10
	v_readlane_b32 s83, v255, 11
	v_readlane_b32 s84, v255, 12
	v_readlane_b32 s85, v255, 13
	v_readlane_b32 s86, v255, 14
	v_readlane_b32 s87, v255, 15
	v_readlane_b32 s90, v255, 18
	v_readlane_b32 s91, v255, 19
	v_readlane_b32 s92, v255, 16
	v_readlane_b32 s93, v255, 17
	s_nop 2
	v_lshl_add_u32 v240, s4, 8, v155
	v_ashrrev_i32_e32 v241, 31, v240
	v_lshl_add_u64 v[238:239], v[240:241], 2, s[92:93]
	global_load_dword v230, v[238:239], off
	global_load_dword v231, v[238:239], off offset:64
	global_load_dword v232, v[238:239], off offset:128
	global_load_dword v233, v[238:239], off offset:192
	global_load_dword v234, v[238:239], off offset:512
	global_load_dword v235, v[238:239], off offset:576
	global_load_dword v236, v[238:239], off offset:640
	global_load_dword v237, v[238:239], off offset:704
	s_barrier
	s_mov_b32 s32, 0
	s_branch .LBB0_912

; #define PG8_STAGE(bufoff, gbase, voff) do { _Pragma("unroll") for (int _i = 0; _i < 2; ++_i) \
;         __builtin_amdgcn_global_load_lds((const unsigned*)((const char*)(gbase) + (voff)[_i]), (PG8_LAS unsigned*)(lds + (bufoff) + ldsw + _i * 8192), 16, 0, 0); } while (0)
; #define PG8_LDA(dst, b, h) do { _Pragma("unroll") for (int m = 0; m < 4; ++m) _Pragma("unroll") for (int k = 0; k < 2; ++k) dst[m][k] = *(const PG8_LAS bf16x8*)(lds + PG8_SA(b, h) + aoff + m * 2048 + k * 1024); } while (0)
; #define PG8_LDB(dst, b, h) do { _Pragma("unroll") for (int n = 0; n < 2; ++n) _Pragma("unroll") for (int k = 0; k < 2; ++k) dst[n][k] = *(const PG8_LAS bf16x8*)(lds + PG8_SB(b, h) + boff + n * 2048 + k * 1024); } while (0)
; #define PG8_MMA(ai, bj, At, Bt) do { __builtin_amdgcn_s_setprio(1); _Pragma("unroll") for (int m = 0; m < 4; ++m) _Pragma("unroll") for (int n = 0; n < 2; ++n) _Pragma("unroll") for (int k = 0; k < 2; ++k) \
;         acc[ai][bj][m][n] = __builtin_amdgcn_mfma_f32_16x16x32_bf16(Bt[n][k], At[m][k], acc[ai][bj][m][n], 0, 0, 0); __builtin_amdgcn_s_setprio(0); } while (0)
; #define PG8_WAIT_V(n) asm volatile("s_waitcnt vmcnt(" #n ")" ::: "memory")
; #define PG8_WAIT_L(n) asm volatile("s_waitcnt lgkmcnt(" #n ")" ::: "memory")
; #define PG8_BAR __builtin_amdgcn_s_barrier()
; #define PG8_SCHED __builtin_amdgcn_sched_barrier(0)
;     __host__ __device__ bool next(int i, Unit& u) const {
;         const long L = (long)i * G + c; if (L >= nwg) return false;
;         int wgid = (int)L; { const int q = nwg / NXCD, r = nwg % NXCD, xcd = wgid % NXCD, off = wgid / NXCD; wgid = (xcd < r ? xcd * (q + 1) : r * (q + 1) + (xcd - r) * q) + off; }
;         const int nig = WGM * nN, gid = wgid / nig, fm = gid * WGM, gsz = (nM - fm) < WGM ? (nM - fm) : WGM;
;         u.pm = fm + ((wgid % nig) % gsz); u.pn = (wgid % nig) / gsz; return true;
;     }
; template <class Epi, class Sched, bool ALIGN_EPI = false, bool SP2 = false>
; __device__ __forceinline__ void gemm_phase(PG8_LAS unsigned char* lds, const Gemm g, const Sched& S, const Epi& E) {
;     ...
;             PG8_LDB(B0, 0, 0); PG8_LDB(B1, 0, 1); PG8_SCHED; PG8_LDA(At, 0, 0); PG8_STAGE(PG8_SA(1, 1), a1 + hstep, voffA);
;             PG8_WAIT_V(8); PG8_WAIT_L(0); PG8_BAR; PG8_MMA(0, 0, At, B0); PG8_MMA(0, 1, At, B1); PG8_BAR; PG8_SCHED;
.LBB0_912:
	ds_read_b128 v[144:147], v159
	ds_read_b128 v[148:151], v159 offset:1024
	ds_read_b128 v[162:165], v159 offset:2048
	ds_read_b128 v[166:169], v159 offset:3072
	ds_read_b128 v[170:173], v160
	ds_read_b128 v[174:177], v160 offset:1024
	ds_read_b128 v[178:181], v160 offset:2048
	ds_read_b128 v[182:185], v160 offset:3072
	ds_read_b128 v[186:189], v161
	ds_read_b128 v[190:193], v161 offset:1024
	ds_read_b128 v[194:197], v161 offset:2048
	ds_read_b128 v[198:201], v161 offset:3072
	ds_read_b128 v[202:205], v161 offset:4096
	ds_read_b128 v[206:209], v161 offset:5120
	ds_read_b128 v[210:213], v161 offset:6144
	ds_read_b128 v[214:217], v161 offset:7168
	s_add_i32 s72, s72, 1
	s_mul_i32 s0, s72, s73
	s_mul_hi_u32 s1, s72, s3
	s_add_i32 s1, s1, s0
	s_mul_i32 s0, s72, s3
	s_add_u32 s46, s0, s2
	s_addc_u32 s47, s1, s74
	v_cmp_gt_i64_e32 vcc, s[46:47], v[142:143]
	v_cmp_lt_i64_e64 s[0:1], s[46:47], v[140:141]
	s_cbranch_vccnz .LBB0_914
	s_ashr_i32 s5, s46, 31
	s_lshr_b32 s5, s5, 29
	s_add_i32 s5, s46, s5
	s_ashr_i32 s33, s5, 3
	s_and_b32 s5, s5, -8
	s_sub_i32 s5, s46, s5
	s_cmp_lt_i32 s5, 0
	s_cselect_b32 s34, s77, 0x180
	s_mul_i32 s5, s5, s34
	s_add_i32 s5, s5, s33
	s_ashr_i32 s33, s5, 31
	s_lshr_b32 s33, s33, 21
	s_add_i32 s33, s5, s33
	s_ashr_i32 s34, s33, 11
	s_lshl_b32 s34, s34, 3
	s_sub_i32 s35, 12, s34
	s_min_i32 s35, s35, 8
	s_abs_i32 s42, s35
	v_cvt_f32_u32_e32 v0, s42
	s_sub_i32 s44, 0, s42
	s_and_b32 s33, s33, 0xfffff800
	s_sub_i32 s5, s5, s33
	v_rcp_iflag_f32_e32 v0, v0
	s_abs_i32 s33, s5
	s_xor_b32 s43, s5, s35
	s_ashr_i32 s43, s43, 31
	v_mul_f32_e32 v0, 0x4f7ffffe, v0
	v_cvt_u32_f32_e32 v0, v0
	s_nop 0
	v_readfirstlane_b32 s45, v0
	s_mul_i32 s44, s44, s45
	s_mul_hi_u32 s44, s45, s44
	s_add_i32 s45, s45, s44
	s_mul_hi_u32 s44, s33, s45
	s_mul_i32 s45, s44, s42
	s_sub_i32 s33, s33, s45
	s_add_i32 s46, s44, 1
	s_sub_i32 s45, s33, s42
	s_cmp_ge_u32 s33, s42
	s_cselect_b32 s44, s46, s44
	s_cselect_b32 s33, s45, s33
	s_add_i32 s45, s44, 1
	s_cmp_ge_u32 s33, s42
	s_cselect_b32 s33, s45, s44
	s_xor_b32 s33, s33, s43
	s_sub_i32 s42, s33, s43
	s_mul_i32 s33, s42, s35
	s_sub_i32 s5, s5, s33
	s_add_i32 s44, s34, s5
.LBB0_914:
	s_ashr_i32 s45, s44, 31
	s_lshl_b64 s[46:47], s[44:45], 19
	s_add_u32 s46, s60, s46
	s_addc_u32 s47, s61, s47
	s_and_b64 s[48:49], s[0:1], exec
	s_cselect_b32 s5, s47, s55
	s_cselect_b32 s45, s46, s54
	s_ashr_i32 s43, s42, 31
	s_lshl_b64 s[48:49], s[42:43], 19
	s_add_u32 s48, s16, s48
	s_addc_u32 s49, s17, s49
	s_and_b64 s[58:59], s[0:1], exec
	s_cselect_b32 s43, s49, s57
	s_cselect_b32 s86, s48, s56
	s_add_u32 s54, s54, 0x40080
	s_addc_u32 s55, s55, 0
	s_add_u32 s87, s56, 0x100
	s_addc_u32 s90, s57, 0
	s_mov_b32 s91, -2
	s_waitcnt lgkmcnt(0)
	s_add_u32 s33, s54, 0xfffc0080
	s_addc_u32 s34, s55, -1
	s_cmp_eq_u32 s91, 12
	s_cselect_b32 s59, s5, s34
	s_cselect_b32 s58, s45, s33
	s_cselect_b32 s57, s43, s90
	s_cselect_b32 s56, s86, s87
	s_add_i32 m0, s53, 0xc000
	global_load_lds_dwordx4 v136, s[54:55]
	s_add_i32 m0, s53, 0xe000
	s_nop 0
	global_load_lds_dwordx4 v138, s[54:55]
	s_cmp_eq_u32 s32, 0
	s_cbranch_scc1 .LfwP10_0_s
	s_waitcnt vmcnt(32)
	s_branch .LfwP10_0_e

; #define PG8_STAGE(bufoff, gbase, voff) do { _Pragma("unroll") for (int _i = 0; _i < 2; ++_i) \
;         __builtin_amdgcn_global_load_lds((const unsigned*)((const char*)(gbase) + (voff)[_i]), (PG8_LAS unsigned*)(lds + (bufoff) + ldsw + _i * 8192), 16, 0, 0); } while (0)
; #define PG8_LDA(dst, b, h) do { _Pragma("unroll") for (int m = 0; m < 4; ++m) _Pragma("unroll") for (int k = 0; k < 2; ++k) dst[m][k] = *(const PG8_LAS bf16x8*)(lds + PG8_SA(b, h) + aoff + m * 2048 + k * 1024); } while (0)
; #define PG8_MMA(ai, bj, At, Bt) do { __builtin_amdgcn_s_setprio(1); _Pragma("unroll") for (int m = 0; m < 4; ++m) _Pragma("unroll") for (int n = 0; n < 2; ++n) _Pragma("unroll") for (int k = 0; k < 2; ++k) \
;         acc[ai][bj][m][n] = __builtin_amdgcn_mfma_f32_16x16x32_bf16(Bt[n][k], At[m][k], acc[ai][bj][m][n], 0, 0, 0); __builtin_amdgcn_s_setprio(0); } while (0)
; #define PG8_WAIT_V(n) asm volatile("s_waitcnt vmcnt(" #n ")" ::: "memory")
; #define PG8_WAIT_L(n) asm volatile("s_waitcnt lgkmcnt(" #n ")" ::: "memory")
; #define PG8_BAR __builtin_amdgcn_s_barrier()
; #define PG8_SCHED __builtin_amdgcn_sched_barrier(0)
; template <class Epi, class Sched, bool ALIGN_EPI = false, bool SP2 = false>
; __device__ __forceinline__ void gemm_phase(PG8_LAS unsigned char* lds, const Gemm g, const Sched& S, const Epi& E) {
;     ...
;             PG8_WAIT_V(8); PG8_WAIT_L(0); PG8_BAR; PG8_MMA(0, 0, At, B0); PG8_MMA(0, 1, At, B1); PG8_BAR; PG8_SCHED;
;             PG8_LDA(At, 0, 1); PG8_STAGE(PG8_SB(0, 0), b2, voffB); PG8_STAGE(PG8_SB(0, 1), b2 + hstep, voffB); PG8_STAGE(PG8_SA(0, 0), a2, voffA);
;             PG8_WAIT_V(8); PG8_WAIT_L(0); PG8_BAR; PG8_MMA(1, 0, At, B0); PG8_MMA(1, 1, At, B1); PG8_BAR; PG8_SCHED;
.LfwP10_0_e:
	s_waitcnt lgkmcnt(0)
	s_barrier
	s_setprio 1
	s_waitcnt lgkmcnt(0)
	v_mfma_f32_16x16x32_bf16 v[124:127], v[144:147], v[186:189], 0
	v_mfma_f32_16x16x32_bf16 v[120:123], v[162:165], v[186:189], 0
	v_mfma_f32_16x16x32_bf16 v[108:111], v[144:147], v[194:197], 0
	v_mfma_f32_16x16x32_bf16 v[104:107], v[162:165], v[194:197], 0
	v_mfma_f32_16x16x32_bf16 v[92:95], v[144:147], v[202:205], 0
	v_mfma_f32_16x16x32_bf16 v[88:91], v[162:165], v[202:205], 0
	v_mfma_f32_16x16x32_bf16 v[76:79], v[144:147], v[210:213], 0
	v_mfma_f32_16x16x32_bf16 v[72:75], v[162:165], v[210:213], 0
	v_mfma_f32_16x16x32_bf16 v[124:127], v[148:151], v[190:193], v[124:127]
	v_mfma_f32_16x16x32_bf16 v[120:123], v[166:169], v[190:193], v[120:123]
	v_mfma_f32_16x16x32_bf16 v[108:111], v[148:151], v[198:201], v[108:111]
	v_mfma_f32_16x16x32_bf16 v[104:107], v[166:169], v[198:201], v[104:107]
	v_mfma_f32_16x16x32_bf16 v[92:95], v[148:151], v[206:209], v[92:95]
	v_mfma_f32_16x16x32_bf16 v[88:91], v[166:169], v[206:209], v[88:91]
	v_mfma_f32_16x16x32_bf16 v[76:79], v[148:151], v[214:217], v[76:79]
	v_mfma_f32_16x16x32_bf16 v[72:75], v[166:169], v[214:217], v[72:75]
	s_setprio 0
	s_setprio 1
	v_mfma_f32_16x16x32_bf16 v[116:119], v[170:173], v[186:189], 0
	v_mfma_f32_16x16x32_bf16 v[112:115], v[178:181], v[186:189], 0
	v_mfma_f32_16x16x32_bf16 v[100:103], v[170:173], v[194:197], 0
	v_mfma_f32_16x16x32_bf16 v[96:99], v[178:181], v[194:197], 0
	v_mfma_f32_16x16x32_bf16 v[84:87], v[170:173], v[202:205], 0
	v_mfma_f32_16x16x32_bf16 v[80:83], v[178:181], v[202:205], 0
	v_mfma_f32_16x16x32_bf16 v[68:71], v[170:173], v[210:213], 0
	v_mfma_f32_16x16x32_bf16 v[64:67], v[178:181], v[210:213], 0
	v_mfma_f32_16x16x32_bf16 v[116:119], v[174:177], v[190:193], v[116:119]
	v_mfma_f32_16x16x32_bf16 v[112:115], v[182:185], v[190:193], v[112:115]
	v_mfma_f32_16x16x32_bf16 v[100:103], v[174:177], v[198:201], v[100:103]
	v_mfma_f32_16x16x32_bf16 v[96:99], v[182:185], v[198:201], v[96:99]
	v_mfma_f32_16x16x32_bf16 v[84:87], v[174:177], v[206:209], v[84:87]
	v_mfma_f32_16x16x32_bf16 v[80:83], v[182:185], v[206:209], v[80:83]
	v_mfma_f32_16x16x32_bf16 v[68:71], v[174:177], v[214:217], v[68:71]
	v_mfma_f32_16x16x32_bf16 v[64:67], v[182:185], v[214:217], v[64:67]
	s_setprio 0
	s_barrier
	s_add_i32 s33, s78, s62
	s_add_u32 s80, s56, s20
	s_addc_u32 s81, s57, s21
	s_mov_b32 m0, s33
	ds_read_b128 v[186:189], v161 offset:16384
	ds_read_b128 v[190:193], v161 offset:17408
	ds_read_b128 v[194:197], v161 offset:18432
	ds_read_b128 v[198:201], v161 offset:19456
	ds_read_b128 v[202:205], v161 offset:20480
	ds_read_b128 v[206:209], v161 offset:21504
	ds_read_b128 v[210:213], v161 offset:22528
	ds_read_b128 v[214:217], v161 offset:23552
	global_load_lds_dwordx4 v130, s[56:57]
	s_add_i32 m0, s33, 0x2000
	s_add_u32 s92, s56, 0x40000
	s_addc_u32 s93, s57, 0
	s_add_i32 s33, s79, s62
	global_load_lds_dwordx4 v134, s[56:57]
	s_mov_b32 m0, s33
	s_add_u32 s82, s58, s20
	s_addc_u32 s83, s59, s21
	global_load_lds_dwordx4 v130, s[92:93]
	s_add_i32 m0, s33, 0x2000
	s_nop 0
	global_load_lds_dwordx4 v134, s[92:93]
	s_mov_b32 m0, s53
	s_nop 0
	global_load_lds_dwordx4 v128, s[58:59]
	s_mov_b32 m0, s63
	s_nop 0
	global_load_lds_dwordx4 v132, s[58:59]
	s_cmp_eq_u32 s32, 0
	s_cbranch_scc1 .LfwP10_1_s
	s_waitcnt vmcnt(32)
	s_branch .LfwP10_1_e

; #define PG8_STAGE(bufoff, gbase, voff) do { _Pragma("unroll") for (int _i = 0; _i < 2; ++_i) \
;         __builtin_amdgcn_global_load_lds((const unsigned*)((const char*)(gbase) + (voff)[_i]), (PG8_LAS unsigned*)(lds + (bufoff) + ldsw + _i * 8192), 16, 0, 0); } while (0)
; #define PG8_LDA(dst, b, h) do { _Pragma("unroll") for (int m = 0; m < 4; ++m) _Pragma("unroll") for (int k = 0; k < 2; ++k) dst[m][k] = *(const PG8_LAS bf16x8*)(lds + PG8_SA(b, h) + aoff + m * 2048 + k * 1024); } while (0)
; #define PG8_LDB(dst, b, h) do { _Pragma("unroll") for (int n = 0; n < 2; ++n) _Pragma("unroll") for (int k = 0; k < 2; ++k) dst[n][k] = *(const PG8_LAS bf16x8*)(lds + PG8_SB(b, h) + boff + n * 2048 + k * 1024); } while (0)
; #define PG8_MMA(ai, bj, At, Bt) do { __builtin_amdgcn_s_setprio(1); _Pragma("unroll") for (int m = 0; m < 4; ++m) _Pragma("unroll") for (int n = 0; n < 2; ++n) _Pragma("unroll") for (int k = 0; k < 2; ++k) \
;         acc[ai][bj][m][n] = __builtin_amdgcn_mfma_f32_16x16x32_bf16(Bt[n][k], At[m][k], acc[ai][bj][m][n], 0, 0, 0); __builtin_amdgcn_s_setprio(0); } while (0)
; #define PG8_WAIT_V(n) asm volatile("s_waitcnt vmcnt(" #n ")" ::: "memory")
; #define PG8_WAIT_L(n) asm volatile("s_waitcnt lgkmcnt(" #n ")" ::: "memory")
; #define PG8_BAR __builtin_amdgcn_s_barrier()
; #define PG8_SCHED __builtin_amdgcn_sched_barrier(0)
; template <class Epi, class Sched, bool ALIGN_EPI = false, bool SP2 = false>
; __device__ __forceinline__ void gemm_phase(PG8_LAS unsigned char* lds, const Gemm g, const Sched& S, const Epi& E) {
;     ...
;             PG8_WAIT_V(8); PG8_WAIT_L(0); PG8_BAR; PG8_MMA(1, 0, At, B0); PG8_MMA(1, 1, At, B1); PG8_BAR; PG8_SCHED;
;             PG8_LDB(B0, 1, 0); PG8_LDB(B1, 1, 1); PG8_SCHED; PG8_LDA(At, 1, 0); PG8_STAGE(PG8_SA(0, 1), a2 + hstep, voffA);
;             PG8_WAIT_V(8); PG8_WAIT_L(0); PG8_BAR; PG8_MMA(0, 0, At, B0); PG8_MMA(0, 1, At, B1); PG8_BAR; PG8_SCHED;
.LfwP10_1_e:
	s_waitcnt lgkmcnt(0)
	s_barrier
	s_setprio 1
	s_waitcnt lgkmcnt(0)
	v_mfma_f32_16x16x32_bf16 v[60:63], v[144:147], v[186:189], 0
	v_mfma_f32_16x16x32_bf16 v[56:59], v[162:165], v[186:189], 0
	v_mfma_f32_16x16x32_bf16 v[48:51], v[144:147], v[194:197], 0
	v_mfma_f32_16x16x32_bf16 v[40:43], v[162:165], v[194:197], 0
	v_mfma_f32_16x16x32_bf16 v[32:35], v[144:147], v[202:205], 0
	v_mfma_f32_16x16x32_bf16 v[24:27], v[162:165], v[202:205], 0
	v_mfma_f32_16x16x32_bf16 v[16:19], v[144:147], v[210:213], 0
	v_mfma_f32_16x16x32_bf16 v[8:11], v[162:165], v[210:213], 0
	v_mfma_f32_16x16x32_bf16 v[60:63], v[148:151], v[190:193], v[60:63]
	v_mfma_f32_16x16x32_bf16 v[56:59], v[166:169], v[190:193], v[56:59]
	v_mfma_f32_16x16x32_bf16 v[48:51], v[148:151], v[198:201], v[48:51]
	v_mfma_f32_16x16x32_bf16 v[40:43], v[166:169], v[198:201], v[40:43]
	v_mfma_f32_16x16x32_bf16 v[32:35], v[148:151], v[206:209], v[32:35]
	v_mfma_f32_16x16x32_bf16 v[24:27], v[166:169], v[206:209], v[24:27]
	v_mfma_f32_16x16x32_bf16 v[16:19], v[148:151], v[214:217], v[16:19]
	v_mfma_f32_16x16x32_bf16 v[8:11], v[166:169], v[214:217], v[8:11]
	s_setprio 0
	s_setprio 1
	v_mfma_f32_16x16x32_bf16 v[52:55], v[170:173], v[186:189], 0
	v_mfma_f32_16x16x32_bf16 v[44:47], v[178:181], v[186:189], 0
	v_mfma_f32_16x16x32_bf16 v[36:39], v[170:173], v[194:197], 0
	v_mfma_f32_16x16x32_bf16 v[28:31], v[178:181], v[194:197], 0
	v_mfma_f32_16x16x32_bf16 v[20:23], v[170:173], v[202:205], 0
	v_mfma_f32_16x16x32_bf16 v[12:15], v[178:181], v[202:205], 0
	v_mfma_f32_16x16x32_bf16 v[4:7], v[170:173], v[210:213], 0
	v_mfma_f32_16x16x32_bf16 v[0:3], v[178:181], v[210:213], 0
	v_mfma_f32_16x16x32_bf16 v[52:55], v[174:177], v[190:193], v[52:55]
	v_mfma_f32_16x16x32_bf16 v[44:47], v[182:185], v[190:193], v[44:47]
	v_mfma_f32_16x16x32_bf16 v[36:39], v[174:177], v[198:201], v[36:39]
	v_mfma_f32_16x16x32_bf16 v[28:31], v[182:185], v[198:201], v[28:31]
	v_mfma_f32_16x16x32_bf16 v[20:23], v[174:177], v[206:209], v[20:23]
	v_mfma_f32_16x16x32_bf16 v[12:15], v[182:185], v[206:209], v[12:15]
	v_mfma_f32_16x16x32_bf16 v[4:7], v[174:177], v[214:217], v[4:7]
	v_mfma_f32_16x16x32_bf16 v[0:3], v[182:185], v[214:217], v[0:3]
	s_setprio 0
	s_barrier
	s_add_i32 s33, 0, 0x18000
	v_add_u32_e32 v153, s33, v157
	s_add_i32 s34, 0, 0x1c000
	ds_read_b128 v[144:147], v153
	ds_read_b128 v[148:151], v153 offset:1024
	ds_read_b128 v[162:165], v153 offset:2048
	ds_read_b128 v[166:169], v153 offset:3072
	v_add_u32_e32 v153, s34, v157
	ds_read_b128 v[170:173], v153
	ds_read_b128 v[174:177], v153 offset:1024
	ds_read_b128 v[178:181], v153 offset:2048
	ds_read_b128 v[182:185], v153 offset:3072
	s_add_u32 s58, s58, 0x40000
	s_addc_u32 s59, s59, 0
	s_mov_b32 m0, s70
	ds_read_b128 v[186:189], v161 offset:32768
	ds_read_b128 v[190:193], v161 offset:33792
	ds_read_b128 v[194:197], v161 offset:34816
	ds_read_b128 v[198:201], v161 offset:35840
	ds_read_b128 v[202:205], v161 offset:36864
	ds_read_b128 v[206:209], v161 offset:37888
	ds_read_b128 v[210:213], v161 offset:38912
	ds_read_b128 v[214:217], v161 offset:39936
	global_load_lds_dwordx4 v128, s[58:59]
	s_mov_b32 m0, s71
	s_nop 0
	global_load_lds_dwordx4 v132, s[58:59]
	s_waitcnt vmcnt(8)
	s_waitcnt lgkmcnt(0)
	s_barrier
	s_setprio 1
	s_waitcnt lgkmcnt(0)
	v_mfma_f32_16x16x32_bf16 v[124:127], v[144:147], v[186:189], v[124:127]
	v_mfma_f32_16x16x32_bf16 v[120:123], v[162:165], v[186:189], v[120:123]
	v_mfma_f32_16x16x32_bf16 v[108:111], v[144:147], v[194:197], v[108:111]
	v_mfma_f32_16x16x32_bf16 v[104:107], v[162:165], v[194:197], v[104:107]
	v_mfma_f32_16x16x32_bf16 v[92:95], v[144:147], v[202:205], v[92:95]
	v_mfma_f32_16x16x32_bf16 v[88:91], v[162:165], v[202:205], v[88:91]
	v_mfma_f32_16x16x32_bf16 v[76:79], v[144:147], v[210:213], v[76:79]
	v_mfma_f32_16x16x32_bf16 v[72:75], v[162:165], v[210:213], v[72:75]
	v_mfma_f32_16x16x32_bf16 v[124:127], v[148:151], v[190:193], v[124:127]
	v_mfma_f32_16x16x32_bf16 v[120:123], v[166:169], v[190:193], v[120:123]
	v_mfma_f32_16x16x32_bf16 v[108:111], v[148:151], v[198:201], v[108:111]
	v_mfma_f32_16x16x32_bf16 v[104:107], v[166:169], v[198:201], v[104:107]
	v_mfma_f32_16x16x32_bf16 v[92:95], v[148:151], v[206:209], v[92:95]
	v_mfma_f32_16x16x32_bf16 v[88:91], v[166:169], v[206:209], v[88:91]
	v_mfma_f32_16x16x32_bf16 v[76:79], v[148:151], v[214:217], v[76:79]
	v_mfma_f32_16x16x32_bf16 v[72:75], v[166:169], v[214:217], v[72:75]
	s_setprio 0
	s_setprio 1
	v_mfma_f32_16x16x32_bf16 v[116:119], v[170:173], v[186:189], v[116:119]
	v_mfma_f32_16x16x32_bf16 v[112:115], v[178:181], v[186:189], v[112:115]
	v_mfma_f32_16x16x32_bf16 v[100:103], v[170:173], v[194:197], v[100:103]
	v_mfma_f32_16x16x32_bf16 v[96:99], v[178:181], v[194:197], v[96:99]
	v_mfma_f32_16x16x32_bf16 v[84:87], v[170:173], v[202:205], v[84:87]
	v_mfma_f32_16x16x32_bf16 v[80:83], v[178:181], v[202:205], v[80:83]
	v_mfma_f32_16x16x32_bf16 v[68:71], v[170:173], v[210:213], v[68:71]
	v_mfma_f32_16x16x32_bf16 v[64:67], v[178:181], v[210:213], v[64:67]
	v_mfma_f32_16x16x32_bf16 v[116:119], v[174:177], v[190:193], v[116:119]
	v_mfma_f32_16x16x32_bf16 v[112:115], v[182:185], v[190:193], v[112:115]
	v_mfma_f32_16x16x32_bf16 v[100:103], v[174:177], v[198:201], v[100:103]
	v_mfma_f32_16x16x32_bf16 v[96:99], v[182:185], v[198:201], v[96:99]
	v_mfma_f32_16x16x32_bf16 v[84:87], v[174:177], v[206:209], v[84:87]
	v_mfma_f32_16x16x32_bf16 v[80:83], v[182:185], v[206:209], v[80:83]
	v_mfma_f32_16x16x32_bf16 v[68:71], v[174:177], v[214:217], v[68:71]
	v_mfma_f32_16x16x32_bf16 v[64:67], v[182:185], v[214:217], v[64:67]
	s_setprio 0
	s_barrier
; #define PG8_STAGE(bufoff, gbase, voff) do { _Pragma("unroll") for (int _i = 0; _i < 2; ++_i) \
;         __builtin_amdgcn_global_load_lds((const unsigned*)((const char*)(gbase) + (voff)[_i]), (PG8_LAS unsigned*)(lds + (bufoff) + ldsw + _i * 8192), 16, 0, 0); } while (0)
; #define PG8_LDA(dst, b, h) do { _Pragma("unroll") for (int m = 0; m < 4; ++m) _Pragma("unroll") for (int k = 0; k < 2; ++k) dst[m][k] = *(const PG8_LAS bf16x8*)(lds + PG8_SA(b, h) + aoff + m * 2048 + k * 1024); } while (0)
; #define PG8_MMA(ai, bj, At, Bt) do { __builtin_amdgcn_s_setprio(1); _Pragma("unroll") for (int m = 0; m < 4; ++m) _Pragma("unroll") for (int n = 0; n < 2; ++n) _Pragma("unroll") for (int k = 0; k < 2; ++k) \
;         acc[ai][bj][m][n] = __builtin_amdgcn_mfma_f32_16x16x32_bf16(Bt[n][k], At[m][k], acc[ai][bj][m][n], 0, 0, 0); __builtin_amdgcn_s_setprio(0); } while (0)
; #define PG8_WAIT_V(n) asm volatile("s_waitcnt vmcnt(" #n ")" ::: "memory")
; #define PG8_WAIT_L(n) asm volatile("s_waitcnt lgkmcnt(" #n ")" ::: "memory")
; #define PG8_BAR __builtin_amdgcn_s_barrier()
; #define PG8_SCHED __builtin_amdgcn_sched_barrier(0)
; template <class Epi, class Sched, bool ALIGN_EPI = false, bool SP2 = false>
; __device__ __forceinline__ void gemm_phase(PG8_LAS unsigned char* lds, const Gemm g, const Sched& S, const Epi& E) {
;     ...
;             PG8_LDA(At, 1, 1); PG8_STAGE(PG8_SB(1, 0), b3, voffB); PG8_STAGE(PG8_SB(1, 1), b3 + hstep, voffB); PG8_STAGE(PG8_SA(1, 0), a3, voffA);
;             PG8_WAIT_V(8); PG8_WAIT_L(0); PG8_BAR; PG8_MMA(1, 0, At, B0); PG8_MMA(1, 1, At, B1); PG8_BAR; PG8_SCHED;
	s_add_i32 s33, s33, s62
	s_mov_b32 m0, s33
	ds_read_b128 v[186:189], v161 offset:49152
	ds_read_b128 v[190:193], v161 offset:50176
	ds_read_b128 v[194:197], v161 offset:51200
	ds_read_b128 v[198:201], v161 offset:52224
	ds_read_b128 v[202:205], v161 offset:53248
	ds_read_b128 v[206:209], v161 offset:54272
	ds_read_b128 v[210:213], v161 offset:55296
	ds_read_b128 v[214:217], v161 offset:56320
	global_load_lds_dwordx4 v130, s[80:81]
	s_add_i32 m0, s33, 0x2000
	s_add_u32 s56, s56, 0x40080
	s_addc_u32 s57, s57, 0
	s_add_i32 s33, s34, s62
	global_load_lds_dwordx4 v134, s[80:81]
	s_mov_b32 m0, s33
	s_nop 0
	global_load_lds_dwordx4 v130, s[56:57]
	s_add_i32 m0, s33, 0x2000
	s_nop 0
	global_load_lds_dwordx4 v134, s[56:57]
	s_mov_b32 m0, s75
	s_nop 0
	global_load_lds_dwordx4 v128, s[82:83]
	s_mov_b32 m0, s76
	s_nop 0
	global_load_lds_dwordx4 v132, s[82:83]
	s_waitcnt vmcnt(8)
	s_waitcnt lgkmcnt(0)
	s_barrier
	s_setprio 1
	s_waitcnt lgkmcnt(0)
	v_mfma_f32_16x16x32_bf16 v[60:63], v[144:147], v[186:189], v[60:63]
	v_mfma_f32_16x16x32_bf16 v[56:59], v[162:165], v[186:189], v[56:59]
	v_mfma_f32_16x16x32_bf16 v[48:51], v[144:147], v[194:197], v[48:51]
	v_mfma_f32_16x16x32_bf16 v[40:43], v[162:165], v[194:197], v[40:43]
	v_mfma_f32_16x16x32_bf16 v[32:35], v[144:147], v[202:205], v[32:35]
	v_mfma_f32_16x16x32_bf16 v[24:27], v[162:165], v[202:205], v[24:27]
	v_mfma_f32_16x16x32_bf16 v[16:19], v[144:147], v[210:213], v[16:19]
	v_mfma_f32_16x16x32_bf16 v[8:11], v[162:165], v[210:213], v[8:11]
	v_mfma_f32_16x16x32_bf16 v[60:63], v[148:151], v[190:193], v[60:63]
	v_mfma_f32_16x16x32_bf16 v[56:59], v[166:169], v[190:193], v[56:59]
	v_mfma_f32_16x16x32_bf16 v[48:51], v[148:151], v[198:201], v[48:51]
	v_mfma_f32_16x16x32_bf16 v[40:43], v[166:169], v[198:201], v[40:43]
	v_mfma_f32_16x16x32_bf16 v[32:35], v[148:151], v[206:209], v[32:35]
	v_mfma_f32_16x16x32_bf16 v[24:27], v[166:169], v[206:209], v[24:27]
	v_mfma_f32_16x16x32_bf16 v[16:19], v[148:151], v[214:217], v[16:19]
	v_mfma_f32_16x16x32_bf16 v[8:11], v[166:169], v[214:217], v[8:11]
	s_setprio 0
	s_setprio 1
	v_mfma_f32_16x16x32_bf16 v[52:55], v[170:173], v[186:189], v[52:55]
	v_mfma_f32_16x16x32_bf16 v[44:47], v[178:181], v[186:189], v[44:47]
	v_mfma_f32_16x16x32_bf16 v[36:39], v[170:173], v[194:197], v[36:39]
	v_mfma_f32_16x16x32_bf16 v[28:31], v[178:181], v[194:197], v[28:31]
	v_mfma_f32_16x16x32_bf16 v[20:23], v[170:173], v[202:205], v[20:23]
	v_mfma_f32_16x16x32_bf16 v[12:15], v[178:181], v[202:205], v[12:15]
	v_mfma_f32_16x16x32_bf16 v[4:7], v[170:173], v[210:213], v[4:7]
	v_mfma_f32_16x16x32_bf16 v[0:3], v[178:181], v[210:213], v[0:3]
	v_mfma_f32_16x16x32_bf16 v[52:55], v[174:177], v[190:193], v[52:55]
	v_mfma_f32_16x16x32_bf16 v[44:47], v[182:185], v[190:193], v[44:47]
	v_mfma_f32_16x16x32_bf16 v[36:39], v[174:177], v[198:201], v[36:39]
	v_mfma_f32_16x16x32_bf16 v[28:31], v[182:185], v[198:201], v[28:31]
	v_mfma_f32_16x16x32_bf16 v[20:23], v[174:177], v[206:209], v[20:23]
	v_mfma_f32_16x16x32_bf16 v[12:15], v[182:185], v[206:209], v[12:15]
	v_mfma_f32_16x16x32_bf16 v[4:7], v[174:177], v[214:217], v[4:7]
	v_mfma_f32_16x16x32_bf16 v[0:3], v[182:185], v[214:217], v[0:3]
	s_setprio 0
	s_barrier
	s_add_i32 s91, s91, 2
	s_add_u32 s54, s54, 0x100
	s_addc_u32 s55, s55, 0
	s_add_u32 s87, s87, 0x100
	s_addc_u32 s90, s90, 0
	s_cmp_gt_u32 s91, 13

; __device__ __forceinline__ unsigned pk2(float lo, float hi) { f32x2 v = {lo, hi}; bf16x2_t b = __builtin_convertvector(v, bf16x2_t); return __builtin_bit_cast(unsigned, b); }
;     __device__ __forceinline__ void operator()(const f32x4 (&acc)[2][2][4][2], const Unit& u, int wr, int wc, int fr, int fq) const {
;     ...
;             for (int m = 0; m < 4; ++m) { const int row = row0 + ai * HALF + m * 16; const float rb = rowbias ? rowbias[row] : 0.f; bf16_t* rowp = O + (size_t)row * ldc + col0;
; #pragma unroll
;                 for (int bj = 0; bj < 2; ++bj) { const f32x4 v0 = acc[ai][bj][m][0] + rb, v1 = acc[ai][bj][m][1] + rb;
;                     u32x4 w; w.x = pk2(v0[0], v0[1]); w.y = pk2(v0[2], v0[3]); w.z = pk2(v1[0], v1[1]); w.w = pk2(v1[2], v1[3]);
;                     *(u32x4*)(rowp + bj * HALF) = w; } }
.LBB0_918:
	s_mov_b32 s32, 1
	v_lshl_add_u32 v148, s4, 8, v155
	v_readlane_b32 s80, v255, 4
	v_ashrrev_i32_e32 v149, 31, v148
	v_cndmask_b32_e64 v144, 0, 1, s[12:13]
	v_readlane_b32 s92, v255, 16
	v_readlane_b32 s93, v255, 17
	v_mov_b32_e32 v154, 0
	v_cmp_ne_u32_e64 s[4:5], 1, v144
	s_andn2_b64 vcc, exec, s[12:13]
	v_lshl_add_u64 v[146:147], v[148:149], 2, s[92:93]
	v_mov_b32_e32 v156, 0
	v_readlane_b32 s81, v255, 5
	v_readlane_b32 s82, v255, 6
	v_readlane_b32 s83, v255, 7
	v_readlane_b32 s84, v255, 8
	v_readlane_b32 s85, v255, 9
	v_readlane_b32 s86, v255, 10
	v_readlane_b32 s87, v255, 11
	v_readlane_b32 s88, v255, 12
	v_readlane_b32 s89, v255, 13
	v_readlane_b32 s90, v255, 14
	v_readlane_b32 s91, v255, 15
	v_readlane_b32 s94, v255, 18
	v_readlane_b32 s95, v255, 19
	v_mov_b32_e32 v156, v230
.LBB0_920:
	v_lshl_or_b32 v150, s52, 8, v158
	v_lshlrev_b64 v[144:145], 17, v[148:149]
	v_ashrrev_i32_e32 v151, 31, v150
	v_lshl_add_u64 v[144:145], s[10:11], 0, v[144:145]
	s_nop 0
	v_pk_add_f32 v[126:127], v[126:127], v[156:157] op_sel_hi:[1,0]
	v_pk_add_f32 v[124:125], v[124:125], v[156:157] op_sel_hi:[1,0]
	v_pk_add_f32 v[162:163], v[122:123], v[156:157] op_sel_hi:[1,0]
	v_pk_add_f32 v[122:123], v[120:121], v[156:157] op_sel_hi:[1,0]
	v_lshl_add_u64 v[144:145], v[150:151], 1, v[144:145]
	v_cvt_pk_bf16_f32 v120, v124, v125
	v_cvt_pk_bf16_f32 v121, v126, v127
	v_cvt_pk_bf16_f32 v122, v122, v123
	v_cvt_pk_bf16_f32 v123, v162, v163
	global_store_dwordx4 v[144:145], v[120:123], off
	v_pk_add_f32 v[118:119], v[118:119], v[156:157] op_sel_hi:[1,0]
	v_pk_add_f32 v[116:117], v[116:117], v[156:157] op_sel_hi:[1,0]
	v_pk_add_f32 v[120:121], v[114:115], v[156:157] op_sel_hi:[1,0]
	v_pk_add_f32 v[114:115], v[112:113], v[156:157] op_sel_hi:[1,0]
	v_cvt_pk_bf16_f32 v112, v116, v117
	v_cvt_pk_bf16_f32 v113, v118, v119
	v_cvt_pk_bf16_f32 v114, v114, v115
	v_cvt_pk_bf16_f32 v115, v120, v121
	s_and_b64 vcc, exec, s[4:5]
	global_store_dwordx4 v[144:145], v[112:115], off offset:256
	v_mov_b32_e32 v154, v231
.LBB0_922:
	s_nop 0
	v_or_b32_e32 v112, 16, v148
	v_ashrrev_i32_e32 v113, 31, v112
	v_lshlrev_b64 v[112:113], 17, v[112:113]
	v_lshl_add_u64 v[112:113], s[10:11], 0, v[112:113]
	s_nop 0
	v_pk_add_f32 v[110:111], v[110:111], v[154:155] op_sel_hi:[1,0]
	v_pk_add_f32 v[108:109], v[108:109], v[154:155] op_sel_hi:[1,0]
	v_pk_add_f32 v[114:115], v[106:107], v[154:155] op_sel_hi:[1,0]
	v_pk_add_f32 v[106:107], v[104:105], v[154:155] op_sel_hi:[1,0]
	v_lshl_add_u64 v[112:113], v[150:151], 1, v[112:113]
	v_cvt_pk_bf16_f32 v104, v108, v109
	v_cvt_pk_bf16_f32 v105, v110, v111
	v_cvt_pk_bf16_f32 v106, v106, v107
	v_cvt_pk_bf16_f32 v107, v114, v115
	global_store_dwordx4 v[112:113], v[104:107], off
	v_pk_add_f32 v[102:103], v[102:103], v[154:155] op_sel_hi:[1,0]
	v_pk_add_f32 v[100:101], v[100:101], v[154:155] op_sel_hi:[1,0]
	v_pk_add_f32 v[104:105], v[98:99], v[154:155] op_sel_hi:[1,0]
	v_pk_add_f32 v[98:99], v[96:97], v[154:155] op_sel_hi:[1,0]
	v_cvt_pk_bf16_f32 v96, v100, v101
	v_cvt_pk_bf16_f32 v97, v102, v103
	v_cvt_pk_bf16_f32 v98, v98, v99
	v_cvt_pk_bf16_f32 v99, v104, v105
	global_store_dwordx4 v[112:113], v[96:99], off offset:256
	s_and_b64 vcc, exec, s[4:5]
	s_nop 0
	v_mov_b32_e32 v96, 0
	v_mov_b32_e32 v98, 0
	v_mov_b32_e32 v98, v232
.LBB0_924:
	v_or_b32_e32 v100, 32, v148
	v_ashrrev_i32_e32 v101, 31, v100
	v_lshlrev_b64 v[100:101], 17, v[100:101]
	v_lshl_add_u64 v[100:101], s[10:11], 0, v[100:101]
	s_nop 0
	v_pk_add_f32 v[94:95], v[94:95], v[98:99] op_sel_hi:[1,0]
	v_pk_add_f32 v[92:93], v[92:93], v[98:99] op_sel_hi:[1,0]
	v_pk_add_f32 v[102:103], v[90:91], v[98:99] op_sel_hi:[1,0]
	v_pk_add_f32 v[90:91], v[88:89], v[98:99] op_sel_hi:[1,0]
	v_lshl_add_u64 v[100:101], v[150:151], 1, v[100:101]
	v_cvt_pk_bf16_f32 v88, v92, v93
	v_cvt_pk_bf16_f32 v89, v94, v95
	v_cvt_pk_bf16_f32 v90, v90, v91
	v_cvt_pk_bf16_f32 v91, v102, v103
	global_store_dwordx4 v[100:101], v[88:91], off
	v_pk_add_f32 v[86:87], v[86:87], v[98:99] op_sel_hi:[1,0]
	v_pk_add_f32 v[84:85], v[84:85], v[98:99] op_sel_hi:[1,0]
	v_pk_add_f32 v[88:89], v[82:83], v[98:99] op_sel_hi:[1,0]
	v_pk_add_f32 v[82:83], v[80:81], v[98:99] op_sel_hi:[1,0]
	v_cvt_pk_bf16_f32 v80, v84, v85
	v_cvt_pk_bf16_f32 v81, v86, v87
	v_cvt_pk_bf16_f32 v82, v82, v83
	v_cvt_pk_bf16_f32 v83, v88, v89
	s_and_b64 vcc, exec, s[4:5]
	global_store_dwordx4 v[100:101], v[80:83], off offset:256
	v_mov_b32_e32 v96, v233
.LBB0_926:
	s_nop 0
	v_or_b32_e32 v80, 48, v148
	v_ashrrev_i32_e32 v81, 31, v80
	v_lshlrev_b64 v[80:81], 17, v[80:81]
	v_lshl_add_u64 v[80:81], s[10:11], 0, v[80:81]
	s_nop 0
	v_pk_add_f32 v[78:79], v[78:79], v[96:97] op_sel_hi:[1,0]
	v_pk_add_f32 v[76:77], v[76:77], v[96:97] op_sel_hi:[1,0]
	v_pk_add_f32 v[82:83], v[74:75], v[96:97] op_sel_hi:[1,0]
	v_pk_add_f32 v[74:75], v[72:73], v[96:97] op_sel_hi:[1,0]
	v_lshl_add_u64 v[80:81], v[150:151], 1, v[80:81]
	v_cvt_pk_bf16_f32 v72, v76, v77
	v_cvt_pk_bf16_f32 v73, v78, v79
	v_cvt_pk_bf16_f32 v74, v74, v75
	v_cvt_pk_bf16_f32 v75, v82, v83
	global_store_dwordx4 v[80:81], v[72:75], off
	v_pk_add_f32 v[70:71], v[70:71], v[96:97] op_sel_hi:[1,0]
	v_pk_add_f32 v[68:69], v[68:69], v[96:97] op_sel_hi:[1,0]
	v_pk_add_f32 v[72:73], v[66:67], v[96:97] op_sel_hi:[1,0]
	v_pk_add_f32 v[66:67], v[64:65], v[96:97] op_sel_hi:[1,0]
	v_cvt_pk_bf16_f32 v64, v68, v69
	v_cvt_pk_bf16_f32 v65, v70, v71
	v_cvt_pk_bf16_f32 v66, v66, v67
	v_cvt_pk_bf16_f32 v67, v72, v73
	global_store_dwordx4 v[80:81], v[64:67], off offset:256
	s_and_b64 vcc, exec, s[4:5]
	s_nop 0
	v_mov_b32_e32 v64, 0
	v_mov_b32_e32 v66, 0
	v_mov_b32_e32 v66, v234
; __device__ __forceinline__ unsigned pk2(float lo, float hi) { f32x2 v = {lo, hi}; bf16x2_t b = __builtin_convertvector(v, bf16x2_t); return __builtin_bit_cast(unsigned, b); }
;     __device__ __forceinline__ void operator()(const f32x4 (&acc)[2][2][4][2], const Unit& u, int wr, int wc, int fr, int fq) const {
;     ...
;             for (int m = 0; m < 4; ++m) { const int row = row0 + ai * HALF + m * 16; const float rb = rowbias ? rowbias[row] : 0.f; bf16_t* rowp = O + (size_t)row * ldc + col0;
; #pragma unroll
;                 for (int bj = 0; bj < 2; ++bj) { const f32x4 v0 = acc[ai][bj][m][0] + rb, v1 = acc[ai][bj][m][1] + rb;
;                     u32x4 w; w.x = pk2(v0[0], v0[1]); w.y = pk2(v0[2], v0[3]); w.z = pk2(v1[0], v1[1]); w.w = pk2(v1[2], v1[3]);
;                     *(u32x4*)(rowp + bj * HALF) = w; } }
.LBB0_928:
	s_nop 0
	v_pk_add_f32 v[60:61], v[60:61], v[66:67] op_sel_hi:[1,0]
	v_pk_add_f32 v[62:63], v[62:63], v[66:67] op_sel_hi:[1,0]
	v_pk_add_f32 v[70:71], v[58:59], v[66:67] op_sel_hi:[1,0]
	v_pk_add_f32 v[58:59], v[56:57], v[66:67] op_sel_hi:[1,0]
	v_cvt_pk_bf16_f32 v56, v60, v61
	v_add_co_u32_e32 v60, vcc, s64, v144
	v_cvt_pk_bf16_f32 v57, v62, v63
	v_cvt_pk_bf16_f32 v58, v58, v59
	v_cvt_pk_bf16_f32 v59, v70, v71
	v_addc_co_u32_e32 v61, vcc, 0, v145, vcc
	global_store_dwordx4 v[60:61], v[56:59], off
	v_pk_add_f32 v[54:55], v[54:55], v[66:67] op_sel_hi:[1,0]
	v_pk_add_f32 v[52:53], v[52:53], v[66:67] op_sel_hi:[1,0]
	v_pk_add_f32 v[56:57], v[46:47], v[66:67] op_sel_hi:[1,0]
	v_pk_add_f32 v[46:47], v[44:45], v[66:67] op_sel_hi:[1,0]
	v_lshl_add_u64 v[68:69], v[144:145], 0, s[24:25]
	v_cvt_pk_bf16_f32 v44, v52, v53
	v_cvt_pk_bf16_f32 v45, v54, v55
	v_cvt_pk_bf16_f32 v46, v46, v47
	v_cvt_pk_bf16_f32 v47, v56, v57
	s_and_b64 vcc, exec, s[4:5]
	global_store_dwordx4 v[68:69], v[44:47], off offset:256
	v_mov_b32_e32 v64, v235
.LBB0_930:
	s_nop 0
	v_pk_add_f32 v[46:47], v[50:51], v[64:65] op_sel_hi:[1,0]
	v_pk_add_f32 v[48:49], v[48:49], v[64:65] op_sel_hi:[1,0]
	v_pk_add_f32 v[50:51], v[42:43], v[64:65] op_sel_hi:[1,0]
	v_pk_add_f32 v[42:43], v[40:41], v[64:65] op_sel_hi:[1,0]
	v_cvt_pk_bf16_f32 v41, v46, v47
	v_add_co_u32_e32 v46, vcc, s65, v144
	v_cvt_pk_bf16_f32 v40, v48, v49
	v_cvt_pk_bf16_f32 v42, v42, v43
	v_cvt_pk_bf16_f32 v43, v50, v51
	v_addc_co_u32_e32 v47, vcc, 0, v145, vcc
	global_store_dwordx4 v[46:47], v[40:43], off
	v_pk_add_f32 v[38:39], v[38:39], v[64:65] op_sel_hi:[1,0]
	v_pk_add_f32 v[36:37], v[36:37], v[64:65] op_sel_hi:[1,0]
	v_pk_add_f32 v[40:41], v[30:31], v[64:65] op_sel_hi:[1,0]
	v_pk_add_f32 v[30:31], v[28:29], v[64:65] op_sel_hi:[1,0]
	v_lshl_add_u64 v[44:45], v[144:145], 0, s[36:37]
	v_cvt_pk_bf16_f32 v28, v36, v37
	v_cvt_pk_bf16_f32 v29, v38, v39
	v_cvt_pk_bf16_f32 v30, v30, v31
	v_cvt_pk_bf16_f32 v31, v40, v41
	global_store_dwordx4 v[44:45], v[28:31], off offset:256
	s_and_b64 vcc, exec, s[4:5]
	s_nop 0
	v_mov_b32_e32 v28, 0
	v_mov_b32_e32 v30, 0
	v_mov_b32_e32 v30, v236
.LBB0_932:
	s_nop 0
	v_pk_add_f32 v[32:33], v[32:33], v[30:31] op_sel_hi:[1,0]
	v_pk_add_f32 v[34:35], v[34:35], v[30:31] op_sel_hi:[1,0]
	v_pk_add_f32 v[38:39], v[26:27], v[30:31] op_sel_hi:[1,0]
	v_pk_add_f32 v[26:27], v[24:25], v[30:31] op_sel_hi:[1,0]
	v_cvt_pk_bf16_f32 v24, v32, v33
	v_add_co_u32_e32 v32, vcc, s66, v144
	v_cvt_pk_bf16_f32 v25, v34, v35
	v_cvt_pk_bf16_f32 v26, v26, v27
	v_cvt_pk_bf16_f32 v27, v38, v39
	v_addc_co_u32_e32 v33, vcc, 0, v145, vcc
	global_store_dwordx4 v[32:33], v[24:27], off
	v_pk_add_f32 v[22:23], v[22:23], v[30:31] op_sel_hi:[1,0]
	v_pk_add_f32 v[20:21], v[20:21], v[30:31] op_sel_hi:[1,0]
	v_pk_add_f32 v[24:25], v[14:15], v[30:31] op_sel_hi:[1,0]
	v_pk_add_f32 v[14:15], v[12:13], v[30:31] op_sel_hi:[1,0]
	v_lshl_add_u64 v[36:37], v[144:145], 0, s[38:39]
	v_cvt_pk_bf16_f32 v12, v20, v21
	v_cvt_pk_bf16_f32 v13, v22, v23
	v_cvt_pk_bf16_f32 v14, v14, v15
	v_cvt_pk_bf16_f32 v15, v24, v25
	s_and_b64 vcc, exec, s[4:5]
	global_store_dwordx4 v[36:37], v[12:15], off offset:256
	v_mov_b32_e32 v28, v237
.LBB0_934:
	s_nop 0
	v_pk_add_f32 v[14:15], v[18:19], v[28:29] op_sel_hi:[1,0]
	v_pk_add_f32 v[16:17], v[16:17], v[28:29] op_sel_hi:[1,0]
	v_pk_add_f32 v[18:19], v[10:11], v[28:29] op_sel_hi:[1,0]
	v_pk_add_f32 v[10:11], v[8:9], v[28:29] op_sel_hi:[1,0]
	v_cvt_pk_bf16_f32 v9, v14, v15
	v_add_co_u32_e32 v14, vcc, s67, v144
	v_cvt_pk_bf16_f32 v8, v16, v17
	v_cvt_pk_bf16_f32 v10, v10, v11
	v_cvt_pk_bf16_f32 v11, v18, v19
	v_addc_co_u32_e32 v15, vcc, 0, v145, vcc
	global_store_dwordx4 v[14:15], v[8:11], off
	v_pk_add_f32 v[6:7], v[6:7], v[28:29] op_sel_hi:[1,0]
	v_pk_add_f32 v[4:5], v[4:5], v[28:29] op_sel_hi:[1,0]
	v_pk_add_f32 v[8:9], v[2:3], v[28:29] op_sel_hi:[1,0]
	v_pk_add_f32 v[2:3], v[0:1], v[28:29] op_sel_hi:[1,0]
	v_lshl_add_u64 v[12:13], v[144:145], 0, s[40:41]
	v_cvt_pk_bf16_f32 v0, v4, v5
	v_cvt_pk_bf16_f32 v1, v6, v7
	v_cvt_pk_bf16_f32 v2, v2, v3
	v_cvt_pk_bf16_f32 v3, v8, v9
	s_andn2_b64 vcc, exec, s[0:1]
	s_mov_b64 s[0:1], -1
	global_store_dwordx4 v[12:13], v[0:3], off offset:256
	s_cbranch_vccnz .LBB0_911
	v_lshl_add_u32 v240, s44, 8, v155
	v_ashrrev_i32_e32 v241, 31, v240
	v_lshl_add_u64 v[238:239], v[240:241], 2, s[92:93]
	global_load_dword v230, v[238:239], off
	global_load_dword v231, v[238:239], off offset:64
	global_load_dword v232, v[238:239], off offset:128
	global_load_dword v233, v[238:239], off offset:192
	global_load_dword v234, v[238:239], off offset:512
	global_load_dword v235, v[238:239], off offset:576
	global_load_dword v236, v[238:239], off offset:640
	global_load_dword v237, v[238:239], off offset:704
	s_andn2_b64 vcc, exec, s[8:9]
	s_cbranch_vccnz .LBB0_910
	s_barrier
	s_branch .LBB0_910

; #define PG8_STAGE(bufoff, gbase, voff) do { _Pragma("unroll") for (int _i = 0; _i < 2; ++_i) \
;         __builtin_amdgcn_global_load_lds((const unsigned*)((const char*)(gbase) + (voff)[_i]), (PG8_LAS unsigned*)(lds + (bufoff) + ldsw + _i * 8192), 16, 0, 0); } while (0)
; #define PG8_LDA(dst, b, h) do { _Pragma("unroll") for (int m = 0; m < 4; ++m) _Pragma("unroll") for (int k = 0; k < 2; ++k) dst[m][k] = *(const PG8_LAS bf16x8*)(lds + PG8_SA(b, h) + aoff + m * 2048 + k * 1024); } while (0)
; #define PG8_LDB(dst, b, h) do { _Pragma("unroll") for (int n = 0; n < 2; ++n) _Pragma("unroll") for (int k = 0; k < 2; ++k) dst[n][k] = *(const PG8_LAS bf16x8*)(lds + PG8_SB(b, h) + boff + n * 2048 + k * 1024); } while (0)
; #define PG8_SCHED __builtin_amdgcn_sched_barrier(0)
;     __host__ __device__ bool next(int i, Unit& u) const {
;         const long L = (long)i * G + c; if (L >= nwg) return false;
;         int wgid = (int)L; { const int q = nwg / NXCD, r = nwg % NXCD, xcd = wgid % NXCD, off = wgid / NXCD; wgid = (xcd < r ? xcd * (q + 1) : r * (q + 1) + (xcd - r) * q) + off; }
;         const int nig = WGM * nN, gid = wgid / nig, fm = gid * WGM, gsz = (nM - fm) < WGM ? (nM - fm) : WGM;
;         u.pm = fm + ((wgid % nig) % gsz); u.pn = (wgid % nig) / gsz; return true;
;     }
; template <class Epi, class Sched, bool ALIGN_EPI = false, bool SP2 = false>
; __device__ __forceinline__ void gemm_phase(PG8_LAS unsigned char* lds, const Gemm g, const Sched& S, const Epi& E) {
;     ...
;             PG8_LDB(B0, 0, 0); PG8_LDB(B1, 0, 1); PG8_SCHED; PG8_LDA(At, 0, 0); PG8_STAGE(PG8_SA(1, 1), a1 + hstep, voffA);
.LBB0_1203:
	ds_read_b128 v[128:131], v181
	ds_read_b128 v[132:135], v181 offset:1024
	ds_read_b128 v[136:139], v181 offset:2048
	ds_read_b128 v[140:143], v181 offset:3072
	ds_read_b128 v[144:147], v182
	ds_read_b128 v[166:169], v182 offset:1024
	ds_read_b128 v[170:173], v182 offset:2048
	ds_read_b128 v[174:177], v182 offset:3072
	ds_read_b128 v[184:187], v183
	ds_read_b128 v[188:191], v183 offset:1024
	ds_read_b128 v[192:195], v183 offset:2048
	ds_read_b128 v[196:199], v183 offset:3072
	ds_read_b128 v[200:203], v183 offset:4096
	ds_read_b128 v[204:207], v183 offset:5120
	ds_read_b128 v[208:211], v183 offset:6144
	ds_read_b128 v[212:215], v183 offset:7168
	s_add_i32 s63, s63, 1
	s_mul_i32 s0, s63, s66
	s_mul_hi_u32 s1, s63, s3
	s_add_i32 s1, s1, s0
	s_mul_i32 s0, s63, s3
	s_add_u32 s44, s0, s2
	s_addc_u32 s45, s1, s59
	v_cmp_gt_i64_e32 vcc, s[44:45], v[164:165]
	v_cmp_lt_i64_e64 s[0:1], s[44:45], v[162:163]
	s_cbranch_vccnz .LBB0_1209
	s_ashr_i32 s33, s44, 31
	s_lshr_b32 s33, s33, 29
	s_add_i32 s42, s44, s33
	s_and_b32 s33, s42, -8
	s_sub_i32 s43, s44, s33
	s_cmp_gt_i32 s43, -1
	s_mov_b64 s[40:41], -1
	s_cbranch_scc0 .LBB0_1206
	s_lshl_b32 s44, s43, 7
	s_mov_b64 s[40:41], 0

; #define PG8_STAGE(bufoff, gbase, voff) do { _Pragma("unroll") for (int _i = 0; _i < 2; ++_i) \
;         __builtin_amdgcn_global_load_lds((const unsigned*)((const char*)(gbase) + (voff)[_i]), (PG8_LAS unsigned*)(lds + (bufoff) + ldsw + _i * 8192), 16, 0, 0); } while (0)
; #define PG8_LDA(dst, b, h) do { _Pragma("unroll") for (int m = 0; m < 4; ++m) _Pragma("unroll") for (int k = 0; k < 2; ++k) dst[m][k] = *(const PG8_LAS bf16x8*)(lds + PG8_SA(b, h) + aoff + m * 2048 + k * 1024); } while (0)
; #define PG8_LDB(dst, b, h) do { _Pragma("unroll") for (int n = 0; n < 2; ++n) _Pragma("unroll") for (int k = 0; k < 2; ++k) dst[n][k] = *(const PG8_LAS bf16x8*)(lds + PG8_SB(b, h) + boff + n * 2048 + k * 1024); } while (0)
; #define PG8_WAIT_V(n) asm volatile("s_waitcnt vmcnt(" #n ")" ::: "memory")
; #define PG8_WAIT_L(n) asm volatile("s_waitcnt lgkmcnt(" #n ")" ::: "memory")
; #define PG8_BAR __builtin_amdgcn_s_barrier()
; #define PG8_SCHED __builtin_amdgcn_sched_barrier(0)
; template <class Epi, class Sched, bool ALIGN_EPI = false, bool SP2 = false>
; __device__ __forceinline__ void gemm_phase(PG8_LAS unsigned char* lds, const Gemm g, const Sched& S, const Epi& E) {
;     ...
;         const char* nA = has_next ? (const char*)g.A + (size_t)nxt.pm * tstep : cA; const char* nB = has_next ? (const char*)g.Bt + (size_t)nxt.pn * tstep : cB;
;         for (int t = 0; t < nt; t += 2) {
;             const bool last = (t == nt - 2);
;             const char* a1 = cA + (size_t)(t + 1) * kstep;
;             const char* a2 = last ? nA : cA + (size_t)(t + 2) * kstep; const char* b2 = last ? nB : cB + (size_t)(t + 2) * kstep;
;             const char* a3 = a2 + kstep; const char* b3 = b2 + kstep;
;             if (last && has_next) S.a_ready(nxt);
;             if constexpr (SP2) {
;             PG8_LDB(B0, 0, 0); PG8_LDB(B1, 0, 1); PG8_SCHED; PG8_LDA(At, 0, 0); PG8_STAGE(PG8_SA(1, 1), a1 + hstep, voffA);
;             PG8_WAIT_V(8); PG8_WAIT_L(0); PG8_BAR; PG8_MMA(0, 0, At, B0); PG8_MMA(0, 1, At, B1); PG8_BAR; PG8_SCHED;
;             PG8_LDA(At, 0, 1); PG8_STAGE(PG8_SB(0, 0), b2, voffB); PG8_STAGE(PG8_SB(0, 1), b2 + hstep, voffB); PG8_STAGE(PG8_SA(0, 0), a2, voffA);
;             PG8_WAIT_V(8); PG8_WAIT_L(0); PG8_BAR; PG8_MMA(1, 0, At, B0); PG8_MMA(1, 1, At, B1); PG8_BAR; PG8_SCHED;
.LBB0_1209:
	s_ashr_i32 s43, s42, 31
	s_lshl_b64 s[44:45], s[42:43], 19
	s_add_u32 s44, s16, s44
	s_addc_u32 s45, s17, s45
	s_and_b64 s[46:47], s[0:1], exec
	s_cselect_b32 s43, s45, s5
	s_cselect_b32 s76, s44, s4
	s_ashr_i32 s41, s40, 31
	s_lshl_b64 s[46:47], s[40:41], 19
	s_add_u32 s46, s56, s46
	s_addc_u32 s47, s57, s47
	s_and_b64 s[54:55], s[0:1], exec
	s_cselect_b32 s41, s47, s53
	s_cselect_b32 s77, s46, s52
	s_add_u32 s4, s4, 0x40080
	s_addc_u32 s5, s5, 0
	s_add_u32 s78, s52, 0x100
	s_addc_u32 s79, s53, 0
	s_mov_b32 s80, -2
	s_waitcnt lgkmcnt(0)
	s_add_u32 s33, s4, 0xfffc0080
	s_addc_u32 s34, s5, -1
	s_cmp_eq_u32 s80, 12
	s_cselect_b32 s55, s43, s34
	s_cselect_b32 s54, s76, s33
	s_cselect_b32 s53, s41, s79
	s_cselect_b32 s52, s77, s78
	s_add_i32 m0, s49, 0xc000
	global_load_lds_dwordx4 v158, s[4:5]
	s_add_i32 m0, s49, 0xe000
	s_nop 0
	global_load_lds_dwordx4 v160, s[4:5]
	s_waitcnt vmcnt(8)
	s_waitcnt lgkmcnt(0)
	s_barrier
	s_setprio 1
	s_waitcnt lgkmcnt(0)
	v_mfma_f32_16x16x32_bf16 v[124:127], v[128:131], v[184:187], 0
	v_mfma_f32_16x16x32_bf16 v[120:123], v[136:139], v[184:187], 0
	v_mfma_f32_16x16x32_bf16 v[116:119], v[128:131], v[192:195], 0
	v_mfma_f32_16x16x32_bf16 v[112:115], v[136:139], v[192:195], 0
	v_mfma_f32_16x16x32_bf16 v[108:111], v[128:131], v[200:203], 0
	v_mfma_f32_16x16x32_bf16 v[104:107], v[136:139], v[200:203], 0
	v_mfma_f32_16x16x32_bf16 v[100:103], v[128:131], v[208:211], 0
	v_mfma_f32_16x16x32_bf16 v[96:99], v[136:139], v[208:211], 0
	v_mfma_f32_16x16x32_bf16 v[124:127], v[132:135], v[188:191], v[124:127]
	v_mfma_f32_16x16x32_bf16 v[120:123], v[140:143], v[188:191], v[120:123]
	v_mfma_f32_16x16x32_bf16 v[116:119], v[132:135], v[196:199], v[116:119]
	v_mfma_f32_16x16x32_bf16 v[112:115], v[140:143], v[196:199], v[112:115]
	v_mfma_f32_16x16x32_bf16 v[108:111], v[132:135], v[204:207], v[108:111]
	v_mfma_f32_16x16x32_bf16 v[104:107], v[140:143], v[204:207], v[104:107]
	v_mfma_f32_16x16x32_bf16 v[100:103], v[132:135], v[212:215], v[100:103]
	v_mfma_f32_16x16x32_bf16 v[96:99], v[140:143], v[212:215], v[96:99]
	s_setprio 0
	s_setprio 1
	v_mfma_f32_16x16x32_bf16 v[60:63], v[144:147], v[184:187], 0
	v_mfma_f32_16x16x32_bf16 v[56:59], v[170:173], v[184:187], 0
	v_mfma_f32_16x16x32_bf16 v[52:55], v[144:147], v[192:195], 0
	v_mfma_f32_16x16x32_bf16 v[48:51], v[170:173], v[192:195], 0
	v_mfma_f32_16x16x32_bf16 v[44:47], v[144:147], v[200:203], 0
	v_mfma_f32_16x16x32_bf16 v[40:43], v[170:173], v[200:203], 0
	v_mfma_f32_16x16x32_bf16 v[36:39], v[144:147], v[208:211], 0
	v_mfma_f32_16x16x32_bf16 v[32:35], v[170:173], v[208:211], 0
	v_mfma_f32_16x16x32_bf16 v[60:63], v[166:169], v[188:191], v[60:63]
	v_mfma_f32_16x16x32_bf16 v[56:59], v[174:177], v[188:191], v[56:59]
	v_mfma_f32_16x16x32_bf16 v[52:55], v[166:169], v[196:199], v[52:55]
	v_mfma_f32_16x16x32_bf16 v[48:51], v[174:177], v[196:199], v[48:51]
	v_mfma_f32_16x16x32_bf16 v[44:47], v[166:169], v[204:207], v[44:47]
	v_mfma_f32_16x16x32_bf16 v[40:43], v[174:177], v[204:207], v[40:43]
	v_mfma_f32_16x16x32_bf16 v[36:39], v[166:169], v[212:215], v[36:39]
	v_mfma_f32_16x16x32_bf16 v[32:35], v[174:177], v[212:215], v[32:35]
	s_setprio 0
	s_barrier
	s_add_i32 s33, s69, s58
	s_add_u32 s86, s52, s20
	s_addc_u32 s87, s53, s21
	s_mov_b32 m0, s33
	ds_read_b128 v[184:187], v183 offset:16384
	ds_read_b128 v[188:191], v183 offset:17408
	ds_read_b128 v[192:195], v183 offset:18432
	ds_read_b128 v[196:199], v183 offset:19456
	ds_read_b128 v[200:203], v183 offset:20480
	ds_read_b128 v[204:207], v183 offset:21504
	ds_read_b128 v[208:211], v183 offset:22528
	ds_read_b128 v[212:215], v183 offset:23552
	global_load_lds_dwordx4 v150, s[52:53]
	s_add_i32 m0, s33, 0x2000
	s_add_u32 s82, s52, 0x40000
	s_addc_u32 s83, s53, 0
	s_add_i32 s33, s70, s58
	global_load_lds_dwordx4 v156, s[52:53]
	s_mov_b32 m0, s33
	s_add_u32 s88, s54, s20
	s_addc_u32 s89, s55, s21
	global_load_lds_dwordx4 v150, s[82:83]
	s_add_i32 m0, s33, 0x2000
	s_nop 0
	global_load_lds_dwordx4 v156, s[82:83]
	s_mov_b32 m0, s49
	s_nop 0
	global_load_lds_dwordx4 v148, s[54:55]
	s_mov_b32 m0, s60
	s_nop 0
	global_load_lds_dwordx4 v154, s[54:55]
	s_waitcnt vmcnt(8)
	s_waitcnt lgkmcnt(0)
	s_barrier
	s_setprio 1
	s_waitcnt lgkmcnt(0)
	v_mfma_f32_16x16x32_bf16 v[92:95], v[128:131], v[184:187], 0
	v_mfma_f32_16x16x32_bf16 v[88:91], v[136:139], v[184:187], 0
	v_mfma_f32_16x16x32_bf16 v[84:87], v[128:131], v[192:195], 0
	v_mfma_f32_16x16x32_bf16 v[80:83], v[136:139], v[192:195], 0
	v_mfma_f32_16x16x32_bf16 v[76:79], v[128:131], v[200:203], 0
	v_mfma_f32_16x16x32_bf16 v[72:75], v[136:139], v[200:203], 0
	v_mfma_f32_16x16x32_bf16 v[68:71], v[128:131], v[208:211], 0
	v_mfma_f32_16x16x32_bf16 v[64:67], v[136:139], v[208:211], 0
	v_mfma_f32_16x16x32_bf16 v[92:95], v[132:135], v[188:191], v[92:95]
	v_mfma_f32_16x16x32_bf16 v[88:91], v[140:143], v[188:191], v[88:91]
	v_mfma_f32_16x16x32_bf16 v[84:87], v[132:135], v[196:199], v[84:87]
	v_mfma_f32_16x16x32_bf16 v[80:83], v[140:143], v[196:199], v[80:83]
	v_mfma_f32_16x16x32_bf16 v[76:79], v[132:135], v[204:207], v[76:79]
	v_mfma_f32_16x16x32_bf16 v[72:75], v[140:143], v[204:207], v[72:75]
	v_mfma_f32_16x16x32_bf16 v[68:71], v[132:135], v[212:215], v[68:71]
	v_mfma_f32_16x16x32_bf16 v[64:67], v[140:143], v[212:215], v[64:67]
	s_setprio 0
	s_setprio 1
	v_mfma_f32_16x16x32_bf16 v[28:31], v[144:147], v[184:187], 0
	v_mfma_f32_16x16x32_bf16 v[24:27], v[170:173], v[184:187], 0
	v_mfma_f32_16x16x32_bf16 v[20:23], v[144:147], v[192:195], 0
	v_mfma_f32_16x16x32_bf16 v[16:19], v[170:173], v[192:195], 0
	v_mfma_f32_16x16x32_bf16 v[12:15], v[144:147], v[200:203], 0
	v_mfma_f32_16x16x32_bf16 v[8:11], v[170:173], v[200:203], 0
	v_mfma_f32_16x16x32_bf16 v[4:7], v[144:147], v[208:211], 0
	v_mfma_f32_16x16x32_bf16 v[0:3], v[170:173], v[208:211], 0
	v_mfma_f32_16x16x32_bf16 v[28:31], v[166:169], v[188:191], v[28:31]
	v_mfma_f32_16x16x32_bf16 v[24:27], v[174:177], v[188:191], v[24:27]
	v_mfma_f32_16x16x32_bf16 v[20:23], v[166:169], v[196:199], v[20:23]
	v_mfma_f32_16x16x32_bf16 v[16:19], v[174:177], v[196:199], v[16:19]
	v_mfma_f32_16x16x32_bf16 v[12:15], v[166:169], v[204:207], v[12:15]
	v_mfma_f32_16x16x32_bf16 v[8:11], v[174:177], v[204:207], v[8:11]
	v_mfma_f32_16x16x32_bf16 v[4:7], v[166:169], v[212:215], v[4:7]
	v_mfma_f32_16x16x32_bf16 v[0:3], v[174:177], v[212:215], v[0:3]
	s_setprio 0
	s_barrier
; #define PG8_STAGE(bufoff, gbase, voff) do { _Pragma("unroll") for (int _i = 0; _i < 2; ++_i) \
;         __builtin_amdgcn_global_load_lds((const unsigned*)((const char*)(gbase) + (voff)[_i]), (PG8_LAS unsigned*)(lds + (bufoff) + ldsw + _i * 8192), 16, 0, 0); } while (0)
; #define PG8_LDA(dst, b, h) do { _Pragma("unroll") for (int m = 0; m < 4; ++m) _Pragma("unroll") for (int k = 0; k < 2; ++k) dst[m][k] = *(const PG8_LAS bf16x8*)(lds + PG8_SA(b, h) + aoff + m * 2048 + k * 1024); } while (0)
; #define PG8_LDB(dst, b, h) do { _Pragma("unroll") for (int n = 0; n < 2; ++n) _Pragma("unroll") for (int k = 0; k < 2; ++k) dst[n][k] = *(const PG8_LAS bf16x8*)(lds + PG8_SB(b, h) + boff + n * 2048 + k * 1024); } while (0)
; #define PG8_MMA(ai, bj, At, Bt) do { __builtin_amdgcn_s_setprio(1); _Pragma("unroll") for (int m = 0; m < 4; ++m) _Pragma("unroll") for (int n = 0; n < 2; ++n) _Pragma("unroll") for (int k = 0; k < 2; ++k) \
;         acc[ai][bj][m][n] = __builtin_amdgcn_mfma_f32_16x16x32_bf16(Bt[n][k], At[m][k], acc[ai][bj][m][n], 0, 0, 0); __builtin_amdgcn_s_setprio(0); } while (0)
; #define PG8_WAIT_V(n) asm volatile("s_waitcnt vmcnt(" #n ")" ::: "memory")
; #define PG8_WAIT_L(n) asm volatile("s_waitcnt lgkmcnt(" #n ")" ::: "memory")
; #define PG8_BAR __builtin_amdgcn_s_barrier()
; #define PG8_SCHED __builtin_amdgcn_sched_barrier(0)
; template <class Epi, class Sched, bool ALIGN_EPI = false, bool SP2 = false>
; __device__ __forceinline__ void gemm_phase(PG8_LAS unsigned char* lds, const Gemm g, const Sched& S, const Epi& E) {
;     ...
;             PG8_LDB(B0, 1, 0); PG8_LDB(B1, 1, 1); PG8_SCHED; PG8_LDA(At, 1, 0); PG8_STAGE(PG8_SA(0, 1), a2 + hstep, voffA);
;             PG8_WAIT_V(8); PG8_WAIT_L(0); PG8_BAR; PG8_MMA(0, 0, At, B0); PG8_MMA(0, 1, At, B1); PG8_BAR; PG8_SCHED;
;             PG8_LDA(At, 1, 1); PG8_STAGE(PG8_SB(1, 0), b3, voffB); PG8_STAGE(PG8_SB(1, 1), b3 + hstep, voffB); PG8_STAGE(PG8_SA(1, 0), a3, voffA);
;             PG8_WAIT_V(8); PG8_WAIT_L(0); PG8_BAR; PG8_MMA(1, 0, At, B0); PG8_MMA(1, 1, At, B1); PG8_BAR; PG8_SCHED;
	s_add_i32 s33, 0, 0x18000
	s_add_i32 s34, 0, 0x1c000
	v_add_u32_e32 v140, s33, v179
	v_add_u32_e32 v153, s34, v179
	ds_read_b128 v[128:131], v140
	ds_read_b128 v[132:135], v140 offset:1024
	ds_read_b128 v[136:139], v140 offset:2048
	ds_read_b128 v[140:143], v140 offset:3072
	ds_read_b128 v[144:147], v153
	ds_read_b128 v[166:169], v153 offset:1024
	ds_read_b128 v[170:173], v153 offset:2048
	ds_read_b128 v[174:177], v153 offset:3072
	s_add_u32 s54, s54, 0x40000
	s_addc_u32 s55, s55, 0
	s_mov_b32 m0, s61
	ds_read_b128 v[184:187], v183 offset:32768
	ds_read_b128 v[188:191], v183 offset:33792
	ds_read_b128 v[192:195], v183 offset:34816
	ds_read_b128 v[196:199], v183 offset:35840
	ds_read_b128 v[200:203], v183 offset:36864
	ds_read_b128 v[204:207], v183 offset:37888
	ds_read_b128 v[208:211], v183 offset:38912
	ds_read_b128 v[212:215], v183 offset:39936
	global_load_lds_dwordx4 v148, s[54:55]
	s_mov_b32 m0, s62
	s_nop 0
	global_load_lds_dwordx4 v154, s[54:55]
	s_waitcnt vmcnt(8)
	s_waitcnt lgkmcnt(0)
	s_barrier
	s_setprio 1
	s_waitcnt lgkmcnt(0)
	v_mfma_f32_16x16x32_bf16 v[124:127], v[128:131], v[184:187], v[124:127]
	v_mfma_f32_16x16x32_bf16 v[120:123], v[136:139], v[184:187], v[120:123]
	v_mfma_f32_16x16x32_bf16 v[116:119], v[128:131], v[192:195], v[116:119]
	v_mfma_f32_16x16x32_bf16 v[112:115], v[136:139], v[192:195], v[112:115]
	v_mfma_f32_16x16x32_bf16 v[108:111], v[128:131], v[200:203], v[108:111]
	v_mfma_f32_16x16x32_bf16 v[104:107], v[136:139], v[200:203], v[104:107]
	v_mfma_f32_16x16x32_bf16 v[100:103], v[128:131], v[208:211], v[100:103]
	v_mfma_f32_16x16x32_bf16 v[96:99], v[136:139], v[208:211], v[96:99]
	v_mfma_f32_16x16x32_bf16 v[124:127], v[132:135], v[188:191], v[124:127]
	v_mfma_f32_16x16x32_bf16 v[120:123], v[140:143], v[188:191], v[120:123]
	v_mfma_f32_16x16x32_bf16 v[116:119], v[132:135], v[196:199], v[116:119]
	v_mfma_f32_16x16x32_bf16 v[112:115], v[140:143], v[196:199], v[112:115]
	v_mfma_f32_16x16x32_bf16 v[108:111], v[132:135], v[204:207], v[108:111]
	v_mfma_f32_16x16x32_bf16 v[104:107], v[140:143], v[204:207], v[104:107]
	v_mfma_f32_16x16x32_bf16 v[100:103], v[132:135], v[212:215], v[100:103]
	v_mfma_f32_16x16x32_bf16 v[96:99], v[140:143], v[212:215], v[96:99]
	s_setprio 0
	s_setprio 1
	v_mfma_f32_16x16x32_bf16 v[60:63], v[144:147], v[184:187], v[60:63]
	v_mfma_f32_16x16x32_bf16 v[56:59], v[170:173], v[184:187], v[56:59]
	v_mfma_f32_16x16x32_bf16 v[52:55], v[144:147], v[192:195], v[52:55]
	v_mfma_f32_16x16x32_bf16 v[48:51], v[170:173], v[192:195], v[48:51]
	v_mfma_f32_16x16x32_bf16 v[44:47], v[144:147], v[200:203], v[44:47]
	v_mfma_f32_16x16x32_bf16 v[40:43], v[170:173], v[200:203], v[40:43]
	v_mfma_f32_16x16x32_bf16 v[36:39], v[144:147], v[208:211], v[36:39]
	v_mfma_f32_16x16x32_bf16 v[32:35], v[170:173], v[208:211], v[32:35]
	v_mfma_f32_16x16x32_bf16 v[60:63], v[166:169], v[188:191], v[60:63]
	v_mfma_f32_16x16x32_bf16 v[56:59], v[174:177], v[188:191], v[56:59]
	v_mfma_f32_16x16x32_bf16 v[52:55], v[166:169], v[196:199], v[52:55]
	v_mfma_f32_16x16x32_bf16 v[48:51], v[174:177], v[196:199], v[48:51]
	v_mfma_f32_16x16x32_bf16 v[44:47], v[166:169], v[204:207], v[44:47]
	v_mfma_f32_16x16x32_bf16 v[40:43], v[174:177], v[204:207], v[40:43]
	v_mfma_f32_16x16x32_bf16 v[36:39], v[166:169], v[212:215], v[36:39]
	v_mfma_f32_16x16x32_bf16 v[32:35], v[174:177], v[212:215], v[32:35]
	s_setprio 0
	s_barrier
	s_add_i32 s33, s33, s58
	s_mov_b32 m0, s33
	ds_read_b128 v[184:187], v183 offset:49152
	ds_read_b128 v[188:191], v183 offset:50176
	ds_read_b128 v[192:195], v183 offset:51200
	ds_read_b128 v[196:199], v183 offset:52224
	ds_read_b128 v[200:203], v183 offset:53248
	ds_read_b128 v[204:207], v183 offset:54272
	ds_read_b128 v[208:211], v183 offset:55296
	ds_read_b128 v[212:215], v183 offset:56320
	global_load_lds_dwordx4 v150, s[86:87]
	s_add_i32 m0, s33, 0x2000
	s_add_u32 s52, s52, 0x40080
	s_addc_u32 s53, s53, 0
	s_add_i32 s33, s34, s58
	global_load_lds_dwordx4 v156, s[86:87]
	s_mov_b32 m0, s33
	s_nop 0
	global_load_lds_dwordx4 v150, s[52:53]
	s_add_i32 m0, s33, 0x2000
	s_nop 0
	global_load_lds_dwordx4 v156, s[52:53]
	s_mov_b32 m0, s67
	s_nop 0
	global_load_lds_dwordx4 v148, s[88:89]
	s_mov_b32 m0, s68
	s_nop 0
	global_load_lds_dwordx4 v154, s[88:89]
	s_waitcnt vmcnt(8)
	s_waitcnt lgkmcnt(0)
	s_barrier
	s_setprio 1
	s_waitcnt lgkmcnt(0)
	v_mfma_f32_16x16x32_bf16 v[92:95], v[128:131], v[184:187], v[92:95]
	v_mfma_f32_16x16x32_bf16 v[88:91], v[136:139], v[184:187], v[88:91]
	v_mfma_f32_16x16x32_bf16 v[84:87], v[128:131], v[192:195], v[84:87]
	v_mfma_f32_16x16x32_bf16 v[80:83], v[136:139], v[192:195], v[80:83]
	v_mfma_f32_16x16x32_bf16 v[76:79], v[128:131], v[200:203], v[76:79]
	v_mfma_f32_16x16x32_bf16 v[72:75], v[136:139], v[200:203], v[72:75]
	v_mfma_f32_16x16x32_bf16 v[68:71], v[128:131], v[208:211], v[68:71]
	v_mfma_f32_16x16x32_bf16 v[64:67], v[136:139], v[208:211], v[64:67]
	v_mfma_f32_16x16x32_bf16 v[92:95], v[132:135], v[188:191], v[92:95]
	v_mfma_f32_16x16x32_bf16 v[88:91], v[140:143], v[188:191], v[88:91]
	v_mfma_f32_16x16x32_bf16 v[84:87], v[132:135], v[196:199], v[84:87]
	v_mfma_f32_16x16x32_bf16 v[80:83], v[140:143], v[196:199], v[80:83]
	v_mfma_f32_16x16x32_bf16 v[76:79], v[132:135], v[204:207], v[76:79]
	v_mfma_f32_16x16x32_bf16 v[72:75], v[140:143], v[204:207], v[72:75]
	v_mfma_f32_16x16x32_bf16 v[68:71], v[132:135], v[212:215], v[68:71]
	v_mfma_f32_16x16x32_bf16 v[64:67], v[140:143], v[212:215], v[64:67]
	s_setprio 0
	s_setprio 1
	v_mfma_f32_16x16x32_bf16 v[28:31], v[144:147], v[184:187], v[28:31]
	v_mfma_f32_16x16x32_bf16 v[24:27], v[170:173], v[184:187], v[24:27]
	v_mfma_f32_16x16x32_bf16 v[20:23], v[144:147], v[192:195], v[20:23]
	v_mfma_f32_16x16x32_bf16 v[16:19], v[170:173], v[192:195], v[16:19]
	v_mfma_f32_16x16x32_bf16 v[12:15], v[144:147], v[200:203], v[12:15]
	v_mfma_f32_16x16x32_bf16 v[8:11], v[170:173], v[200:203], v[8:11]
	v_mfma_f32_16x16x32_bf16 v[4:7], v[144:147], v[208:211], v[4:7]
	v_mfma_f32_16x16x32_bf16 v[0:3], v[170:173], v[208:211], v[0:3]
	v_mfma_f32_16x16x32_bf16 v[28:31], v[166:169], v[188:191], v[28:31]
	v_mfma_f32_16x16x32_bf16 v[24:27], v[174:177], v[188:191], v[24:27]
	v_mfma_f32_16x16x32_bf16 v[20:23], v[166:169], v[196:199], v[20:23]
	v_mfma_f32_16x16x32_bf16 v[16:19], v[174:177], v[196:199], v[16:19]
	v_mfma_f32_16x16x32_bf16 v[12:15], v[166:169], v[204:207], v[12:15]
	v_mfma_f32_16x16x32_bf16 v[8:11], v[174:177], v[204:207], v[8:11]
	v_mfma_f32_16x16x32_bf16 v[4:7], v[166:169], v[212:215], v[4:7]
	v_mfma_f32_16x16x32_bf16 v[0:3], v[174:177], v[212:215], v[0:3]
	s_setprio 0
	s_barrier
	s_add_i32 s80, s80, 2
	s_add_u32 s4, s4, 0x100
	s_addc_u32 s5, s5, 0
	s_add_u32 s78, s78, 0x100
	s_addc_u32 s79, s79, 0
	s_cmp_gt_u32 s80, 13

; #define PG8_STAGE(bufoff, gbase, voff) do { _Pragma("unroll") for (int _i = 0; _i < 2; ++_i) \
;         __builtin_amdgcn_global_load_lds((const unsigned*)((const char*)(gbase) + (voff)[_i]), (PG8_LAS unsigned*)(lds + (bufoff) + ldsw + _i * 8192), 16, 0, 0); } while (0)
; #define PG8_WAIT_V(n) asm volatile("s_waitcnt vmcnt(" #n ")" ::: "memory")
; #define PG8_BAR __builtin_amdgcn_s_barrier()
; template <class Epi, class Sched, bool ALIGN_EPI = false, bool SP2 = false>
; __device__ __forceinline__ void gemm_phase(PG8_LAS unsigned char* lds, const Gemm g, const Sched& S, const Epi& E) {
;     ...
;     for (int i = 0; i < 2; ++i) { int R, C; stage_rc(tid * 16 + i * 8192, R, C); const int Rb = Epi::PERM ? ((R & ~31) + perm32(R & 31)) : R;
;         voffA[i] = (unsigned)(R * K + C) * 2u; voffB[i] = (unsigned)(Rb * K + C) * 2u; }
;     const size_t kstep = (size_t)(BK * 2);
;     const size_t hstep = (size_t)HALF * K * 2;
;     const size_t tstep = 2 * hstep;
;     const unsigned ldsw = (unsigned)wid * 1024u;
;     const int aoff = lds_byte(wr * 64 + fr, fq * 8), boff = lds_byte(wc * 32 + fr, fq * 8);
;     ...
;         PG8_STAGE(PG8_SB(1, 0), cB + kstep, voffB); PG8_STAGE(PG8_SA(1, 0), cA + kstep, voffA); PG8_STAGE(PG8_SB(1, 1), cB + hstep + kstep, voffB);
;         PG8_WAIT_V(6); PG8_BAR;
.LBB0_1336:
	s_add_u32 s8, s28, 0xfa00000
	s_addc_u32 s9, s29, 0
	s_lshl_b32 s10, s10, 5
	s_and_b32 s18, s10, 0x60
	s_mov_b64 s[10:11], 0x80
	s_add_i32 m0, s25, 0x18000
	v_lshl_add_u64 v[6:7], v[6:7], 0, s[10:11]
	s_ashr_i32 s51, s3, 31
	s_lshl_b32 s13, s12, 13
	s_lshl_b32 s19, s18, 7
	s_waitcnt vmcnt(2)
	s_barrier
	global_load_lds_dwordx4 v[6:7], off
	v_lshl_add_u64 v[4:5], v[4:5], 0, s[10:11]
	s_add_i32 m0, s25, 0x1a000
	s_add_i32 s52, s25, 0x8000
	s_add_i32 s53, s25, 0xa000
	global_load_lds_dwordx4 v[4:5], off
	v_lshl_add_u64 v[0:1], v[0:1], 0, s[10:11]
	s_mov_b32 m0, s52
	s_add_u32 s14, s38, 0x40080
	global_load_lds_dwordx4 v[0:1], off
	v_lshl_add_u64 v[0:1], v[2:3], 0, s[10:11]
	s_mov_b32 m0, s53
	s_addc_u32 s15, s39, 0
	global_load_lds_dwordx4 v[0:1], off
	s_add_i32 m0, s25, 0x1c000
	v_lshl_add_u64 v[0:1], s[14:15], 0, v[130:131]
	global_load_lds_dwordx4 v[0:1], off
	v_lshl_add_u64 v[0:1], s[14:15], 0, v[134:135]
	s_add_i32 m0, s25, 0x1e000
	s_sext_i32_i16 s57, s0
	global_load_lds_dwordx4 v[0:1], off
	v_and_b32_e32 v0, 15, v152
	v_lshlrev_b32_e32 v1, 1, v11
	v_lshlrev_b32_e32 v2, 6, v152
	s_movk_i32 s0, 0x3c0
	v_lshlrev_b32_e32 v3, 2, v152
	v_and_or_b32 v2, v2, s0, v1
	v_and_b32_e32 v3, 32, v3
	v_lshl_or_b32 v144, s12, 6, v0
	v_lshl_or_b32 v0, v0, 6, v1
	v_lshlrev_b32_e32 v1, 8, v152
	v_bitop3_b32 v145, s19, v2, v3 bitop3:0xf6
	v_and_b32_e32 v1, 0x38000, v1
	v_lshlrev_b32_e32 v2, 11, v10
	v_or3_b32 v1, v8, v1, v2
	v_add_u32_e32 v136, v1, v9
	v_lshlrev_b32_e32 v1, 4, v12
	s_waitcnt vmcnt(6)
	s_cmpk_lt_u32 s1, 0x100
	v_and_b32_e32 v1, 0x78000, v1
	v_bitop3_b32 v0, v0, s13, v3 bitop3:0xde
	s_cselect_b64 s[12:13], -1, 0
	v_or3_b32 v1, v8, v1, v2
	s_add_i32 s54, 0, 0x10000
	s_add_i32 s55, 0, 0x14000
	v_or_b32_e32 v146, s18, v11
	v_mov_b32_e32 v137, v131
	v_add_u32_e32 v138, v1, v9
	v_mov_b32_e32 v139, v131
	v_mov_b64_e32 v[140:141], 0x1600
	v_mov_b64_e32 v[142:143], 0x15ff
	v_add_u32_e32 v147, s54, v145
	v_add_u32_e32 v148, s55, v145
	v_add_u32_e32 v149, 0, v0
	s_movk_i32 s56, 0x1600
	s_barrier
	s_mov_b32 s77, 0
	s_branch .LBB0_1339

; #define PG8_STAGE(bufoff, gbase, voff) do { _Pragma("unroll") for (int _i = 0; _i < 2; ++_i) \
;         __builtin_amdgcn_global_load_lds((const unsigned*)((const char*)(gbase) + (voff)[_i]), (PG8_LAS unsigned*)(lds + (bufoff) + ldsw + _i * 8192), 16, 0, 0); } while (0)
; #define PG8_LDA(dst, b, h) do { _Pragma("unroll") for (int m = 0; m < 4; ++m) _Pragma("unroll") for (int k = 0; k < 2; ++k) dst[m][k] = *(const PG8_LAS bf16x8*)(lds + PG8_SA(b, h) + aoff + m * 2048 + k * 1024); } while (0)
; #define PG8_LDB(dst, b, h) do { _Pragma("unroll") for (int n = 0; n < 2; ++n) _Pragma("unroll") for (int k = 0; k < 2; ++k) dst[n][k] = *(const PG8_LAS bf16x8*)(lds + PG8_SB(b, h) + boff + n * 2048 + k * 1024); } while (0)
; #define PG8_MMA(ai, bj, At, Bt) do { __builtin_amdgcn_s_setprio(1); _Pragma("unroll") for (int m = 0; m < 4; ++m) _Pragma("unroll") for (int n = 0; n < 2; ++n) _Pragma("unroll") for (int k = 0; k < 2; ++k) \
;         acc[ai][bj][m][n] = __builtin_amdgcn_mfma_f32_16x16x32_bf16(Bt[n][k], At[m][k], acc[ai][bj][m][n], 0, 0, 0); __builtin_amdgcn_s_setprio(0); } while (0)
; #define PG8_WAIT_V(n) asm volatile("s_waitcnt vmcnt(" #n ")" ::: "memory")
; #define PG8_WAIT_L(n) asm volatile("s_waitcnt lgkmcnt(" #n ")" ::: "memory")
; #define PG8_BAR __builtin_amdgcn_s_barrier()
; #define PG8_SCHED __builtin_amdgcn_sched_barrier(0)
;     __host__ __device__ bool next(int i, Unit& u) const {
;         const long L = (long)i * G + c; if (L >= nwg) return false;
;         int wgid = (int)L; { const int q = nwg / NXCD, r = nwg % NXCD, xcd = wgid % NXCD, off = wgid / NXCD; wgid = (xcd < r ? xcd * (q + 1) : r * (q + 1) + (xcd - r) * q) + off; }
;         const int nig = WGM * nN, gid = wgid / nig, fm = gid * WGM, gsz = (nM - fm) < WGM ? (nM - fm) : WGM;
;         u.pm = fm + ((wgid % nig) % gsz); u.pn = (wgid % nig) / gsz; return true;
;     }
; template <class Epi, class Sched, bool ALIGN_EPI = false, bool SP2 = false>
; __device__ __forceinline__ void gemm_phase(PG8_LAS unsigned char* lds, const Gemm g, const Sched& S, const Epi& E) {
;     ...
;             PG8_LDB(B0, 0, 0); PG8_LDB(B1, 0, 1); PG8_SCHED; PG8_LDA(At, 0, 0); PG8_STAGE(PG8_SA(1, 1), a1 + hstep, voffA);
;             PG8_WAIT_V(8); PG8_WAIT_L(0); PG8_BAR; PG8_MMA(0, 0, At, B0); PG8_MMA(0, 1, At, B1); PG8_BAR; PG8_SCHED;
.LBB0_1339:
	ds_read_b128 v[154:157], v147
	ds_read_b128 v[158:161], v147 offset:1024
	ds_read_b128 v[162:165], v147 offset:2048
	ds_read_b128 v[166:169], v147 offset:3072
	ds_read_b128 v[170:173], v148
	ds_read_b128 v[174:177], v148 offset:1024
	ds_read_b128 v[178:181], v148 offset:2048
	ds_read_b128 v[182:185], v148 offset:3072
	ds_read_b128 v[186:189], v149
	ds_read_b128 v[190:193], v149 offset:1024
	ds_read_b128 v[194:197], v149 offset:2048
	ds_read_b128 v[198:201], v149 offset:3072
	ds_read_b128 v[202:205], v149 offset:4096
	ds_read_b128 v[206:209], v149 offset:5120
	ds_read_b128 v[210:213], v149 offset:6144
	ds_read_b128 v[214:217], v149 offset:7168
	s_add_i32 s50, s50, 1
	s_mul_i32 s0, s50, s51
	s_mul_hi_u32 s1, s50, s3
	s_add_i32 s1, s1, s0
	s_mul_i32 s0, s50, s3
	s_add_u32 s20, s0, s2
	s_addc_u32 s21, s1, s45
	v_cmp_gt_i64_e32 vcc, s[20:21], v[142:143]
	v_cmp_lt_i64_e64 s[0:1], s[20:21], v[140:141]
	s_cbranch_vccnz .LBB0_1341
	s_ashr_i32 s14, s20, 31
	s_lshr_b32 s14, s14, 29
	s_add_i32 s14, s20, s14
	s_ashr_i32 s15, s14, 3
	s_and_b32 s14, s14, -8
	s_sub_i32 s14, s20, s14
	s_cmp_lt_i32 s14, 0
	s_cselect_b32 s18, s46, 0x2c0
	s_mul_i32 s14, s14, s18
	s_add_i32 s14, s14, s15
	s_mul_hi_i32 s15, s14, 0x2e8ba2e9
	s_lshr_b32 s18, s15, 31
	s_ashr_i32 s15, s15, 5
	s_add_i32 s15, s15, s18
	s_lshl_b32 s18, s15, 3
	s_sub_i32 s19, 0x100, s18
	s_min_i32 s19, s19, 8
	s_abs_i32 s20, s19
	v_cvt_f32_u32_e32 v0, s20
	s_sub_i32 s22, 0, s20
	s_mulk_i32 s15, 0xb0
	s_sub_i32 s15, s14, s15
	v_rcp_iflag_f32_e32 v0, v0
	s_abs_i32 s14, s15
	s_xor_b32 s21, s15, s19
	s_ashr_i32 s21, s21, 31
	v_mul_f32_e32 v0, 0x4f7ffffe, v0
	v_cvt_u32_f32_e32 v0, v0
	s_nop 0
	v_readfirstlane_b32 s23, v0
	s_mul_i32 s22, s22, s23
	s_mul_hi_u32 s22, s23, s22
	s_add_i32 s23, s23, s22
	s_mul_hi_u32 s22, s14, s23
	s_mul_i32 s23, s22, s20
	s_sub_i32 s14, s14, s23
	s_add_i32 s33, s22, 1
	s_sub_i32 s23, s14, s20
	s_cmp_ge_u32 s14, s20
	s_cselect_b32 s22, s33, s22
	s_cselect_b32 s14, s23, s14
	s_add_i32 s23, s22, 1
	s_cmp_ge_u32 s14, s20
	s_cselect_b32 s14, s23, s22
	s_xor_b32 s14, s14, s21
	s_sub_i32 s14, s14, s21
	s_mul_i32 s19, s14, s19
	s_sub_i32 s15, s15, s19
	s_add_i32 s18, s18, s15
.LBB0_1341:
	s_ashr_i32 s19, s18, 31
	s_lshl_b64 s[20:21], s[18:19], 19
	s_add_u32 s20, s16, s20
	s_addc_u32 s21, s17, s21
	s_and_b64 s[22:23], s[0:1], exec
	s_cselect_b32 s19, s21, s37
	s_cselect_b32 s58, s20, s36
	s_ashr_i32 s15, s14, 31
	s_lshl_b64 s[22:23], s[14:15], 19
	s_add_u32 s22, s42, s22
	s_addc_u32 s23, s43, s23
	s_and_b64 s[40:41], s[0:1], exec
	s_cselect_b32 s15, s23, s39
	s_cselect_b32 s59, s22, s38
	s_add_u32 s36, s36, 0x40080
	s_addc_u32 s37, s37, 0
	s_add_u32 s60, s38, 0x100
	s_addc_u32 s61, s39, 0
	s_mov_b32 s62, -2
	s_waitcnt lgkmcnt(0)
	s_add_u32 s33, s36, 0xfffc0080
	s_addc_u32 s34, s37, -1
	s_cmp_eq_u32 s62, 12
	s_cselect_b32 s41, s19, s34
	s_cselect_b32 s40, s58, s33
	s_cselect_b32 s39, s15, s61
	s_cselect_b32 s38, s59, s60
	s_add_i32 m0, s25, 0xc000
	global_load_lds_dwordx4 v136, s[36:37]
	s_add_i32 m0, s25, 0xe000
	s_nop 0
	global_load_lds_dwordx4 v138, s[36:37]
	s_cmp_eq_u32 s77, 0
	s_cbranch_scc1 .LfwP15_0_s
	s_waitcnt vmcnt(16)
	s_branch .LfwP15_0_e

; #define PG8_STAGE(bufoff, gbase, voff) do { _Pragma("unroll") for (int _i = 0; _i < 2; ++_i) \
;         __builtin_amdgcn_global_load_lds((const unsigned*)((const char*)(gbase) + (voff)[_i]), (PG8_LAS unsigned*)(lds + (bufoff) + ldsw + _i * 8192), 16, 0, 0); } while (0)
; #define PG8_LDA(dst, b, h) do { _Pragma("unroll") for (int m = 0; m < 4; ++m) _Pragma("unroll") for (int k = 0; k < 2; ++k) dst[m][k] = *(const PG8_LAS bf16x8*)(lds + PG8_SA(b, h) + aoff + m * 2048 + k * 1024); } while (0)
; #define PG8_MMA(ai, bj, At, Bt) do { __builtin_amdgcn_s_setprio(1); _Pragma("unroll") for (int m = 0; m < 4; ++m) _Pragma("unroll") for (int n = 0; n < 2; ++n) _Pragma("unroll") for (int k = 0; k < 2; ++k) \
;         acc[ai][bj][m][n] = __builtin_amdgcn_mfma_f32_16x16x32_bf16(Bt[n][k], At[m][k], acc[ai][bj][m][n], 0, 0, 0); __builtin_amdgcn_s_setprio(0); } while (0)
; #define PG8_WAIT_V(n) asm volatile("s_waitcnt vmcnt(" #n ")" ::: "memory")
; #define PG8_WAIT_L(n) asm volatile("s_waitcnt lgkmcnt(" #n ")" ::: "memory")
; #define PG8_BAR __builtin_amdgcn_s_barrier()
; #define PG8_SCHED __builtin_amdgcn_sched_barrier(0)
; template <class Epi, class Sched, bool ALIGN_EPI = false, bool SP2 = false>
; __device__ __forceinline__ void gemm_phase(PG8_LAS unsigned char* lds, const Gemm g, const Sched& S, const Epi& E) {
;     ...
;             PG8_WAIT_V(8); PG8_WAIT_L(0); PG8_BAR; PG8_MMA(0, 0, At, B0); PG8_MMA(0, 1, At, B1); PG8_BAR; PG8_SCHED;
;             PG8_LDA(At, 0, 1); PG8_STAGE(PG8_SB(0, 0), b2, voffB); PG8_STAGE(PG8_SB(0, 1), b2 + hstep, voffB); PG8_STAGE(PG8_SA(0, 0), a2, voffA);
;             PG8_WAIT_V(8); PG8_WAIT_L(0); PG8_BAR; PG8_MMA(1, 0, At, B0); PG8_MMA(1, 1, At, B1); PG8_BAR; PG8_SCHED;
.LfwP15_0_e:
	s_waitcnt lgkmcnt(0)
	s_barrier
	s_setprio 1
	s_waitcnt lgkmcnt(0)
	v_mfma_f32_16x16x32_bf16 v[124:127], v[154:157], v[186:189], 0
	v_mfma_f32_16x16x32_bf16 v[116:119], v[162:165], v[186:189], 0
	v_mfma_f32_16x16x32_bf16 v[108:111], v[154:157], v[194:197], 0
	v_mfma_f32_16x16x32_bf16 v[100:103], v[162:165], v[194:197], 0
	v_mfma_f32_16x16x32_bf16 v[92:95], v[154:157], v[202:205], 0
	v_mfma_f32_16x16x32_bf16 v[84:87], v[162:165], v[202:205], 0
	v_mfma_f32_16x16x32_bf16 v[76:79], v[154:157], v[210:213], 0
	v_mfma_f32_16x16x32_bf16 v[68:71], v[162:165], v[210:213], 0
	v_mfma_f32_16x16x32_bf16 v[124:127], v[158:161], v[190:193], v[124:127]
	v_mfma_f32_16x16x32_bf16 v[116:119], v[166:169], v[190:193], v[116:119]
	v_mfma_f32_16x16x32_bf16 v[108:111], v[158:161], v[198:201], v[108:111]
	v_mfma_f32_16x16x32_bf16 v[100:103], v[166:169], v[198:201], v[100:103]
	v_mfma_f32_16x16x32_bf16 v[92:95], v[158:161], v[206:209], v[92:95]
	v_mfma_f32_16x16x32_bf16 v[84:87], v[166:169], v[206:209], v[84:87]
	v_mfma_f32_16x16x32_bf16 v[76:79], v[158:161], v[214:217], v[76:79]
	v_mfma_f32_16x16x32_bf16 v[68:71], v[166:169], v[214:217], v[68:71]
	s_setprio 0
	s_setprio 1
	v_mfma_f32_16x16x32_bf16 v[120:123], v[170:173], v[186:189], 0
	v_mfma_f32_16x16x32_bf16 v[112:115], v[178:181], v[186:189], 0
	v_mfma_f32_16x16x32_bf16 v[104:107], v[170:173], v[194:197], 0
	v_mfma_f32_16x16x32_bf16 v[96:99], v[178:181], v[194:197], 0
	v_mfma_f32_16x16x32_bf16 v[88:91], v[170:173], v[202:205], 0
	v_mfma_f32_16x16x32_bf16 v[80:83], v[178:181], v[202:205], 0
	v_mfma_f32_16x16x32_bf16 v[72:75], v[170:173], v[210:213], 0
	v_mfma_f32_16x16x32_bf16 v[64:67], v[178:181], v[210:213], 0
	v_mfma_f32_16x16x32_bf16 v[120:123], v[174:177], v[190:193], v[120:123]
	v_mfma_f32_16x16x32_bf16 v[112:115], v[182:185], v[190:193], v[112:115]
	v_mfma_f32_16x16x32_bf16 v[104:107], v[174:177], v[198:201], v[104:107]
	v_mfma_f32_16x16x32_bf16 v[96:99], v[182:185], v[198:201], v[96:99]
	v_mfma_f32_16x16x32_bf16 v[88:91], v[174:177], v[206:209], v[88:91]
	v_mfma_f32_16x16x32_bf16 v[80:83], v[182:185], v[206:209], v[80:83]
	v_mfma_f32_16x16x32_bf16 v[72:75], v[174:177], v[214:217], v[72:75]
	v_mfma_f32_16x16x32_bf16 v[64:67], v[182:185], v[214:217], v[64:67]
	s_setprio 0
	s_barrier
	s_add_i32 s33, s54, s44
	s_add_u32 s82, s38, s10
	s_addc_u32 s83, s39, s11
	s_mov_b32 m0, s33
	ds_read_b128 v[186:189], v149 offset:16384
	ds_read_b128 v[190:193], v149 offset:17408
	ds_read_b128 v[194:197], v149 offset:18432
	ds_read_b128 v[198:201], v149 offset:19456
	ds_read_b128 v[202:205], v149 offset:20480
	ds_read_b128 v[206:209], v149 offset:21504
	ds_read_b128 v[210:213], v149 offset:22528
	ds_read_b128 v[214:217], v149 offset:23552
	global_load_lds_dwordx4 v130, s[38:39]
	s_add_i32 m0, s33, 0x2000
	s_add_u32 s64, s38, 0x40000
	s_addc_u32 s65, s39, 0
	s_add_i32 s33, s55, s44
	global_load_lds_dwordx4 v134, s[38:39]
	s_mov_b32 m0, s33
	s_add_u32 s84, s40, s10
	s_addc_u32 s85, s41, s11
	global_load_lds_dwordx4 v130, s[64:65]
	s_add_i32 m0, s33, 0x2000
	s_nop 0
	global_load_lds_dwordx4 v134, s[64:65]
	s_mov_b32 m0, s25
	s_nop 0
	global_load_lds_dwordx4 v128, s[40:41]
	s_mov_b32 m0, s47
	s_nop 0
	global_load_lds_dwordx4 v132, s[40:41]
	s_cmp_eq_u32 s77, 0
	s_cbranch_scc1 .LfwP15_1_s
	s_waitcnt vmcnt(16)
	s_branch .LfwP15_1_e

; #define PG8_STAGE(bufoff, gbase, voff) do { _Pragma("unroll") for (int _i = 0; _i < 2; ++_i) \
;         __builtin_amdgcn_global_load_lds((const unsigned*)((const char*)(gbase) + (voff)[_i]), (PG8_LAS unsigned*)(lds + (bufoff) + ldsw + _i * 8192), 16, 0, 0); } while (0)
; #define PG8_LDA(dst, b, h) do { _Pragma("unroll") for (int m = 0; m < 4; ++m) _Pragma("unroll") for (int k = 0; k < 2; ++k) dst[m][k] = *(const PG8_LAS bf16x8*)(lds + PG8_SA(b, h) + aoff + m * 2048 + k * 1024); } while (0)
; #define PG8_LDB(dst, b, h) do { _Pragma("unroll") for (int n = 0; n < 2; ++n) _Pragma("unroll") for (int k = 0; k < 2; ++k) dst[n][k] = *(const PG8_LAS bf16x8*)(lds + PG8_SB(b, h) + boff + n * 2048 + k * 1024); } while (0)
; #define PG8_MMA(ai, bj, At, Bt) do { __builtin_amdgcn_s_setprio(1); _Pragma("unroll") for (int m = 0; m < 4; ++m) _Pragma("unroll") for (int n = 0; n < 2; ++n) _Pragma("unroll") for (int k = 0; k < 2; ++k) \
;         acc[ai][bj][m][n] = __builtin_amdgcn_mfma_f32_16x16x32_bf16(Bt[n][k], At[m][k], acc[ai][bj][m][n], 0, 0, 0); __builtin_amdgcn_s_setprio(0); } while (0)
; #define PG8_WAIT_V(n) asm volatile("s_waitcnt vmcnt(" #n ")" ::: "memory")
; #define PG8_WAIT_L(n) asm volatile("s_waitcnt lgkmcnt(" #n ")" ::: "memory")
; #define PG8_BAR __builtin_amdgcn_s_barrier()
; #define PG8_SCHED __builtin_amdgcn_sched_barrier(0)
; template <class Epi, class Sched, bool ALIGN_EPI = false, bool SP2 = false>
; __device__ __forceinline__ void gemm_phase(PG8_LAS unsigned char* lds, const Gemm g, const Sched& S, const Epi& E) {
;     ...
;             PG8_WAIT_V(8); PG8_WAIT_L(0); PG8_BAR; PG8_MMA(1, 0, At, B0); PG8_MMA(1, 1, At, B1); PG8_BAR; PG8_SCHED;
;             PG8_LDB(B0, 1, 0); PG8_LDB(B1, 1, 1); PG8_SCHED; PG8_LDA(At, 1, 0); PG8_STAGE(PG8_SA(0, 1), a2 + hstep, voffA);
;             PG8_WAIT_V(8); PG8_WAIT_L(0); PG8_BAR; PG8_MMA(0, 0, At, B0); PG8_MMA(0, 1, At, B1); PG8_BAR; PG8_SCHED;
.LfwP15_1_e:
	s_waitcnt lgkmcnt(0)
	s_barrier
	s_setprio 1
	s_waitcnt lgkmcnt(0)
	v_mfma_f32_16x16x32_bf16 v[60:63], v[154:157], v[186:189], 0
	v_mfma_f32_16x16x32_bf16 v[52:55], v[162:165], v[186:189], 0
	v_mfma_f32_16x16x32_bf16 v[44:47], v[154:157], v[194:197], 0
	v_mfma_f32_16x16x32_bf16 v[36:39], v[162:165], v[194:197], 0
	v_mfma_f32_16x16x32_bf16 v[28:31], v[154:157], v[202:205], 0
	v_mfma_f32_16x16x32_bf16 v[20:23], v[162:165], v[202:205], 0
	v_mfma_f32_16x16x32_bf16 v[12:15], v[154:157], v[210:213], 0
	v_mfma_f32_16x16x32_bf16 v[4:7], v[162:165], v[210:213], 0
	v_mfma_f32_16x16x32_bf16 v[60:63], v[158:161], v[190:193], v[60:63]
	v_mfma_f32_16x16x32_bf16 v[52:55], v[166:169], v[190:193], v[52:55]
	v_mfma_f32_16x16x32_bf16 v[44:47], v[158:161], v[198:201], v[44:47]
	v_mfma_f32_16x16x32_bf16 v[36:39], v[166:169], v[198:201], v[36:39]
	v_mfma_f32_16x16x32_bf16 v[28:31], v[158:161], v[206:209], v[28:31]
	v_mfma_f32_16x16x32_bf16 v[20:23], v[166:169], v[206:209], v[20:23]
	v_mfma_f32_16x16x32_bf16 v[12:15], v[158:161], v[214:217], v[12:15]
	v_mfma_f32_16x16x32_bf16 v[4:7], v[166:169], v[214:217], v[4:7]
	s_setprio 0
	s_setprio 1
	v_mfma_f32_16x16x32_bf16 v[56:59], v[170:173], v[186:189], 0
	v_mfma_f32_16x16x32_bf16 v[48:51], v[178:181], v[186:189], 0
	v_mfma_f32_16x16x32_bf16 v[40:43], v[170:173], v[194:197], 0
	v_mfma_f32_16x16x32_bf16 v[32:35], v[178:181], v[194:197], 0
	v_mfma_f32_16x16x32_bf16 v[24:27], v[170:173], v[202:205], 0
	v_mfma_f32_16x16x32_bf16 v[16:19], v[178:181], v[202:205], 0
	v_mfma_f32_16x16x32_bf16 v[8:11], v[170:173], v[210:213], 0
	v_mfma_f32_16x16x32_bf16 v[0:3], v[178:181], v[210:213], 0
	v_mfma_f32_16x16x32_bf16 v[56:59], v[174:177], v[190:193], v[56:59]
	v_mfma_f32_16x16x32_bf16 v[48:51], v[182:185], v[190:193], v[48:51]
	v_mfma_f32_16x16x32_bf16 v[40:43], v[174:177], v[198:201], v[40:43]
	v_mfma_f32_16x16x32_bf16 v[32:35], v[182:185], v[198:201], v[32:35]
	v_mfma_f32_16x16x32_bf16 v[24:27], v[174:177], v[206:209], v[24:27]
	v_mfma_f32_16x16x32_bf16 v[16:19], v[182:185], v[206:209], v[16:19]
	v_mfma_f32_16x16x32_bf16 v[8:11], v[174:177], v[214:217], v[8:11]
	v_mfma_f32_16x16x32_bf16 v[0:3], v[182:185], v[214:217], v[0:3]
	s_setprio 0
	s_barrier
	s_add_i32 s33, 0, 0x18000
	v_add_u32_e32 v153, s33, v145
	s_add_i32 s34, 0, 0x1c000
	ds_read_b128 v[154:157], v153
	ds_read_b128 v[158:161], v153 offset:1024
	ds_read_b128 v[162:165], v153 offset:2048
	ds_read_b128 v[166:169], v153 offset:3072
	v_add_u32_e32 v153, s34, v145
	ds_read_b128 v[170:173], v153
	ds_read_b128 v[174:177], v153 offset:1024
	ds_read_b128 v[178:181], v153 offset:2048
	ds_read_b128 v[182:185], v153 offset:3072
	s_add_u32 s40, s40, 0x40000
	s_addc_u32 s41, s41, 0
	s_mov_b32 m0, s48
	ds_read_b128 v[186:189], v149 offset:32768
	ds_read_b128 v[190:193], v149 offset:33792
	ds_read_b128 v[194:197], v149 offset:34816
	ds_read_b128 v[198:201], v149 offset:35840
	ds_read_b128 v[202:205], v149 offset:36864
	ds_read_b128 v[206:209], v149 offset:37888
	ds_read_b128 v[210:213], v149 offset:38912
	ds_read_b128 v[214:217], v149 offset:39936
	global_load_lds_dwordx4 v128, s[40:41]
	s_mov_b32 m0, s49
	s_nop 0
	global_load_lds_dwordx4 v132, s[40:41]
	s_waitcnt vmcnt(8)
	s_waitcnt lgkmcnt(0)
	s_barrier
	s_setprio 1
	s_waitcnt lgkmcnt(0)
	v_mfma_f32_16x16x32_bf16 v[124:127], v[154:157], v[186:189], v[124:127]
	v_mfma_f32_16x16x32_bf16 v[116:119], v[162:165], v[186:189], v[116:119]
	v_mfma_f32_16x16x32_bf16 v[108:111], v[154:157], v[194:197], v[108:111]
	v_mfma_f32_16x16x32_bf16 v[100:103], v[162:165], v[194:197], v[100:103]
	v_mfma_f32_16x16x32_bf16 v[92:95], v[154:157], v[202:205], v[92:95]
	v_mfma_f32_16x16x32_bf16 v[84:87], v[162:165], v[202:205], v[84:87]
	v_mfma_f32_16x16x32_bf16 v[76:79], v[154:157], v[210:213], v[76:79]
	v_mfma_f32_16x16x32_bf16 v[68:71], v[162:165], v[210:213], v[68:71]
	v_mfma_f32_16x16x32_bf16 v[124:127], v[158:161], v[190:193], v[124:127]
	v_mfma_f32_16x16x32_bf16 v[116:119], v[166:169], v[190:193], v[116:119]
	v_mfma_f32_16x16x32_bf16 v[108:111], v[158:161], v[198:201], v[108:111]
	v_mfma_f32_16x16x32_bf16 v[100:103], v[166:169], v[198:201], v[100:103]
	v_mfma_f32_16x16x32_bf16 v[92:95], v[158:161], v[206:209], v[92:95]
	v_mfma_f32_16x16x32_bf16 v[84:87], v[166:169], v[206:209], v[84:87]
	v_mfma_f32_16x16x32_bf16 v[76:79], v[158:161], v[214:217], v[76:79]
	v_mfma_f32_16x16x32_bf16 v[68:71], v[166:169], v[214:217], v[68:71]
	s_setprio 0
	s_setprio 1
	v_mfma_f32_16x16x32_bf16 v[120:123], v[170:173], v[186:189], v[120:123]
	v_mfma_f32_16x16x32_bf16 v[112:115], v[178:181], v[186:189], v[112:115]
	v_mfma_f32_16x16x32_bf16 v[104:107], v[170:173], v[194:197], v[104:107]
	v_mfma_f32_16x16x32_bf16 v[96:99], v[178:181], v[194:197], v[96:99]
	v_mfma_f32_16x16x32_bf16 v[88:91], v[170:173], v[202:205], v[88:91]
	v_mfma_f32_16x16x32_bf16 v[80:83], v[178:181], v[202:205], v[80:83]
	v_mfma_f32_16x16x32_bf16 v[72:75], v[170:173], v[210:213], v[72:75]
	v_mfma_f32_16x16x32_bf16 v[64:67], v[178:181], v[210:213], v[64:67]
	v_mfma_f32_16x16x32_bf16 v[120:123], v[174:177], v[190:193], v[120:123]
	v_mfma_f32_16x16x32_bf16 v[112:115], v[182:185], v[190:193], v[112:115]
	v_mfma_f32_16x16x32_bf16 v[104:107], v[174:177], v[198:201], v[104:107]
	v_mfma_f32_16x16x32_bf16 v[96:99], v[182:185], v[198:201], v[96:99]
	v_mfma_f32_16x16x32_bf16 v[88:91], v[174:177], v[206:209], v[88:91]
	v_mfma_f32_16x16x32_bf16 v[80:83], v[182:185], v[206:209], v[80:83]
	v_mfma_f32_16x16x32_bf16 v[72:75], v[174:177], v[214:217], v[72:75]
	v_mfma_f32_16x16x32_bf16 v[64:67], v[182:185], v[214:217], v[64:67]
	s_setprio 0
	s_barrier
; #define PG8_STAGE(bufoff, gbase, voff) do { _Pragma("unroll") for (int _i = 0; _i < 2; ++_i) \
;         __builtin_amdgcn_global_load_lds((const unsigned*)((const char*)(gbase) + (voff)[_i]), (PG8_LAS unsigned*)(lds + (bufoff) + ldsw + _i * 8192), 16, 0, 0); } while (0)
; #define PG8_LDA(dst, b, h) do { _Pragma("unroll") for (int m = 0; m < 4; ++m) _Pragma("unroll") for (int k = 0; k < 2; ++k) dst[m][k] = *(const PG8_LAS bf16x8*)(lds + PG8_SA(b, h) + aoff + m * 2048 + k * 1024); } while (0)
; #define PG8_MMA(ai, bj, At, Bt) do { __builtin_amdgcn_s_setprio(1); _Pragma("unroll") for (int m = 0; m < 4; ++m) _Pragma("unroll") for (int n = 0; n < 2; ++n) _Pragma("unroll") for (int k = 0; k < 2; ++k) \
;         acc[ai][bj][m][n] = __builtin_amdgcn_mfma_f32_16x16x32_bf16(Bt[n][k], At[m][k], acc[ai][bj][m][n], 0, 0, 0); __builtin_amdgcn_s_setprio(0); } while (0)
; #define PG8_WAIT_V(n) asm volatile("s_waitcnt vmcnt(" #n ")" ::: "memory")
; #define PG8_WAIT_L(n) asm volatile("s_waitcnt lgkmcnt(" #n ")" ::: "memory")
; #define PG8_BAR __builtin_amdgcn_s_barrier()
; #define PG8_SCHED __builtin_amdgcn_sched_barrier(0)
; template <class Epi, class Sched, bool ALIGN_EPI = false, bool SP2 = false>
; __device__ __forceinline__ void gemm_phase(PG8_LAS unsigned char* lds, const Gemm g, const Sched& S, const Epi& E) {
;     ...
;             PG8_LDA(At, 1, 1); PG8_STAGE(PG8_SB(1, 0), b3, voffB); PG8_STAGE(PG8_SB(1, 1), b3 + hstep, voffB); PG8_STAGE(PG8_SA(1, 0), a3, voffA);
;             PG8_WAIT_V(8); PG8_WAIT_L(0); PG8_BAR; PG8_MMA(1, 0, At, B0); PG8_MMA(1, 1, At, B1); PG8_BAR; PG8_SCHED;
	s_add_i32 s33, s33, s44
	s_mov_b32 m0, s33
	ds_read_b128 v[186:189], v149 offset:49152
	ds_read_b128 v[190:193], v149 offset:50176
	ds_read_b128 v[194:197], v149 offset:51200
	ds_read_b128 v[198:201], v149 offset:52224
	ds_read_b128 v[202:205], v149 offset:53248
	ds_read_b128 v[206:209], v149 offset:54272
	ds_read_b128 v[210:213], v149 offset:55296
	ds_read_b128 v[214:217], v149 offset:56320
	global_load_lds_dwordx4 v130, s[82:83]
	s_add_i32 m0, s33, 0x2000
	s_add_u32 s38, s38, 0x40080
	s_addc_u32 s39, s39, 0
	s_add_i32 s33, s34, s44
	global_load_lds_dwordx4 v134, s[82:83]
	s_mov_b32 m0, s33
	s_nop 0
	global_load_lds_dwordx4 v130, s[38:39]
	s_add_i32 m0, s33, 0x2000
	s_nop 0
	global_load_lds_dwordx4 v134, s[38:39]
	s_mov_b32 m0, s52
	s_nop 0
	global_load_lds_dwordx4 v128, s[84:85]
	s_mov_b32 m0, s53
	s_nop 0
	global_load_lds_dwordx4 v132, s[84:85]
	s_waitcnt vmcnt(8)
	s_waitcnt lgkmcnt(0)
	s_barrier
	s_setprio 1
	s_waitcnt lgkmcnt(0)
	v_mfma_f32_16x16x32_bf16 v[60:63], v[154:157], v[186:189], v[60:63]
	v_mfma_f32_16x16x32_bf16 v[52:55], v[162:165], v[186:189], v[52:55]
	v_mfma_f32_16x16x32_bf16 v[44:47], v[154:157], v[194:197], v[44:47]
	v_mfma_f32_16x16x32_bf16 v[36:39], v[162:165], v[194:197], v[36:39]
	v_mfma_f32_16x16x32_bf16 v[28:31], v[154:157], v[202:205], v[28:31]
	v_mfma_f32_16x16x32_bf16 v[20:23], v[162:165], v[202:205], v[20:23]
	v_mfma_f32_16x16x32_bf16 v[12:15], v[154:157], v[210:213], v[12:15]
	v_mfma_f32_16x16x32_bf16 v[4:7], v[162:165], v[210:213], v[4:7]
	v_mfma_f32_16x16x32_bf16 v[60:63], v[158:161], v[190:193], v[60:63]
	v_mfma_f32_16x16x32_bf16 v[52:55], v[166:169], v[190:193], v[52:55]
	v_mfma_f32_16x16x32_bf16 v[44:47], v[158:161], v[198:201], v[44:47]
	v_mfma_f32_16x16x32_bf16 v[36:39], v[166:169], v[198:201], v[36:39]
	v_mfma_f32_16x16x32_bf16 v[28:31], v[158:161], v[206:209], v[28:31]
	v_mfma_f32_16x16x32_bf16 v[20:23], v[166:169], v[206:209], v[20:23]
	v_mfma_f32_16x16x32_bf16 v[12:15], v[158:161], v[214:217], v[12:15]
	v_mfma_f32_16x16x32_bf16 v[4:7], v[166:169], v[214:217], v[4:7]
	s_setprio 0
	s_setprio 1
	v_mfma_f32_16x16x32_bf16 v[56:59], v[170:173], v[186:189], v[56:59]
	v_mfma_f32_16x16x32_bf16 v[48:51], v[178:181], v[186:189], v[48:51]
	v_mfma_f32_16x16x32_bf16 v[40:43], v[170:173], v[194:197], v[40:43]
	v_mfma_f32_16x16x32_bf16 v[32:35], v[178:181], v[194:197], v[32:35]
	v_mfma_f32_16x16x32_bf16 v[24:27], v[170:173], v[202:205], v[24:27]
	v_mfma_f32_16x16x32_bf16 v[16:19], v[178:181], v[202:205], v[16:19]
	v_mfma_f32_16x16x32_bf16 v[8:11], v[170:173], v[210:213], v[8:11]
	v_mfma_f32_16x16x32_bf16 v[0:3], v[178:181], v[210:213], v[0:3]
	v_mfma_f32_16x16x32_bf16 v[56:59], v[174:177], v[190:193], v[56:59]
	v_mfma_f32_16x16x32_bf16 v[48:51], v[182:185], v[190:193], v[48:51]
	v_mfma_f32_16x16x32_bf16 v[40:43], v[174:177], v[198:201], v[40:43]
	v_mfma_f32_16x16x32_bf16 v[32:35], v[182:185], v[198:201], v[32:35]
	v_mfma_f32_16x16x32_bf16 v[24:27], v[174:177], v[206:209], v[24:27]
	v_mfma_f32_16x16x32_bf16 v[16:19], v[182:185], v[206:209], v[16:19]
	v_mfma_f32_16x16x32_bf16 v[8:11], v[174:177], v[214:217], v[8:11]
	v_mfma_f32_16x16x32_bf16 v[0:3], v[182:185], v[214:217], v[0:3]
	s_setprio 0
	s_barrier
	s_add_i32 s62, s62, 2
	s_add_u32 s36, s36, 0x100
	s_addc_u32 s37, s37, 0
	s_add_u32 s60, s60, 0x100
	s_addc_u32 s61, s61, 0
	s_cmp_gt_u32 s62, 13

; __device__ __forceinline__ unsigned pk2(float lo, float hi) { f32x2 v = {lo, hi}; bf16x2_t b = __builtin_convertvector(v, bf16x2_t); return __builtin_bit_cast(unsigned, b); }
; __device__ __forceinline__ float silu_f(float a) { return a * __builtin_amdgcn_rcpf(1.0f + __expf(-a)); }
;     __device__ __forceinline__ void operator()(const f32x4 (&acc)[2][2][4][2], const Unit& u, int wr, int wc, int fr, int fq) const {
;         const int row0 = u.pm * BM + wr * 64 + fr; const int col0 = u.pn * HALF + wc * 32 + 8 * fq;
; #pragma unroll
;         for (int ai = 0; ai < 2; ++ai)
; #pragma unroll
;             for (int m = 0; m < 4; ++m) { const int row = row0 + ai * HALF + m * 16;
;                 const f32x4 a0 = acc[ai][0][m][0], a1 = acc[ai][0][m][1], b0 = acc[ai][1][m][0], b1 = acc[ai][1][m][1];
;                 u32x4 w; w.x = pk2(silu_f(a0[0]) * b0[0], silu_f(a0[1]) * b0[1]); w.y = pk2(silu_f(a0[2]) * b0[2], silu_f(a0[3]) * b0[3]);
;                 w.z = pk2(silu_f(a1[0]) * b1[0], silu_f(a1[1]) * b1[1]); w.w = pk2(silu_f(a1[2]) * b1[2], silu_f(a1[3]) * b1[3]);
;                 *(u32x4*)(H + (size_t)row * ldh + col0) = w; }
.LBB0_1345:
	s_mov_b32 s77, 1
	v_mul_f32_e32 v151, 0xbfb8aa3b, v124
	v_exp_f32_e32 v151, v151
	v_mul_f32_e32 v153, 0xbfb8aa3b, v125
	v_exp_f32_e32 v153, v153
	v_mul_f32_e32 v157, 0xbfb8aa3b, v127
	v_add_f32_e32 v151, 1.0, v151
	v_rcp_f32_e32 v156, v151
	v_add_f32_e32 v151, 1.0, v153
	v_mul_f32_e32 v153, 0xbfb8aa3b, v126
	v_exp_f32_e32 v153, v153
	v_exp_f32_e32 v159, v157
	v_rcp_f32_e32 v157, v151
	v_lshl_or_b32 v154, s57, 7, v146
	v_add_f32_e32 v151, 1.0, v153
	v_rcp_f32_e32 v158, v151
	v_add_f32_e32 v151, 1.0, v159
	v_rcp_f32_e32 v159, v151
	v_pk_mul_f32 v[124:125], v[124:125], v[156:157]
	v_lshl_add_u32 v150, s24, 8, v144
	v_pk_mul_f32 v[120:121], v[124:125], v[120:121]
	v_pk_mul_f32 v[124:125], v[126:127], v[158:159]
	v_cvt_pk_bf16_f32 v120, v120, v121
	v_mul_f32_e32 v121, 0xbfb8aa3b, v116
	v_pk_mul_f32 v[122:123], v[124:125], v[122:123]
	v_exp_f32_e32 v124, v121
	v_mul_f32_e32 v121, 0xbfb8aa3b, v117
	v_exp_f32_e32 v125, v121
	v_cvt_pk_bf16_f32 v121, v122, v123
	v_add_f32_e32 v122, 1.0, v124
	v_mul_f32_e32 v124, 0xbfb8aa3b, v118
	v_add_f32_e32 v123, 1.0, v125
	v_mul_f32_e32 v125, 0xbfb8aa3b, v119
	v_exp_f32_e32 v124, v124
	v_exp_f32_e32 v125, v125
	v_rcp_f32_e32 v122, v122
	v_rcp_f32_e32 v123, v123
	v_add_f32_e32 v124, 1.0, v124
	v_add_f32_e32 v125, 1.0, v125
	v_rcp_f32_e32 v124, v124
	v_rcp_f32_e32 v125, v125
	v_pk_mul_f32 v[116:117], v[116:117], v[122:123]
	v_ashrrev_i32_e32 v155, 31, v154
	v_pk_mul_f32 v[112:113], v[116:117], v[112:113]
	s_andn2_b64 vcc, exec, s[0:1]
	v_cvt_pk_bf16_f32 v122, v112, v113
	v_pk_mul_f32 v[112:113], v[118:119], v[124:125]
	v_mul_f32_e32 v118, 0xbfb8aa3b, v110
	v_pk_mul_f32 v[112:113], v[112:113], v[114:115]
	v_lshlrev_b64 v[114:115], 1, v[154:155]
	v_cvt_pk_bf16_f32 v123, v112, v113
	v_mov_b64_e32 v[112:113], s[8:9]
	v_mad_i64_i32 v[116:117], s[36:37], v150, s56, v[112:113]
	v_lshl_add_u64 v[116:117], v[116:117], 0, v[114:115]
	global_store_dwordx4 v[116:117], v[120:123], off
	v_mul_f32_e32 v116, 0xbfb8aa3b, v108
	v_mul_f32_e32 v117, 0xbfb8aa3b, v109
	v_exp_f32_e32 v116, v116
	v_exp_f32_e32 v117, v117
	v_mul_f32_e32 v119, 0xbfb8aa3b, v111
	v_exp_f32_e32 v118, v118
	v_exp_f32_e32 v119, v119
	v_add_f32_e32 v116, 1.0, v116
	v_add_f32_e32 v117, 1.0, v117
	v_rcp_f32_e32 v116, v116
	v_rcp_f32_e32 v117, v117
	v_add_f32_e32 v118, 1.0, v118
	v_add_f32_e32 v119, 1.0, v119
	v_rcp_f32_e32 v118, v118
	v_rcp_f32_e32 v119, v119
	v_pk_mul_f32 v[108:109], v[108:109], v[116:117]
	v_or_b32_e32 v120, 16, v150
	v_pk_mul_f32 v[104:105], v[108:109], v[104:105]
	v_pk_mul_f32 v[108:109], v[110:111], v[118:119]
	v_cvt_pk_bf16_f32 v104, v104, v105
	v_mul_f32_e32 v105, 0xbfb8aa3b, v100
	v_pk_mul_f32 v[106:107], v[108:109], v[106:107]
	v_exp_f32_e32 v108, v105
	v_mul_f32_e32 v105, 0xbfb8aa3b, v101
	v_exp_f32_e32 v109, v105
	v_cvt_pk_bf16_f32 v105, v106, v107
	v_add_f32_e32 v106, 1.0, v108
	v_mul_f32_e32 v108, 0xbfb8aa3b, v102
	v_add_f32_e32 v107, 1.0, v109
	v_mul_f32_e32 v109, 0xbfb8aa3b, v103
	v_exp_f32_e32 v108, v108
	v_exp_f32_e32 v109, v109
	v_rcp_f32_e32 v106, v106
	v_rcp_f32_e32 v107, v107
	v_add_f32_e32 v108, 1.0, v108
	v_add_f32_e32 v109, 1.0, v109
	v_rcp_f32_e32 v108, v108
	v_rcp_f32_e32 v109, v109
	v_pk_mul_f32 v[100:101], v[100:101], v[106:107]
	s_mov_b64 s[0:1], -1
	v_pk_mul_f32 v[96:97], v[100:101], v[96:97]
	v_or_b32_e32 v100, 32, v150
	v_cvt_pk_bf16_f32 v106, v96, v97
	v_pk_mul_f32 v[96:97], v[102:103], v[108:109]
	s_nop 0
	v_pk_mul_f32 v[96:97], v[96:97], v[98:99]
	v_mul_f32_e32 v98, 0xbfb8aa3b, v94
	v_cvt_pk_bf16_f32 v107, v96, v97
	v_mad_i64_i32 v[96:97], s[36:37], v120, s56, v[112:113]
	v_lshl_add_u64 v[96:97], v[96:97], 0, v[114:115]
	global_store_dwordx4 v[96:97], v[104:107], off
	v_mul_f32_e32 v96, 0xbfb8aa3b, v92
	v_mul_f32_e32 v97, 0xbfb8aa3b, v93
	v_exp_f32_e32 v96, v96
	v_exp_f32_e32 v97, v97
	v_mul_f32_e32 v99, 0xbfb8aa3b, v95
	v_exp_f32_e32 v98, v98
	v_exp_f32_e32 v99, v99
	v_add_f32_e32 v96, 1.0, v96
	v_add_f32_e32 v97, 1.0, v97
	v_rcp_f32_e32 v96, v96
	v_rcp_f32_e32 v97, v97
	v_add_f32_e32 v98, 1.0, v98
	v_add_f32_e32 v99, 1.0, v99
	v_rcp_f32_e32 v98, v98
	v_rcp_f32_e32 v99, v99
	v_pk_mul_f32 v[92:93], v[92:93], v[96:97]
	s_nop 0
	v_pk_mul_f32 v[88:89], v[92:93], v[88:89]
	v_pk_mul_f32 v[92:93], v[94:95], v[98:99]
	v_cvt_pk_bf16_f32 v88, v88, v89
	v_mul_f32_e32 v89, 0xbfb8aa3b, v84
	v_pk_mul_f32 v[90:91], v[92:93], v[90:91]
	v_exp_f32_e32 v92, v89
	v_mul_f32_e32 v89, 0xbfb8aa3b, v85
	v_exp_f32_e32 v93, v89
	v_cvt_pk_bf16_f32 v89, v90, v91
	v_add_f32_e32 v90, 1.0, v92
	v_mul_f32_e32 v92, 0xbfb8aa3b, v86
	v_add_f32_e32 v91, 1.0, v93
	v_mul_f32_e32 v93, 0xbfb8aa3b, v87
	v_exp_f32_e32 v92, v92
	v_exp_f32_e32 v93, v93
	v_rcp_f32_e32 v90, v90
	v_rcp_f32_e32 v91, v91
	v_add_f32_e32 v92, 1.0, v92
	v_add_f32_e32 v93, 1.0, v93
	v_rcp_f32_e32 v92, v92
	v_rcp_f32_e32 v93, v93
	v_pk_mul_f32 v[84:85], v[84:85], v[90:91]
	s_nop 0
	v_pk_mul_f32 v[80:81], v[84:85], v[80:81]
	v_or_b32_e32 v84, 48, v150
	v_cvt_pk_bf16_f32 v90, v80, v81
	v_pk_mul_f32 v[80:81], v[86:87], v[92:93]
	s_nop 0
	v_pk_mul_f32 v[80:81], v[80:81], v[82:83]
	v_mul_f32_e32 v82, 0xbfb8aa3b, v78
	v_cvt_pk_bf16_f32 v91, v80, v81
	v_mad_i64_i32 v[80:81], s[36:37], v100, s56, v[112:113]
	v_lshl_add_u64 v[80:81], v[80:81], 0, v[114:115]
	global_store_dwordx4 v[80:81], v[88:91], off
	v_mul_f32_e32 v80, 0xbfb8aa3b, v76
	v_mul_f32_e32 v81, 0xbfb8aa3b, v77
	v_exp_f32_e32 v80, v80
	v_exp_f32_e32 v81, v81
	v_mul_f32_e32 v83, 0xbfb8aa3b, v79
	v_exp_f32_e32 v82, v82
	v_exp_f32_e32 v83, v83
	v_add_f32_e32 v80, 1.0, v80
	v_add_f32_e32 v81, 1.0, v81
	v_rcp_f32_e32 v80, v80
	v_rcp_f32_e32 v81, v81
	v_add_f32_e32 v82, 1.0, v82
	v_add_f32_e32 v83, 1.0, v83
; __device__ __forceinline__ unsigned pk2(float lo, float hi) { f32x2 v = {lo, hi}; bf16x2_t b = __builtin_convertvector(v, bf16x2_t); return __builtin_bit_cast(unsigned, b); }
; __device__ __forceinline__ float silu_f(float a) { return a * __builtin_amdgcn_rcpf(1.0f + __expf(-a)); }
;     __device__ __forceinline__ void operator()(const f32x4 (&acc)[2][2][4][2], const Unit& u, int wr, int wc, int fr, int fq) const {
;     ...
;             for (int m = 0; m < 4; ++m) { const int row = row0 + ai * HALF + m * 16;
;                 const f32x4 a0 = acc[ai][0][m][0], a1 = acc[ai][0][m][1], b0 = acc[ai][1][m][0], b1 = acc[ai][1][m][1];
;                 u32x4 w; w.x = pk2(silu_f(a0[0]) * b0[0], silu_f(a0[1]) * b0[1]); w.y = pk2(silu_f(a0[2]) * b0[2], silu_f(a0[3]) * b0[3]);
;                 w.z = pk2(silu_f(a1[0]) * b1[0], silu_f(a1[1]) * b1[1]); w.w = pk2(silu_f(a1[2]) * b1[2], silu_f(a1[3]) * b1[3]);
;                 *(u32x4*)(H + (size_t)row * ldh + col0) = w; }
	v_rcp_f32_e32 v82, v82
	v_rcp_f32_e32 v83, v83
	v_pk_mul_f32 v[76:77], v[76:77], v[80:81]
	s_nop 0
	v_pk_mul_f32 v[72:73], v[76:77], v[72:73]
	v_pk_mul_f32 v[76:77], v[78:79], v[82:83]
	v_cvt_pk_bf16_f32 v72, v72, v73
	v_mul_f32_e32 v73, 0xbfb8aa3b, v68
	v_pk_mul_f32 v[74:75], v[76:77], v[74:75]
	v_exp_f32_e32 v76, v73
	v_mul_f32_e32 v73, 0xbfb8aa3b, v69
	v_exp_f32_e32 v77, v73
	v_cvt_pk_bf16_f32 v73, v74, v75
	v_add_f32_e32 v74, 1.0, v76
	v_mul_f32_e32 v76, 0xbfb8aa3b, v70
	v_add_f32_e32 v75, 1.0, v77
	v_mul_f32_e32 v77, 0xbfb8aa3b, v71
	v_exp_f32_e32 v76, v76
	v_exp_f32_e32 v77, v77
	v_rcp_f32_e32 v74, v74
	v_rcp_f32_e32 v75, v75
	v_add_f32_e32 v76, 1.0, v76
	v_add_f32_e32 v77, 1.0, v77
	v_rcp_f32_e32 v76, v76
	v_rcp_f32_e32 v77, v77
	v_pk_mul_f32 v[68:69], v[68:69], v[74:75]
	s_nop 0
	v_pk_mul_f32 v[64:65], v[68:69], v[64:65]
	v_add_u32_e32 v68, 0x80, v150
	v_cvt_pk_bf16_f32 v74, v64, v65
	v_pk_mul_f32 v[64:65], v[70:71], v[76:77]
	s_nop 0
	v_pk_mul_f32 v[64:65], v[64:65], v[66:67]
	v_mul_f32_e32 v66, 0xbfb8aa3b, v62
	v_cvt_pk_bf16_f32 v75, v64, v65
	v_mad_i64_i32 v[64:65], s[36:37], v84, s56, v[112:113]
	v_lshl_add_u64 v[64:65], v[64:65], 0, v[114:115]
	global_store_dwordx4 v[64:65], v[72:75], off
	v_mul_f32_e32 v64, 0xbfb8aa3b, v60
	v_mul_f32_e32 v65, 0xbfb8aa3b, v61
	v_exp_f32_e32 v64, v64
	v_exp_f32_e32 v65, v65
	v_mul_f32_e32 v67, 0xbfb8aa3b, v63
	v_exp_f32_e32 v66, v66
	v_exp_f32_e32 v67, v67
	v_add_f32_e32 v64, 1.0, v64
	v_add_f32_e32 v65, 1.0, v65
	v_rcp_f32_e32 v64, v64
	v_rcp_f32_e32 v65, v65
	v_add_f32_e32 v66, 1.0, v66
	v_add_f32_e32 v67, 1.0, v67
	v_rcp_f32_e32 v66, v66
	v_rcp_f32_e32 v67, v67
	v_pk_mul_f32 v[60:61], v[60:61], v[64:65]
	s_nop 0
	v_pk_mul_f32 v[56:57], v[60:61], v[56:57]
	v_pk_mul_f32 v[60:61], v[62:63], v[66:67]
	v_cvt_pk_bf16_f32 v56, v56, v57
	v_mul_f32_e32 v57, 0xbfb8aa3b, v52
	v_pk_mul_f32 v[58:59], v[60:61], v[58:59]
	v_exp_f32_e32 v60, v57
	v_mul_f32_e32 v57, 0xbfb8aa3b, v53
	v_exp_f32_e32 v61, v57
	v_cvt_pk_bf16_f32 v57, v58, v59
	v_add_f32_e32 v58, 1.0, v60
	v_mul_f32_e32 v60, 0xbfb8aa3b, v54
	v_add_f32_e32 v59, 1.0, v61
	v_mul_f32_e32 v61, 0xbfb8aa3b, v55
	v_exp_f32_e32 v60, v60
	v_exp_f32_e32 v61, v61
	v_rcp_f32_e32 v58, v58
	v_rcp_f32_e32 v59, v59
	v_add_f32_e32 v60, 1.0, v60
	v_add_f32_e32 v61, 1.0, v61
	v_rcp_f32_e32 v60, v60
	v_rcp_f32_e32 v61, v61
	v_pk_mul_f32 v[52:53], v[52:53], v[58:59]
	s_nop 0
	v_pk_mul_f32 v[48:49], v[52:53], v[48:49]
	v_add_u32_e32 v52, 0x90, v150
	v_cvt_pk_bf16_f32 v58, v48, v49
	v_pk_mul_f32 v[48:49], v[54:55], v[60:61]
	s_nop 0
	v_pk_mul_f32 v[48:49], v[48:49], v[50:51]
	v_mul_f32_e32 v50, 0xbfb8aa3b, v46
	v_cvt_pk_bf16_f32 v59, v48, v49
	v_mad_i64_i32 v[48:49], s[36:37], v68, s56, v[112:113]
	v_lshl_add_u64 v[48:49], v[48:49], 0, v[114:115]
	global_store_dwordx4 v[48:49], v[56:59], off
	v_mul_f32_e32 v48, 0xbfb8aa3b, v44
	v_mul_f32_e32 v49, 0xbfb8aa3b, v45
	v_exp_f32_e32 v48, v48
	v_exp_f32_e32 v49, v49
	v_mul_f32_e32 v51, 0xbfb8aa3b, v47
	v_exp_f32_e32 v50, v50
	v_exp_f32_e32 v51, v51
	v_add_f32_e32 v48, 1.0, v48
	v_add_f32_e32 v49, 1.0, v49
	v_rcp_f32_e32 v48, v48
	v_rcp_f32_e32 v49, v49
	v_add_f32_e32 v50, 1.0, v50
	v_add_f32_e32 v51, 1.0, v51
	v_rcp_f32_e32 v50, v50
	v_rcp_f32_e32 v51, v51
	v_pk_mul_f32 v[44:45], v[44:45], v[48:49]
	s_nop 0
	v_pk_mul_f32 v[40:41], v[44:45], v[40:41]
	v_pk_mul_f32 v[44:45], v[46:47], v[50:51]
	v_cvt_pk_bf16_f32 v40, v40, v41
	v_mul_f32_e32 v41, 0xbfb8aa3b, v36
	v_pk_mul_f32 v[42:43], v[44:45], v[42:43]
	v_exp_f32_e32 v44, v41
	v_mul_f32_e32 v41, 0xbfb8aa3b, v37
	v_exp_f32_e32 v45, v41
	v_cvt_pk_bf16_f32 v41, v42, v43
	v_add_f32_e32 v42, 1.0, v44
	v_mul_f32_e32 v44, 0xbfb8aa3b, v38
	v_add_f32_e32 v43, 1.0, v45
	v_mul_f32_e32 v45, 0xbfb8aa3b, v39
	v_exp_f32_e32 v44, v44
	v_exp_f32_e32 v45, v45
	v_rcp_f32_e32 v42, v42
; __device__ __forceinline__ unsigned pk2(float lo, float hi) { f32x2 v = {lo, hi}; bf16x2_t b = __builtin_convertvector(v, bf16x2_t); return __builtin_bit_cast(unsigned, b); }
; __device__ __forceinline__ float silu_f(float a) { return a * __builtin_amdgcn_rcpf(1.0f + __expf(-a)); }
;     __device__ __forceinline__ void operator()(const f32x4 (&acc)[2][2][4][2], const Unit& u, int wr, int wc, int fr, int fq) const {
;     ...
;             for (int m = 0; m < 4; ++m) { const int row = row0 + ai * HALF + m * 16;
;                 const f32x4 a0 = acc[ai][0][m][0], a1 = acc[ai][0][m][1], b0 = acc[ai][1][m][0], b1 = acc[ai][1][m][1];
;                 u32x4 w; w.x = pk2(silu_f(a0[0]) * b0[0], silu_f(a0[1]) * b0[1]); w.y = pk2(silu_f(a0[2]) * b0[2], silu_f(a0[3]) * b0[3]);
;                 w.z = pk2(silu_f(a1[0]) * b1[0], silu_f(a1[1]) * b1[1]); w.w = pk2(silu_f(a1[2]) * b1[2], silu_f(a1[3]) * b1[3]);
;                 *(u32x4*)(H + (size_t)row * ldh + col0) = w; }
	v_rcp_f32_e32 v43, v43
	v_add_f32_e32 v44, 1.0, v44
	v_add_f32_e32 v45, 1.0, v45
	v_rcp_f32_e32 v44, v44
	v_rcp_f32_e32 v45, v45
	v_pk_mul_f32 v[36:37], v[36:37], v[42:43]
	s_nop 0
	v_pk_mul_f32 v[32:33], v[36:37], v[32:33]
	v_add_u32_e32 v36, 0xa0, v150
	v_cvt_pk_bf16_f32 v42, v32, v33
	v_pk_mul_f32 v[32:33], v[38:39], v[44:45]
	s_nop 0
	v_pk_mul_f32 v[32:33], v[32:33], v[34:35]
	v_mul_f32_e32 v34, 0xbfb8aa3b, v30
	v_cvt_pk_bf16_f32 v43, v32, v33
	v_mad_i64_i32 v[32:33], s[36:37], v52, s56, v[112:113]
	v_lshl_add_u64 v[32:33], v[32:33], 0, v[114:115]
	global_store_dwordx4 v[32:33], v[40:43], off
	v_mul_f32_e32 v32, 0xbfb8aa3b, v28
	v_mul_f32_e32 v33, 0xbfb8aa3b, v29
	v_exp_f32_e32 v32, v32
	v_exp_f32_e32 v33, v33
	v_mul_f32_e32 v35, 0xbfb8aa3b, v31
	v_exp_f32_e32 v34, v34
	v_exp_f32_e32 v35, v35
	v_add_f32_e32 v32, 1.0, v32
	v_add_f32_e32 v33, 1.0, v33
	v_rcp_f32_e32 v32, v32
	v_rcp_f32_e32 v33, v33
	v_add_f32_e32 v34, 1.0, v34
	v_add_f32_e32 v35, 1.0, v35
	v_rcp_f32_e32 v34, v34
	v_rcp_f32_e32 v35, v35
	v_pk_mul_f32 v[28:29], v[28:29], v[32:33]
	s_nop 0
	v_pk_mul_f32 v[24:25], v[28:29], v[24:25]
	v_pk_mul_f32 v[28:29], v[30:31], v[34:35]
	v_cvt_pk_bf16_f32 v24, v24, v25
	v_mul_f32_e32 v25, 0xbfb8aa3b, v20
	v_pk_mul_f32 v[26:27], v[28:29], v[26:27]
	v_exp_f32_e32 v28, v25
	v_mul_f32_e32 v25, 0xbfb8aa3b, v21
	v_exp_f32_e32 v29, v25
	v_cvt_pk_bf16_f32 v25, v26, v27
	v_add_f32_e32 v26, 1.0, v28
	v_mul_f32_e32 v28, 0xbfb8aa3b, v22
	v_add_f32_e32 v27, 1.0, v29
	v_mul_f32_e32 v29, 0xbfb8aa3b, v23
	v_exp_f32_e32 v28, v28
	v_exp_f32_e32 v29, v29
	v_rcp_f32_e32 v26, v26
	v_rcp_f32_e32 v27, v27
	v_add_f32_e32 v28, 1.0, v28
	v_add_f32_e32 v29, 1.0, v29
	v_rcp_f32_e32 v28, v28
	v_rcp_f32_e32 v29, v29
	v_pk_mul_f32 v[20:21], v[20:21], v[26:27]
	s_nop 0
	v_pk_mul_f32 v[16:17], v[20:21], v[16:17]
	v_add_u32_e32 v20, 0xb0, v150
	v_cvt_pk_bf16_f32 v26, v16, v17
	v_pk_mul_f32 v[16:17], v[22:23], v[28:29]
	s_nop 0
	v_pk_mul_f32 v[16:17], v[16:17], v[18:19]
	v_mul_f32_e32 v18, 0xbfb8aa3b, v14
	v_cvt_pk_bf16_f32 v27, v16, v17
	v_mad_i64_i32 v[16:17], s[36:37], v36, s56, v[112:113]
	v_lshl_add_u64 v[16:17], v[16:17], 0, v[114:115]
	global_store_dwordx4 v[16:17], v[24:27], off
	v_mul_f32_e32 v16, 0xbfb8aa3b, v12
	v_mul_f32_e32 v17, 0xbfb8aa3b, v13
	v_exp_f32_e32 v16, v16
	v_exp_f32_e32 v17, v17
	v_mul_f32_e32 v19, 0xbfb8aa3b, v15
	v_exp_f32_e32 v18, v18
	v_exp_f32_e32 v19, v19
	v_add_f32_e32 v16, 1.0, v16
	v_add_f32_e32 v17, 1.0, v17
	v_rcp_f32_e32 v16, v16
	v_rcp_f32_e32 v17, v17
	v_add_f32_e32 v18, 1.0, v18
	v_add_f32_e32 v19, 1.0, v19
	v_rcp_f32_e32 v18, v18
	v_rcp_f32_e32 v19, v19
	v_pk_mul_f32 v[12:13], v[12:13], v[16:17]
	s_nop 0
	v_pk_mul_f32 v[8:9], v[12:13], v[8:9]
	v_pk_mul_f32 v[12:13], v[14:15], v[18:19]
	v_cvt_pk_bf16_f32 v8, v8, v9
	v_mul_f32_e32 v9, 0xbfb8aa3b, v4
	v_pk_mul_f32 v[10:11], v[12:13], v[10:11]
	v_exp_f32_e32 v12, v9
	v_mul_f32_e32 v9, 0xbfb8aa3b, v5
	v_exp_f32_e32 v13, v9
	v_cvt_pk_bf16_f32 v9, v10, v11
	v_add_f32_e32 v10, 1.0, v12
	v_mul_f32_e32 v12, 0xbfb8aa3b, v6
	v_add_f32_e32 v11, 1.0, v13
	v_mul_f32_e32 v13, 0xbfb8aa3b, v7
	v_exp_f32_e32 v12, v12
	v_exp_f32_e32 v13, v13
	v_rcp_f32_e32 v10, v10
	v_rcp_f32_e32 v11, v11
	v_add_f32_e32 v12, 1.0, v12
	v_add_f32_e32 v13, 1.0, v13
	v_rcp_f32_e32 v12, v12
	v_rcp_f32_e32 v13, v13
	v_pk_mul_f32 v[4:5], v[4:5], v[10:11]
	s_nop 0
	v_pk_mul_f32 v[0:1], v[4:5], v[0:1]
	s_nop 0
	v_cvt_pk_bf16_f32 v10, v0, v1
	v_pk_mul_f32 v[0:1], v[6:7], v[12:13]
	s_nop 0
	v_pk_mul_f32 v[0:1], v[0:1], v[2:3]
	s_nop 0
	v_cvt_pk_bf16_f32 v11, v0, v1
	v_mad_i64_i32 v[0:1], s[36:37], v20, s56, v[112:113]
	v_lshl_add_u64 v[0:1], v[0:1], 0, v[114:115]
	global_store_dwordx4 v[0:1], v[8:11], off
	s_cbranch_vccnz .LBB0_1338
	s_andn2_b64 vcc, exec, s[6:7]
	s_cbranch_vccnz .LBB0_1337
	s_barrier
	s_branch .LBB0_1337

; #define PG8_STAGE(bufoff, gbase, voff) do { _Pragma("unroll") for (int _i = 0; _i < 2; ++_i) \
;         __builtin_amdgcn_global_load_lds((const unsigned*)((const char*)(gbase) + (voff)[_i]), (PG8_LAS unsigned*)(lds + (bufoff) + ldsw + _i * 8192), 16, 0, 0); } while (0)
; #define PG8_LDA(dst, b, h) do { _Pragma("unroll") for (int m = 0; m < 4; ++m) _Pragma("unroll") for (int k = 0; k < 2; ++k) dst[m][k] = *(const PG8_LAS bf16x8*)(lds + PG8_SA(b, h) + aoff + m * 2048 + k * 1024); } while (0)
; #define PG8_LDB(dst, b, h) do { _Pragma("unroll") for (int n = 0; n < 2; ++n) _Pragma("unroll") for (int k = 0; k < 2; ++k) dst[n][k] = *(const PG8_LAS bf16x8*)(lds + PG8_SB(b, h) + boff + n * 2048 + k * 1024); } while (0)
; #define PG8_SCHED __builtin_amdgcn_sched_barrier(0)
;     __host__ __device__ bool next(int i, Unit& u) const {
;         const long L = (long)i * G + c; if (L >= nwg) return false;
;         int wgid = (int)L; { const int q = nwg / NXCD, r = nwg % NXCD, xcd = wgid % NXCD, off = wgid / NXCD; wgid = (xcd < r ? xcd * (q + 1) : r * (q + 1) + (xcd - r) * q) + off; }
;         const int nig = WGM * nN, gid = wgid / nig, fm = gid * WGM, gsz = (nM - fm) < WGM ? (nM - fm) : WGM;
;         u.pm = fm + ((wgid % nig) % gsz); u.pn = (wgid % nig) / gsz; return true;
;     }
; template <class Epi, class Sched, bool ALIGN_EPI = false, bool SP2 = false>
; __device__ __forceinline__ void gemm_phase(PG8_LAS unsigned char* lds, const Gemm g, const Sched& S, const Epi& E) {
;     ...
;             PG8_LDB(B0, 0, 0); PG8_LDB(B1, 0, 1); PG8_SCHED; PG8_LDA(At, 0, 0); PG8_STAGE(PG8_SA(1, 1), a1 + hstep, voffA);
.LBB0_1406:
	ds_read_b128 v[128:131], v161
	ds_read_b128 v[132:135], v161 offset:1024
	ds_read_b128 v[152:155], v161 offset:2048
	ds_read_b128 v[164:167], v161 offset:3072
	ds_read_b128 v[168:171], v162
	ds_read_b128 v[172:175], v162 offset:1024
	ds_read_b128 v[176:179], v162 offset:2048
	ds_read_b128 v[180:183], v162 offset:3072
	ds_read_b128 v[184:187], v163
	ds_read_b128 v[188:191], v163 offset:1024
	ds_read_b128 v[192:195], v163 offset:2048
	ds_read_b128 v[196:199], v163 offset:3072
	ds_read_b128 v[200:203], v163 offset:4096
	ds_read_b128 v[204:207], v163 offset:5120
	ds_read_b128 v[208:211], v163 offset:6144
	ds_read_b128 v[212:215], v163 offset:7168
	s_add_i32 s43, s43, 1
	s_mul_i32 s0, s43, s46
	s_mul_hi_u32 s1, s43, s3
	s_add_i32 s1, s1, s0
	s_mul_i32 s0, s43, s3
	s_add_u32 s0, s0, s2
	s_addc_u32 s1, s1, s38
	v_cmp_gt_i64_e32 vcc, s[0:1], v[150:151]
	v_cmp_lt_i64_e64 s[4:5], s[0:1], v[148:149]
	s_cbranch_vccnz .LBB0_1412
	s_ashr_i32 s1, s0, 31
	s_lshr_b32 s1, s1, 29
	s_add_i32 s22, s0, s1
	s_and_b32 s1, s22, -8
	s_sub_i32 s23, s0, s1
	s_cmp_gt_i32 s23, -1
	s_mov_b64 s[0:1], -1
	s_cbranch_scc0 .LBB0_1409
	s_lshl_b32 s28, s23, 7
	s_mov_b64 s[0:1], 0

; #define PG8_STAGE(bufoff, gbase, voff) do { _Pragma("unroll") for (int _i = 0; _i < 2; ++_i) \
;         __builtin_amdgcn_global_load_lds((const unsigned*)((const char*)(gbase) + (voff)[_i]), (PG8_LAS unsigned*)(lds + (bufoff) + ldsw + _i * 8192), 16, 0, 0); } while (0)
; #define PG8_LDA(dst, b, h) do { _Pragma("unroll") for (int m = 0; m < 4; ++m) _Pragma("unroll") for (int k = 0; k < 2; ++k) dst[m][k] = *(const PG8_LAS bf16x8*)(lds + PG8_SA(b, h) + aoff + m * 2048 + k * 1024); } while (0)
; #define PG8_LDB(dst, b, h) do { _Pragma("unroll") for (int n = 0; n < 2; ++n) _Pragma("unroll") for (int k = 0; k < 2; ++k) dst[n][k] = *(const PG8_LAS bf16x8*)(lds + PG8_SB(b, h) + boff + n * 2048 + k * 1024); } while (0)
; #define PG8_WAIT_V(n) asm volatile("s_waitcnt vmcnt(" #n ")" ::: "memory")
; #define PG8_WAIT_L(n) asm volatile("s_waitcnt lgkmcnt(" #n ")" ::: "memory")
; #define PG8_BAR __builtin_amdgcn_s_barrier()
; #define PG8_SCHED __builtin_amdgcn_sched_barrier(0)
; template <class Epi, class Sched, bool ALIGN_EPI = false, bool SP2 = false>
; __device__ __forceinline__ void gemm_phase(PG8_LAS unsigned char* lds, const Gemm g, const Sched& S, const Epi& E) {
;     ...
;         const char* nA = has_next ? (const char*)g.A + (size_t)nxt.pm * tstep : cA; const char* nB = has_next ? (const char*)g.Bt + (size_t)nxt.pn * tstep : cB;
;         for (int t = 0; t < nt; t += 2) {
;             const bool last = (t == nt - 2);
;             const char* a1 = cA + (size_t)(t + 1) * kstep;
;             const char* a2 = last ? nA : cA + (size_t)(t + 2) * kstep; const char* b2 = last ? nB : cB + (size_t)(t + 2) * kstep;
;             const char* a3 = a2 + kstep; const char* b3 = b2 + kstep;
;             if (last && has_next) S.a_ready(nxt);
;             if constexpr (SP2) {
;             PG8_LDB(B0, 0, 0); PG8_LDB(B1, 0, 1); PG8_SCHED; PG8_LDA(At, 0, 0); PG8_STAGE(PG8_SA(1, 1), a1 + hstep, voffA);
;             PG8_WAIT_V(8); PG8_WAIT_L(0); PG8_BAR; PG8_MMA(0, 0, At, B0); PG8_MMA(0, 1, At, B1); PG8_BAR; PG8_SCHED;
;             PG8_LDA(At, 0, 1); PG8_STAGE(PG8_SB(0, 0), b2, voffB); PG8_STAGE(PG8_SB(0, 1), b2 + hstep, voffB); PG8_STAGE(PG8_SA(0, 0), a2, voffA);
;             PG8_WAIT_V(8); PG8_WAIT_L(0); PG8_BAR; PG8_MMA(1, 0, At, B0); PG8_MMA(1, 1, At, B1); PG8_BAR; PG8_SCHED;
.LBB0_1416:
	s_add_u32 s24, s24, 0xb0080
	s_addc_u32 s25, s25, 0
	s_add_u32 s55, s30, 0x100
	s_addc_u32 s56, s31, 0
	s_mov_b32 s57, -2
	s_waitcnt lgkmcnt(0)
	s_add_u32 s28, s24, 0xfff50080
	s_addc_u32 s29, s25, -1
	s_cmp_eq_u32 s57, 40
	s_cselect_b32 s31, s5, s29
	s_cselect_b32 s30, s4, s28
	s_cselect_b32 s29, s23, s56
	s_cselect_b32 s28, s22, s55
	s_add_i32 m0, s39, 0xc000
	global_load_lds_dwordx4 v144, s[24:25]
	s_add_i32 m0, s39, 0xe000
	s_nop 0
	global_load_lds_dwordx4 v146, s[24:25]
	s_waitcnt vmcnt(8)
	s_waitcnt lgkmcnt(0)
	s_barrier
	s_setprio 1
	s_waitcnt lgkmcnt(0)
	v_mfma_f32_16x16x32_bf16 v[124:127], v[128:131], v[184:187], 0
	v_mfma_f32_16x16x32_bf16 v[120:123], v[152:155], v[184:187], 0
	v_mfma_f32_16x16x32_bf16 v[116:119], v[128:131], v[192:195], 0
	v_mfma_f32_16x16x32_bf16 v[112:115], v[152:155], v[192:195], 0
	v_mfma_f32_16x16x32_bf16 v[108:111], v[128:131], v[200:203], 0
	v_mfma_f32_16x16x32_bf16 v[104:107], v[152:155], v[200:203], 0
	v_mfma_f32_16x16x32_bf16 v[100:103], v[128:131], v[208:211], 0
	v_mfma_f32_16x16x32_bf16 v[96:99], v[152:155], v[208:211], 0
	v_mfma_f32_16x16x32_bf16 v[124:127], v[132:135], v[188:191], v[124:127]
	v_mfma_f32_16x16x32_bf16 v[120:123], v[164:167], v[188:191], v[120:123]
	v_mfma_f32_16x16x32_bf16 v[116:119], v[132:135], v[196:199], v[116:119]
	v_mfma_f32_16x16x32_bf16 v[112:115], v[164:167], v[196:199], v[112:115]
	v_mfma_f32_16x16x32_bf16 v[108:111], v[132:135], v[204:207], v[108:111]
	v_mfma_f32_16x16x32_bf16 v[104:107], v[164:167], v[204:207], v[104:107]
	v_mfma_f32_16x16x32_bf16 v[100:103], v[132:135], v[212:215], v[100:103]
	v_mfma_f32_16x16x32_bf16 v[96:99], v[164:167], v[212:215], v[96:99]
	s_setprio 0
	s_setprio 1
	v_mfma_f32_16x16x32_bf16 v[64:67], v[168:171], v[184:187], 0
	v_mfma_f32_16x16x32_bf16 v[56:59], v[176:179], v[184:187], 0
	v_mfma_f32_16x16x32_bf16 v[52:55], v[168:171], v[192:195], 0
	v_mfma_f32_16x16x32_bf16 v[48:51], v[176:179], v[192:195], 0
	v_mfma_f32_16x16x32_bf16 v[44:47], v[168:171], v[200:203], 0
	v_mfma_f32_16x16x32_bf16 v[40:43], v[176:179], v[200:203], 0
	v_mfma_f32_16x16x32_bf16 v[36:39], v[168:171], v[208:211], 0
	v_mfma_f32_16x16x32_bf16 v[32:35], v[176:179], v[208:211], 0
	v_mfma_f32_16x16x32_bf16 v[64:67], v[172:175], v[188:191], v[64:67]
	v_mfma_f32_16x16x32_bf16 v[56:59], v[180:183], v[188:191], v[56:59]
	v_mfma_f32_16x16x32_bf16 v[52:55], v[172:175], v[196:199], v[52:55]
	v_mfma_f32_16x16x32_bf16 v[48:51], v[180:183], v[196:199], v[48:51]
	v_mfma_f32_16x16x32_bf16 v[44:47], v[172:175], v[204:207], v[44:47]
	v_mfma_f32_16x16x32_bf16 v[40:43], v[180:183], v[204:207], v[40:43]
	v_mfma_f32_16x16x32_bf16 v[36:39], v[172:175], v[212:215], v[36:39]
	v_mfma_f32_16x16x32_bf16 v[32:35], v[180:183], v[212:215], v[32:35]
	s_setprio 0
	s_barrier
	s_add_i32 s58, s49, s37
	s_add_u32 s62, s28, s10
	s_addc_u32 s63, s29, s11
	s_mov_b32 m0, s58
	ds_read_b128 v[184:187], v163 offset:16384
	ds_read_b128 v[188:191], v163 offset:17408
	ds_read_b128 v[192:195], v163 offset:18432
	ds_read_b128 v[196:199], v163 offset:19456
	ds_read_b128 v[200:203], v163 offset:20480
	ds_read_b128 v[204:207], v163 offset:21504
	ds_read_b128 v[208:211], v163 offset:22528
	ds_read_b128 v[212:215], v163 offset:23552
	global_load_lds_dwordx4 v138, s[28:29]
	s_add_i32 m0, s58, 0x2000
	s_add_u32 s58, s28, 0xb0000
	s_addc_u32 s59, s29, 0
	s_add_i32 s60, s50, s37
	global_load_lds_dwordx4 v142, s[28:29]
	s_mov_b32 m0, s60
	s_add_u32 s64, s30, s10
	s_addc_u32 s65, s31, s11
	global_load_lds_dwordx4 v138, s[58:59]
	s_add_i32 m0, s60, 0x2000
	s_nop 0
	global_load_lds_dwordx4 v142, s[58:59]
	s_mov_b32 m0, s39
	s_nop 0
	global_load_lds_dwordx4 v136, s[30:31]
	s_mov_b32 m0, s40
	s_nop 0
	global_load_lds_dwordx4 v140, s[30:31]
	s_waitcnt vmcnt(8)
	s_waitcnt lgkmcnt(0)
	s_barrier
	s_setprio 1
	s_waitcnt lgkmcnt(0)
	v_mfma_f32_16x16x32_bf16 v[92:95], v[128:131], v[184:187], 0
	v_mfma_f32_16x16x32_bf16 v[88:91], v[152:155], v[184:187], 0
	v_mfma_f32_16x16x32_bf16 v[84:87], v[128:131], v[192:195], 0
	v_mfma_f32_16x16x32_bf16 v[80:83], v[152:155], v[192:195], 0
	v_mfma_f32_16x16x32_bf16 v[76:79], v[128:131], v[200:203], 0
	v_mfma_f32_16x16x32_bf16 v[72:75], v[152:155], v[200:203], 0
	v_mfma_f32_16x16x32_bf16 v[68:71], v[128:131], v[208:211], 0
	v_mfma_f32_16x16x32_bf16 v[60:63], v[152:155], v[208:211], 0
	v_mfma_f32_16x16x32_bf16 v[92:95], v[132:135], v[188:191], v[92:95]
	v_mfma_f32_16x16x32_bf16 v[88:91], v[164:167], v[188:191], v[88:91]
	v_mfma_f32_16x16x32_bf16 v[84:87], v[132:135], v[196:199], v[84:87]
	v_mfma_f32_16x16x32_bf16 v[80:83], v[164:167], v[196:199], v[80:83]
	v_mfma_f32_16x16x32_bf16 v[76:79], v[132:135], v[204:207], v[76:79]
	v_mfma_f32_16x16x32_bf16 v[72:75], v[164:167], v[204:207], v[72:75]
	v_mfma_f32_16x16x32_bf16 v[68:71], v[132:135], v[212:215], v[68:71]
	v_mfma_f32_16x16x32_bf16 v[60:63], v[164:167], v[212:215], v[60:63]
	s_setprio 0
	s_setprio 1
	v_mfma_f32_16x16x32_bf16 v[28:31], v[168:171], v[184:187], 0
	v_mfma_f32_16x16x32_bf16 v[24:27], v[176:179], v[184:187], 0
	v_mfma_f32_16x16x32_bf16 v[20:23], v[168:171], v[192:195], 0
	v_mfma_f32_16x16x32_bf16 v[16:19], v[176:179], v[192:195], 0
	v_mfma_f32_16x16x32_bf16 v[12:15], v[168:171], v[200:203], 0
	v_mfma_f32_16x16x32_bf16 v[8:11], v[176:179], v[200:203], 0
	v_mfma_f32_16x16x32_bf16 v[4:7], v[168:171], v[208:211], 0
	v_mfma_f32_16x16x32_bf16 v[0:3], v[176:179], v[208:211], 0
	v_mfma_f32_16x16x32_bf16 v[28:31], v[172:175], v[188:191], v[28:31]
	v_mfma_f32_16x16x32_bf16 v[24:27], v[180:183], v[188:191], v[24:27]
	v_mfma_f32_16x16x32_bf16 v[20:23], v[172:175], v[196:199], v[20:23]
	v_mfma_f32_16x16x32_bf16 v[16:19], v[180:183], v[196:199], v[16:19]
	v_mfma_f32_16x16x32_bf16 v[12:15], v[172:175], v[204:207], v[12:15]
	v_mfma_f32_16x16x32_bf16 v[8:11], v[180:183], v[204:207], v[8:11]
	v_mfma_f32_16x16x32_bf16 v[4:7], v[172:175], v[212:215], v[4:7]
	v_mfma_f32_16x16x32_bf16 v[0:3], v[180:183], v[212:215], v[0:3]
	s_setprio 0
	s_barrier
; #define PG8_STAGE(bufoff, gbase, voff) do { _Pragma("unroll") for (int _i = 0; _i < 2; ++_i) \
;         __builtin_amdgcn_global_load_lds((const unsigned*)((const char*)(gbase) + (voff)[_i]), (PG8_LAS unsigned*)(lds + (bufoff) + ldsw + _i * 8192), 16, 0, 0); } while (0)
; #define PG8_LDA(dst, b, h) do { _Pragma("unroll") for (int m = 0; m < 4; ++m) _Pragma("unroll") for (int k = 0; k < 2; ++k) dst[m][k] = *(const PG8_LAS bf16x8*)(lds + PG8_SA(b, h) + aoff + m * 2048 + k * 1024); } while (0)
; #define PG8_LDB(dst, b, h) do { _Pragma("unroll") for (int n = 0; n < 2; ++n) _Pragma("unroll") for (int k = 0; k < 2; ++k) dst[n][k] = *(const PG8_LAS bf16x8*)(lds + PG8_SB(b, h) + boff + n * 2048 + k * 1024); } while (0)
; #define PG8_MMA(ai, bj, At, Bt) do { __builtin_amdgcn_s_setprio(1); _Pragma("unroll") for (int m = 0; m < 4; ++m) _Pragma("unroll") for (int n = 0; n < 2; ++n) _Pragma("unroll") for (int k = 0; k < 2; ++k) \
;         acc[ai][bj][m][n] = __builtin_amdgcn_mfma_f32_16x16x32_bf16(Bt[n][k], At[m][k], acc[ai][bj][m][n], 0, 0, 0); __builtin_amdgcn_s_setprio(0); } while (0)
; #define PG8_WAIT_V(n) asm volatile("s_waitcnt vmcnt(" #n ")" ::: "memory")
; #define PG8_WAIT_L(n) asm volatile("s_waitcnt lgkmcnt(" #n ")" ::: "memory")
; #define PG8_BAR __builtin_amdgcn_s_barrier()
; #define PG8_SCHED __builtin_amdgcn_sched_barrier(0)
; template <class Epi, class Sched, bool ALIGN_EPI = false, bool SP2 = false>
; __device__ __forceinline__ void gemm_phase(PG8_LAS unsigned char* lds, const Gemm g, const Sched& S, const Epi& E) {
;     ...
;             PG8_LDB(B0, 1, 0); PG8_LDB(B1, 1, 1); PG8_SCHED; PG8_LDA(At, 1, 0); PG8_STAGE(PG8_SA(0, 1), a2 + hstep, voffA);
;             PG8_WAIT_V(8); PG8_WAIT_L(0); PG8_BAR; PG8_MMA(0, 0, At, B0); PG8_MMA(0, 1, At, B1); PG8_BAR; PG8_SCHED;
;             PG8_LDA(At, 1, 1); PG8_STAGE(PG8_SB(1, 0), b3, voffB); PG8_STAGE(PG8_SB(1, 1), b3 + hstep, voffB); PG8_STAGE(PG8_SA(1, 0), a3, voffA);
;             PG8_WAIT_V(8); PG8_WAIT_L(0); PG8_BAR; PG8_MMA(1, 0, At, B0); PG8_MMA(1, 1, At, B1); PG8_BAR; PG8_SCHED;
	s_add_i32 s58, 0, 0x18000
	s_add_i32 s59, 0, 0x1c000
	v_add_u32_e32 v164, s58, v159
	v_add_u32_e32 v180, s59, v159
	ds_read_b128 v[128:131], v164
	ds_read_b128 v[132:135], v164 offset:1024
	ds_read_b128 v[152:155], v164 offset:2048
	ds_read_b128 v[164:167], v164 offset:3072
	ds_read_b128 v[168:171], v180
	ds_read_b128 v[172:175], v180 offset:1024
	ds_read_b128 v[176:179], v180 offset:2048
	ds_read_b128 v[180:183], v180 offset:3072
	s_add_u32 s30, s30, 0xb0000
	s_addc_u32 s31, s31, 0
	s_mov_b32 m0, s41
	ds_read_b128 v[184:187], v163 offset:32768
	ds_read_b128 v[188:191], v163 offset:33792
	ds_read_b128 v[192:195], v163 offset:34816
	ds_read_b128 v[196:199], v163 offset:35840
	ds_read_b128 v[200:203], v163 offset:36864
	ds_read_b128 v[204:207], v163 offset:37888
	ds_read_b128 v[208:211], v163 offset:38912
	ds_read_b128 v[212:215], v163 offset:39936
	global_load_lds_dwordx4 v136, s[30:31]
	s_mov_b32 m0, s42
	s_nop 0
	global_load_lds_dwordx4 v140, s[30:31]
	s_waitcnt vmcnt(8)
	s_waitcnt lgkmcnt(0)
	s_barrier
	s_setprio 1
	s_waitcnt lgkmcnt(0)
	v_mfma_f32_16x16x32_bf16 v[124:127], v[128:131], v[184:187], v[124:127]
	v_mfma_f32_16x16x32_bf16 v[120:123], v[152:155], v[184:187], v[120:123]
	v_mfma_f32_16x16x32_bf16 v[116:119], v[128:131], v[192:195], v[116:119]
	v_mfma_f32_16x16x32_bf16 v[112:115], v[152:155], v[192:195], v[112:115]
	v_mfma_f32_16x16x32_bf16 v[108:111], v[128:131], v[200:203], v[108:111]
	v_mfma_f32_16x16x32_bf16 v[104:107], v[152:155], v[200:203], v[104:107]
	v_mfma_f32_16x16x32_bf16 v[100:103], v[128:131], v[208:211], v[100:103]
	v_mfma_f32_16x16x32_bf16 v[96:99], v[152:155], v[208:211], v[96:99]
	v_mfma_f32_16x16x32_bf16 v[124:127], v[132:135], v[188:191], v[124:127]
	v_mfma_f32_16x16x32_bf16 v[120:123], v[164:167], v[188:191], v[120:123]
	v_mfma_f32_16x16x32_bf16 v[116:119], v[132:135], v[196:199], v[116:119]
	v_mfma_f32_16x16x32_bf16 v[112:115], v[164:167], v[196:199], v[112:115]
	v_mfma_f32_16x16x32_bf16 v[108:111], v[132:135], v[204:207], v[108:111]
	v_mfma_f32_16x16x32_bf16 v[104:107], v[164:167], v[204:207], v[104:107]
	v_mfma_f32_16x16x32_bf16 v[100:103], v[132:135], v[212:215], v[100:103]
	v_mfma_f32_16x16x32_bf16 v[96:99], v[164:167], v[212:215], v[96:99]
	s_setprio 0
	s_setprio 1
	v_mfma_f32_16x16x32_bf16 v[64:67], v[168:171], v[184:187], v[64:67]
	v_mfma_f32_16x16x32_bf16 v[56:59], v[176:179], v[184:187], v[56:59]
	v_mfma_f32_16x16x32_bf16 v[52:55], v[168:171], v[192:195], v[52:55]
	v_mfma_f32_16x16x32_bf16 v[48:51], v[176:179], v[192:195], v[48:51]
	v_mfma_f32_16x16x32_bf16 v[44:47], v[168:171], v[200:203], v[44:47]
	v_mfma_f32_16x16x32_bf16 v[40:43], v[176:179], v[200:203], v[40:43]
	v_mfma_f32_16x16x32_bf16 v[36:39], v[168:171], v[208:211], v[36:39]
	v_mfma_f32_16x16x32_bf16 v[32:35], v[176:179], v[208:211], v[32:35]
	v_mfma_f32_16x16x32_bf16 v[64:67], v[172:175], v[188:191], v[64:67]
	v_mfma_f32_16x16x32_bf16 v[56:59], v[180:183], v[188:191], v[56:59]
	v_mfma_f32_16x16x32_bf16 v[52:55], v[172:175], v[196:199], v[52:55]
	v_mfma_f32_16x16x32_bf16 v[48:51], v[180:183], v[196:199], v[48:51]
	v_mfma_f32_16x16x32_bf16 v[44:47], v[172:175], v[204:207], v[44:47]
	v_mfma_f32_16x16x32_bf16 v[40:43], v[180:183], v[204:207], v[40:43]
	v_mfma_f32_16x16x32_bf16 v[36:39], v[172:175], v[212:215], v[36:39]
	v_mfma_f32_16x16x32_bf16 v[32:35], v[180:183], v[212:215], v[32:35]
	s_setprio 0
	s_barrier
	s_add_i32 s30, s58, s37
	s_mov_b32 m0, s30
	ds_read_b128 v[184:187], v163 offset:49152
	ds_read_b128 v[188:191], v163 offset:50176
	ds_read_b128 v[192:195], v163 offset:51200
	ds_read_b128 v[196:199], v163 offset:52224
	ds_read_b128 v[200:203], v163 offset:53248
	ds_read_b128 v[204:207], v163 offset:54272
	ds_read_b128 v[208:211], v163 offset:55296
	ds_read_b128 v[212:215], v163 offset:56320
	global_load_lds_dwordx4 v138, s[62:63]
	s_add_i32 m0, s30, 0x2000
	s_add_u32 s28, s28, 0xb0080
	s_addc_u32 s29, s29, 0
	s_add_i32 s30, s59, s37
	global_load_lds_dwordx4 v142, s[62:63]
	s_mov_b32 m0, s30
	s_nop 0
	global_load_lds_dwordx4 v138, s[28:29]
	s_add_i32 m0, s30, 0x2000
	s_nop 0
	global_load_lds_dwordx4 v142, s[28:29]
	s_mov_b32 m0, s47
	s_nop 0
	global_load_lds_dwordx4 v136, s[64:65]
	s_mov_b32 m0, s48
	s_nop 0
	global_load_lds_dwordx4 v140, s[64:65]
	s_waitcnt vmcnt(8)
	s_waitcnt lgkmcnt(0)
	s_barrier
	s_setprio 1
	s_waitcnt lgkmcnt(0)
	v_mfma_f32_16x16x32_bf16 v[92:95], v[128:131], v[184:187], v[92:95]
	v_mfma_f32_16x16x32_bf16 v[88:91], v[152:155], v[184:187], v[88:91]
	v_mfma_f32_16x16x32_bf16 v[84:87], v[128:131], v[192:195], v[84:87]
	v_mfma_f32_16x16x32_bf16 v[80:83], v[152:155], v[192:195], v[80:83]
	v_mfma_f32_16x16x32_bf16 v[76:79], v[128:131], v[200:203], v[76:79]
	v_mfma_f32_16x16x32_bf16 v[72:75], v[152:155], v[200:203], v[72:75]
	v_mfma_f32_16x16x32_bf16 v[68:71], v[128:131], v[208:211], v[68:71]
	v_mfma_f32_16x16x32_bf16 v[60:63], v[152:155], v[208:211], v[60:63]
	v_mfma_f32_16x16x32_bf16 v[92:95], v[132:135], v[188:191], v[92:95]
	v_mfma_f32_16x16x32_bf16 v[88:91], v[164:167], v[188:191], v[88:91]
	v_mfma_f32_16x16x32_bf16 v[84:87], v[132:135], v[196:199], v[84:87]
	v_mfma_f32_16x16x32_bf16 v[80:83], v[164:167], v[196:199], v[80:83]
	v_mfma_f32_16x16x32_bf16 v[76:79], v[132:135], v[204:207], v[76:79]
	v_mfma_f32_16x16x32_bf16 v[72:75], v[164:167], v[204:207], v[72:75]
	v_mfma_f32_16x16x32_bf16 v[68:71], v[132:135], v[212:215], v[68:71]
	v_mfma_f32_16x16x32_bf16 v[60:63], v[164:167], v[212:215], v[60:63]
	s_setprio 0
	s_setprio 1
	v_mfma_f32_16x16x32_bf16 v[28:31], v[168:171], v[184:187], v[28:31]
	v_mfma_f32_16x16x32_bf16 v[24:27], v[176:179], v[184:187], v[24:27]
	v_mfma_f32_16x16x32_bf16 v[20:23], v[168:171], v[192:195], v[20:23]
	v_mfma_f32_16x16x32_bf16 v[16:19], v[176:179], v[192:195], v[16:19]
	v_mfma_f32_16x16x32_bf16 v[12:15], v[168:171], v[200:203], v[12:15]
	v_mfma_f32_16x16x32_bf16 v[8:11], v[176:179], v[200:203], v[8:11]
	v_mfma_f32_16x16x32_bf16 v[4:7], v[168:171], v[208:211], v[4:7]
	v_mfma_f32_16x16x32_bf16 v[0:3], v[176:179], v[208:211], v[0:3]
	v_mfma_f32_16x16x32_bf16 v[28:31], v[172:175], v[188:191], v[28:31]
	v_mfma_f32_16x16x32_bf16 v[24:27], v[180:183], v[188:191], v[24:27]
	v_mfma_f32_16x16x32_bf16 v[20:23], v[172:175], v[196:199], v[20:23]
	v_mfma_f32_16x16x32_bf16 v[16:19], v[180:183], v[196:199], v[16:19]
	v_mfma_f32_16x16x32_bf16 v[12:15], v[172:175], v[204:207], v[12:15]
	v_mfma_f32_16x16x32_bf16 v[8:11], v[180:183], v[204:207], v[8:11]
	v_mfma_f32_16x16x32_bf16 v[4:7], v[172:175], v[212:215], v[4:7]
	v_mfma_f32_16x16x32_bf16 v[0:3], v[180:183], v[212:215], v[0:3]
	s_setprio 0
	s_barrier
	s_add_i32 s57, s57, 2
	s_add_u32 s24, s24, 0x100
	s_addc_u32 s25, s25, 0
	s_add_u32 s55, s55, 0x100
	s_addc_u32 s56, s56, 0
	s_cmp_gt_u32 s57, 41
